# A/B: all per-phase s_setprio flips in the GEMM K-loops removed
# baseline (speedup 1.0000x reference)
.LBB0_187:
	s_ashr_i32 s15, s14, 31
	s_lshl_b64 s[16:17], s[14:15], 19
	s_add_u32 s16, s30, s16
	s_addc_u32 s17, s31, s17
	s_and_b64 s[18:19], s[0:1], exec
	s_cselect_b32 s3, s17, s25
	s_cselect_b32 s15, s16, s24
	s_ashr_i32 s13, s12, 31
	s_lshl_b64 s[18:19], s[12:13], 19
	s_add_u32 s18, s34, s18
	s_addc_u32 s19, s35, s19
	s_and_b64 s[26:27], s[0:1], exec
	s_cselect_b32 s13, s19, s23
	s_cselect_b32 s21, s18, s22
	s_add_u32 s48, s22, 0x100
	s_addc_u32 s49, s23, 0
	s_add_u32 s22, s24, 0x40080
	s_addc_u32 s23, s25, 0
	s_mov_b32 s50, -2
	s_waitcnt vmcnt(0)
	s_add_u32 s24, s22, 0xfffc0080
	s_addc_u32 s25, s23, -1
	s_add_i32 s51, 0, 0x10000
	s_cmp_eq_u32 s50, 12
	s_cselect_b32 s27, s3, s25
	s_cselect_b32 s26, s15, s24
	v_add_u32_e32 v142, s51, v144
	s_cselect_b32 s25, s13, s49
	s_cselect_b32 s24, s21, s48
	s_add_i32 s54, 0, 0x14000
	ds_read_b128 v[138:141], v142
	ds_read_b128 v[146:149], v142 offset:1024
	ds_read_b128 v[150:153], v142 offset:2048
	ds_read_b128 v[154:157], v142 offset:3072
	v_add_u32_e32 v142, s54, v144
	ds_read_b128 v[158:161], v142
	ds_read_b128 v[162:165], v142 offset:1024
	ds_read_b128 v[166:169], v142 offset:2048
	ds_read_b128 v[170:173], v142 offset:3072
	v_lshl_add_u64 v[142:143], s[22:23], 0, v[136:137]
	s_add_i32 m0, s37, 0xc000
	ds_read_b128 v[174:177], v145
	ds_read_b128 v[178:181], v145 offset:1024
	ds_read_b128 v[182:185], v145 offset:2048
	ds_read_b128 v[186:189], v145 offset:3072
	ds_read_b128 v[190:193], v145 offset:4096
	ds_read_b128 v[194:197], v145 offset:5120
	ds_read_b128 v[198:201], v145 offset:6144
	ds_read_b128 v[202:205], v145 offset:7168
	global_load_lds_dwordx4 v[142:143], off
	v_lshl_add_u64 v[142:143], s[22:23], 0, v[134:135]
	s_add_i32 m0, s37, 0xe000
	s_nop 0
	global_load_lds_dwordx4 v[142:143], off
	s_waitcnt vmcnt(8)
	s_waitcnt lgkmcnt(0)
	s_barrier
	s_waitcnt lgkmcnt(0)
	v_mfma_f32_16x16x32_bf16 v[124:127], v[138:141], v[174:177], 0
	v_mfma_f32_16x16x32_bf16 v[120:123], v[150:153], v[174:177], 0
	v_mfma_f32_16x16x32_bf16 v[112:115], v[138:141], v[182:185], 0
	v_mfma_f32_16x16x32_bf16 v[104:107], v[150:153], v[182:185], 0
	v_mfma_f32_16x16x32_bf16 v[96:99], v[138:141], v[190:193], 0
	v_mfma_f32_16x16x32_bf16 v[88:91], v[150:153], v[190:193], 0
	v_mfma_f32_16x16x32_bf16 v[80:83], v[138:141], v[198:201], 0
	v_mfma_f32_16x16x32_bf16 v[72:75], v[150:153], v[198:201], 0
	v_mfma_f32_16x16x32_bf16 v[124:127], v[146:149], v[178:181], v[124:127]
	v_mfma_f32_16x16x32_bf16 v[120:123], v[154:157], v[178:181], v[120:123]
	v_mfma_f32_16x16x32_bf16 v[112:115], v[146:149], v[186:189], v[112:115]
	v_mfma_f32_16x16x32_bf16 v[104:107], v[154:157], v[186:189], v[104:107]
	v_mfma_f32_16x16x32_bf16 v[96:99], v[146:149], v[194:197], v[96:99]
	v_mfma_f32_16x16x32_bf16 v[88:91], v[154:157], v[194:197], v[88:91]
	v_mfma_f32_16x16x32_bf16 v[80:83], v[146:149], v[202:205], v[80:83]
	v_mfma_f32_16x16x32_bf16 v[72:75], v[154:157], v[202:205], v[72:75]
	v_mfma_f32_16x16x32_bf16 v[116:119], v[158:161], v[174:177], 0
	v_mfma_f32_16x16x32_bf16 v[108:111], v[166:169], v[174:177], 0
	v_mfma_f32_16x16x32_bf16 v[100:103], v[158:161], v[182:185], 0
	v_mfma_f32_16x16x32_bf16 v[92:95], v[166:169], v[182:185], 0
	v_mfma_f32_16x16x32_bf16 v[84:87], v[158:161], v[190:193], 0
	v_mfma_f32_16x16x32_bf16 v[76:79], v[166:169], v[190:193], 0
	v_mfma_f32_16x16x32_bf16 v[68:71], v[158:161], v[198:201], 0
	v_mfma_f32_16x16x32_bf16 v[64:67], v[166:169], v[198:201], 0
	v_mfma_f32_16x16x32_bf16 v[116:119], v[162:165], v[178:181], v[116:119]
	v_mfma_f32_16x16x32_bf16 v[108:111], v[170:173], v[178:181], v[108:111]
	v_mfma_f32_16x16x32_bf16 v[100:103], v[162:165], v[186:189], v[100:103]
	v_mfma_f32_16x16x32_bf16 v[92:95], v[170:173], v[186:189], v[92:95]
	v_mfma_f32_16x16x32_bf16 v[84:87], v[162:165], v[194:197], v[84:87]
	v_mfma_f32_16x16x32_bf16 v[76:79], v[170:173], v[194:197], v[76:79]
	v_mfma_f32_16x16x32_bf16 v[68:71], v[162:165], v[202:205], v[68:71]
	v_mfma_f32_16x16x32_bf16 v[64:67], v[170:173], v[202:205], v[64:67]
	s_barrier
	s_add_i32 s51, s51, s36
	v_lshl_add_u64 v[142:143], s[24:25], 0, v[232:233]
	s_mov_b32 m0, s51
	ds_read_b128 v[174:177], v145 offset:16384
	ds_read_b128 v[178:181], v145 offset:17408
	ds_read_b128 v[182:185], v145 offset:18432
	ds_read_b128 v[186:189], v145 offset:19456
	ds_read_b128 v[190:193], v145 offset:20480
	ds_read_b128 v[194:197], v145 offset:21504
	ds_read_b128 v[198:201], v145 offset:22528
	ds_read_b128 v[202:205], v145 offset:23552
	global_load_lds_dwordx4 v[142:143], off
	s_add_i32 m0, s51, 0x2000
	s_add_u32 s52, s24, 0x40000
	v_lshl_add_u64 v[206:207], s[24:25], 0, v[132:133]
	s_addc_u32 s53, s25, 0
	s_add_i32 s51, s54, s36
	global_load_lds_dwordx4 v[206:207], off
	v_lshl_add_u64 v[208:209], s[52:53], 0, v[232:233]
	s_mov_b32 m0, s51
	v_lshl_add_u64 v[210:211], s[26:27], 0, v[130:131]
	global_load_lds_dwordx4 v[208:209], off
	v_lshl_add_u64 v[208:209], s[52:53], 0, v[132:133]
	s_add_i32 m0, s51, 0x2000
	s_nop 0
	global_load_lds_dwordx4 v[208:209], off
	v_lshl_add_u64 v[208:209], s[26:27], 0, v[128:129]
	s_waitcnt vmcnt(6)
	s_waitcnt lgkmcnt(0)
	s_barrier
	s_waitcnt lgkmcnt(0)
	v_mfma_f32_16x16x32_bf16 v[60:63], v[138:141], v[174:177], 0
	v_mfma_f32_16x16x32_bf16 v[56:59], v[150:153], v[174:177], 0
	v_mfma_f32_16x16x32_bf16 v[48:51], v[138:141], v[182:185], 0
	v_mfma_f32_16x16x32_bf16 v[40:43], v[150:153], v[182:185], 0
	v_mfma_f32_16x16x32_bf16 v[32:35], v[138:141], v[190:193], 0
	v_mfma_f32_16x16x32_bf16 v[24:27], v[150:153], v[190:193], 0
	v_mfma_f32_16x16x32_bf16 v[16:19], v[138:141], v[198:201], 0
	v_mfma_f32_16x16x32_bf16 v[8:11], v[150:153], v[198:201], 0
	v_mfma_f32_16x16x32_bf16 v[60:63], v[146:149], v[178:181], v[60:63]
	v_mfma_f32_16x16x32_bf16 v[56:59], v[154:157], v[178:181], v[56:59]
	v_mfma_f32_16x16x32_bf16 v[48:51], v[146:149], v[186:189], v[48:51]
	v_mfma_f32_16x16x32_bf16 v[40:43], v[154:157], v[186:189], v[40:43]
	v_mfma_f32_16x16x32_bf16 v[32:35], v[146:149], v[194:197], v[32:35]
	v_mfma_f32_16x16x32_bf16 v[24:27], v[154:157], v[194:197], v[24:27]
	v_mfma_f32_16x16x32_bf16 v[16:19], v[146:149], v[202:205], v[16:19]
	v_mfma_f32_16x16x32_bf16 v[8:11], v[154:157], v[202:205], v[8:11]
	v_mfma_f32_16x16x32_bf16 v[52:55], v[158:161], v[174:177], 0
	v_mfma_f32_16x16x32_bf16 v[44:47], v[166:169], v[174:177], 0
	v_mfma_f32_16x16x32_bf16 v[36:39], v[158:161], v[182:185], 0
	v_mfma_f32_16x16x32_bf16 v[28:31], v[166:169], v[182:185], 0
	v_mfma_f32_16x16x32_bf16 v[20:23], v[158:161], v[190:193], 0
	v_mfma_f32_16x16x32_bf16 v[12:15], v[166:169], v[190:193], 0
	v_mfma_f32_16x16x32_bf16 v[4:7], v[158:161], v[198:201], 0
	v_mfma_f32_16x16x32_bf16 v[0:3], v[166:169], v[198:201], 0
	v_mfma_f32_16x16x32_bf16 v[52:55], v[162:165], v[178:181], v[52:55]
	v_mfma_f32_16x16x32_bf16 v[44:47], v[170:173], v[178:181], v[44:47]
	v_mfma_f32_16x16x32_bf16 v[36:39], v[162:165], v[186:189], v[36:39]
	v_mfma_f32_16x16x32_bf16 v[28:31], v[170:173], v[186:189], v[28:31]
	v_mfma_f32_16x16x32_bf16 v[20:23], v[162:165], v[194:197], v[20:23]
	v_mfma_f32_16x16x32_bf16 v[12:15], v[170:173], v[194:197], v[12:15]
	v_mfma_f32_16x16x32_bf16 v[4:7], v[162:165], v[202:205], v[4:7]
	v_mfma_f32_16x16x32_bf16 v[0:3], v[170:173], v[202:205], v[0:3]
	s_barrier
	s_branch .Lzmid_1
.LBB0_188:
	s_add_u32 s24, s22, 0xfffc0080
	s_addc_u32 s25, s23, -1
	s_add_i32 s51, 0, 0x10000
	s_cmp_eq_u32 s50, 12
	s_cselect_b32 s27, s3, s25
	s_cselect_b32 s26, s15, s24
	v_add_u32_e32 v142, s51, v144
	s_cselect_b32 s25, s13, s49
	s_cselect_b32 s24, s21, s48
	s_add_i32 s54, 0, 0x14000
	ds_read_b128 v[138:141], v142
	ds_read_b128 v[146:149], v142 offset:1024
	ds_read_b128 v[150:153], v142 offset:2048
	ds_read_b128 v[154:157], v142 offset:3072
	v_add_u32_e32 v142, s54, v144
	ds_read_b128 v[158:161], v142
	ds_read_b128 v[162:165], v142 offset:1024
	ds_read_b128 v[166:169], v142 offset:2048
	ds_read_b128 v[170:173], v142 offset:3072
	v_lshl_add_u64 v[142:143], s[22:23], 0, v[136:137]
	s_add_i32 m0, s37, 0xc000
	ds_read_b128 v[174:177], v145
	ds_read_b128 v[178:181], v145 offset:1024
	ds_read_b128 v[182:185], v145 offset:2048
	ds_read_b128 v[186:189], v145 offset:3072
	ds_read_b128 v[190:193], v145 offset:4096
	ds_read_b128 v[194:197], v145 offset:5120
	ds_read_b128 v[198:201], v145 offset:6144
	ds_read_b128 v[202:205], v145 offset:7168
	global_load_lds_dwordx4 v[142:143], off
	v_lshl_add_u64 v[142:143], s[22:23], 0, v[134:135]
	s_add_i32 m0, s37, 0xe000
	s_nop 0
	global_load_lds_dwordx4 v[142:143], off
	s_waitcnt vmcnt(8)
	s_waitcnt lgkmcnt(0)
	s_barrier
	s_waitcnt lgkmcnt(0)
	v_mfma_f32_16x16x32_bf16 v[124:127], v[138:141], v[174:177], v[124:127]
	v_mfma_f32_16x16x32_bf16 v[120:123], v[150:153], v[174:177], v[120:123]
	v_mfma_f32_16x16x32_bf16 v[112:115], v[138:141], v[182:185], v[112:115]
	v_mfma_f32_16x16x32_bf16 v[104:107], v[150:153], v[182:185], v[104:107]
	v_mfma_f32_16x16x32_bf16 v[96:99], v[138:141], v[190:193], v[96:99]
	v_mfma_f32_16x16x32_bf16 v[88:91], v[150:153], v[190:193], v[88:91]
	v_mfma_f32_16x16x32_bf16 v[80:83], v[138:141], v[198:201], v[80:83]
	v_mfma_f32_16x16x32_bf16 v[72:75], v[150:153], v[198:201], v[72:75]
	v_mfma_f32_16x16x32_bf16 v[124:127], v[146:149], v[178:181], v[124:127]
	v_mfma_f32_16x16x32_bf16 v[120:123], v[154:157], v[178:181], v[120:123]
	v_mfma_f32_16x16x32_bf16 v[112:115], v[146:149], v[186:189], v[112:115]
	v_mfma_f32_16x16x32_bf16 v[104:107], v[154:157], v[186:189], v[104:107]
	v_mfma_f32_16x16x32_bf16 v[96:99], v[146:149], v[194:197], v[96:99]
	v_mfma_f32_16x16x32_bf16 v[88:91], v[154:157], v[194:197], v[88:91]
	v_mfma_f32_16x16x32_bf16 v[80:83], v[146:149], v[202:205], v[80:83]
	v_mfma_f32_16x16x32_bf16 v[72:75], v[154:157], v[202:205], v[72:75]
	v_mfma_f32_16x16x32_bf16 v[116:119], v[158:161], v[174:177], v[116:119]
	v_mfma_f32_16x16x32_bf16 v[108:111], v[166:169], v[174:177], v[108:111]
	v_mfma_f32_16x16x32_bf16 v[100:103], v[158:161], v[182:185], v[100:103]
	v_mfma_f32_16x16x32_bf16 v[92:95], v[166:169], v[182:185], v[92:95]
	v_mfma_f32_16x16x32_bf16 v[84:87], v[158:161], v[190:193], v[84:87]
	v_mfma_f32_16x16x32_bf16 v[76:79], v[166:169], v[190:193], v[76:79]
	v_mfma_f32_16x16x32_bf16 v[68:71], v[158:161], v[198:201], v[68:71]
	v_mfma_f32_16x16x32_bf16 v[64:67], v[166:169], v[198:201], v[64:67]
	v_mfma_f32_16x16x32_bf16 v[116:119], v[162:165], v[178:181], v[116:119]
	v_mfma_f32_16x16x32_bf16 v[108:111], v[170:173], v[178:181], v[108:111]
	v_mfma_f32_16x16x32_bf16 v[100:103], v[162:165], v[186:189], v[100:103]
	v_mfma_f32_16x16x32_bf16 v[92:95], v[170:173], v[186:189], v[92:95]
	v_mfma_f32_16x16x32_bf16 v[84:87], v[162:165], v[194:197], v[84:87]
	v_mfma_f32_16x16x32_bf16 v[76:79], v[170:173], v[194:197], v[76:79]
	v_mfma_f32_16x16x32_bf16 v[68:71], v[162:165], v[202:205], v[68:71]
	v_mfma_f32_16x16x32_bf16 v[64:67], v[170:173], v[202:205], v[64:67]
	s_barrier
	s_add_i32 s51, s51, s36
	v_lshl_add_u64 v[142:143], s[24:25], 0, v[232:233]
	s_mov_b32 m0, s51
	ds_read_b128 v[174:177], v145 offset:16384
	ds_read_b128 v[178:181], v145 offset:17408
	ds_read_b128 v[182:185], v145 offset:18432
	ds_read_b128 v[186:189], v145 offset:19456
	ds_read_b128 v[190:193], v145 offset:20480
	ds_read_b128 v[194:197], v145 offset:21504
	ds_read_b128 v[198:201], v145 offset:22528
	ds_read_b128 v[202:205], v145 offset:23552
	global_load_lds_dwordx4 v[142:143], off
	s_add_i32 m0, s51, 0x2000
	s_add_u32 s52, s24, 0x40000
	v_lshl_add_u64 v[206:207], s[24:25], 0, v[132:133]
	s_addc_u32 s53, s25, 0
	s_add_i32 s51, s54, s36
	global_load_lds_dwordx4 v[206:207], off
	v_lshl_add_u64 v[208:209], s[52:53], 0, v[232:233]
	s_mov_b32 m0, s51
	v_lshl_add_u64 v[210:211], s[26:27], 0, v[130:131]
	global_load_lds_dwordx4 v[208:209], off
	v_lshl_add_u64 v[208:209], s[52:53], 0, v[132:133]
	s_add_i32 m0, s51, 0x2000
	s_nop 0
	global_load_lds_dwordx4 v[208:209], off
	v_lshl_add_u64 v[208:209], s[26:27], 0, v[128:129]
	s_waitcnt vmcnt(6)
	s_waitcnt lgkmcnt(0)
	s_barrier
	s_waitcnt lgkmcnt(0)
	v_mfma_f32_16x16x32_bf16 v[60:63], v[138:141], v[174:177], v[60:63]
	v_mfma_f32_16x16x32_bf16 v[56:59], v[150:153], v[174:177], v[56:59]
	v_mfma_f32_16x16x32_bf16 v[48:51], v[138:141], v[182:185], v[48:51]
	v_mfma_f32_16x16x32_bf16 v[40:43], v[150:153], v[182:185], v[40:43]
	v_mfma_f32_16x16x32_bf16 v[32:35], v[138:141], v[190:193], v[32:35]
	v_mfma_f32_16x16x32_bf16 v[24:27], v[150:153], v[190:193], v[24:27]
	v_mfma_f32_16x16x32_bf16 v[16:19], v[138:141], v[198:201], v[16:19]
	v_mfma_f32_16x16x32_bf16 v[8:11], v[150:153], v[198:201], v[8:11]
	v_mfma_f32_16x16x32_bf16 v[60:63], v[146:149], v[178:181], v[60:63]
	v_mfma_f32_16x16x32_bf16 v[56:59], v[154:157], v[178:181], v[56:59]
	v_mfma_f32_16x16x32_bf16 v[48:51], v[146:149], v[186:189], v[48:51]
	v_mfma_f32_16x16x32_bf16 v[40:43], v[154:157], v[186:189], v[40:43]
	v_mfma_f32_16x16x32_bf16 v[32:35], v[146:149], v[194:197], v[32:35]
	v_mfma_f32_16x16x32_bf16 v[24:27], v[154:157], v[194:197], v[24:27]
	v_mfma_f32_16x16x32_bf16 v[16:19], v[146:149], v[202:205], v[16:19]
	v_mfma_f32_16x16x32_bf16 v[8:11], v[154:157], v[202:205], v[8:11]
	v_mfma_f32_16x16x32_bf16 v[52:55], v[158:161], v[174:177], v[52:55]
	v_mfma_f32_16x16x32_bf16 v[44:47], v[166:169], v[174:177], v[44:47]
	v_mfma_f32_16x16x32_bf16 v[36:39], v[158:161], v[182:185], v[36:39]
	v_mfma_f32_16x16x32_bf16 v[28:31], v[166:169], v[182:185], v[28:31]
	v_mfma_f32_16x16x32_bf16 v[20:23], v[158:161], v[190:193], v[20:23]
	v_mfma_f32_16x16x32_bf16 v[12:15], v[166:169], v[190:193], v[12:15]
	v_mfma_f32_16x16x32_bf16 v[4:7], v[158:161], v[198:201], v[4:7]
	v_mfma_f32_16x16x32_bf16 v[0:3], v[166:169], v[198:201], v[0:3]
	v_mfma_f32_16x16x32_bf16 v[52:55], v[162:165], v[178:181], v[52:55]
	v_mfma_f32_16x16x32_bf16 v[44:47], v[170:173], v[178:181], v[44:47]
	v_mfma_f32_16x16x32_bf16 v[36:39], v[162:165], v[186:189], v[36:39]
	v_mfma_f32_16x16x32_bf16 v[28:31], v[170:173], v[186:189], v[28:31]
	v_mfma_f32_16x16x32_bf16 v[20:23], v[162:165], v[194:197], v[20:23]
	v_mfma_f32_16x16x32_bf16 v[12:15], v[170:173], v[194:197], v[12:15]
	v_mfma_f32_16x16x32_bf16 v[4:7], v[162:165], v[202:205], v[4:7]
	v_mfma_f32_16x16x32_bf16 v[0:3], v[170:173], v[202:205], v[0:3]
	s_barrier
.Lzmid_1:
	s_add_i32 s51, 0, 0x18000
	s_add_i32 s52, 0, 0x1c000
	v_add_u32_e32 v154, s51, v144
	v_add_u32_e32 v170, s52, v144
	ds_read_b128 v[138:141], v154
	ds_read_b128 v[146:149], v154 offset:1024
	ds_read_b128 v[150:153], v154 offset:2048
	ds_read_b128 v[154:157], v154 offset:3072
	ds_read_b128 v[158:161], v170
	ds_read_b128 v[162:165], v170 offset:1024
	ds_read_b128 v[166:169], v170 offset:2048
	ds_read_b128 v[170:173], v170 offset:3072
	s_add_u32 s26, s26, 0x40000
	s_addc_u32 s27, s27, 0
	s_mov_b32 m0, s37
	s_nop 0
	global_load_lds_dwordx4 v[208:209], off
	s_mov_b32 m0, s38
	s_nop 0
	global_load_lds_dwordx4 v[210:211], off
	s_mov_b32 m0, s39
	v_lshl_add_u64 v[212:213], s[26:27], 0, v[128:129]
	ds_read_b128 v[174:177], v145 offset:32768
	ds_read_b128 v[178:181], v145 offset:33792
	ds_read_b128 v[182:185], v145 offset:34816
	ds_read_b128 v[186:189], v145 offset:35840
	ds_read_b128 v[190:193], v145 offset:36864
	ds_read_b128 v[194:197], v145 offset:37888
	ds_read_b128 v[198:201], v145 offset:38912
	ds_read_b128 v[202:205], v145 offset:39936
	global_load_lds_dwordx4 v[212:213], off
	v_lshl_add_u64 v[212:213], s[26:27], 0, v[130:131]
	s_mov_b32 m0, s40
	s_nop 0
	global_load_lds_dwordx4 v[212:213], off
	s_waitcnt vmcnt(8)
	s_waitcnt lgkmcnt(0)
	s_barrier
	s_waitcnt lgkmcnt(0)
	v_mfma_f32_16x16x32_bf16 v[124:127], v[138:141], v[174:177], v[124:127]
	v_mfma_f32_16x16x32_bf16 v[120:123], v[150:153], v[174:177], v[120:123]
	v_mfma_f32_16x16x32_bf16 v[112:115], v[138:141], v[182:185], v[112:115]
	v_mfma_f32_16x16x32_bf16 v[104:107], v[150:153], v[182:185], v[104:107]
	v_mfma_f32_16x16x32_bf16 v[96:99], v[138:141], v[190:193], v[96:99]
	v_mfma_f32_16x16x32_bf16 v[88:91], v[150:153], v[190:193], v[88:91]
	v_mfma_f32_16x16x32_bf16 v[80:83], v[138:141], v[198:201], v[80:83]
	v_mfma_f32_16x16x32_bf16 v[72:75], v[150:153], v[198:201], v[72:75]
	v_mfma_f32_16x16x32_bf16 v[124:127], v[146:149], v[178:181], v[124:127]
	v_mfma_f32_16x16x32_bf16 v[120:123], v[154:157], v[178:181], v[120:123]
	v_mfma_f32_16x16x32_bf16 v[112:115], v[146:149], v[186:189], v[112:115]
	v_mfma_f32_16x16x32_bf16 v[104:107], v[154:157], v[186:189], v[104:107]
	v_mfma_f32_16x16x32_bf16 v[96:99], v[146:149], v[194:197], v[96:99]
	v_mfma_f32_16x16x32_bf16 v[88:91], v[154:157], v[194:197], v[88:91]
	v_mfma_f32_16x16x32_bf16 v[80:83], v[146:149], v[202:205], v[80:83]
	v_mfma_f32_16x16x32_bf16 v[72:75], v[154:157], v[202:205], v[72:75]
	v_mfma_f32_16x16x32_bf16 v[116:119], v[158:161], v[174:177], v[116:119]
	v_mfma_f32_16x16x32_bf16 v[108:111], v[166:169], v[174:177], v[108:111]
	v_mfma_f32_16x16x32_bf16 v[100:103], v[158:161], v[182:185], v[100:103]
	v_mfma_f32_16x16x32_bf16 v[92:95], v[166:169], v[182:185], v[92:95]
	v_mfma_f32_16x16x32_bf16 v[84:87], v[158:161], v[190:193], v[84:87]
	v_mfma_f32_16x16x32_bf16 v[76:79], v[166:169], v[190:193], v[76:79]
	v_mfma_f32_16x16x32_bf16 v[68:71], v[158:161], v[198:201], v[68:71]
	v_mfma_f32_16x16x32_bf16 v[64:67], v[166:169], v[198:201], v[64:67]
	v_mfma_f32_16x16x32_bf16 v[116:119], v[162:165], v[178:181], v[116:119]
	v_mfma_f32_16x16x32_bf16 v[108:111], v[170:173], v[178:181], v[108:111]
	v_mfma_f32_16x16x32_bf16 v[100:103], v[162:165], v[186:189], v[100:103]
	v_mfma_f32_16x16x32_bf16 v[92:95], v[170:173], v[186:189], v[92:95]
	v_mfma_f32_16x16x32_bf16 v[84:87], v[162:165], v[194:197], v[84:87]
	v_mfma_f32_16x16x32_bf16 v[76:79], v[170:173], v[194:197], v[76:79]
	v_mfma_f32_16x16x32_bf16 v[68:71], v[162:165], v[202:205], v[68:71]
	v_mfma_f32_16x16x32_bf16 v[64:67], v[170:173], v[202:205], v[64:67]
	s_barrier
	s_add_i32 s26, s51, s36
	v_lshl_add_u64 v[142:143], v[142:143], 0, s[94:95]
	s_mov_b32 m0, s26
	ds_read_b128 v[174:177], v145 offset:49152
	ds_read_b128 v[178:181], v145 offset:50176
	ds_read_b128 v[182:185], v145 offset:51200
	ds_read_b128 v[186:189], v145 offset:52224
	ds_read_b128 v[190:193], v145 offset:53248
	ds_read_b128 v[194:197], v145 offset:54272
	ds_read_b128 v[198:201], v145 offset:55296
	ds_read_b128 v[202:205], v145 offset:56320
	global_load_lds_dwordx4 v[142:143], off
	s_add_i32 m0, s26, 0x2000
	s_add_u32 s24, s24, 0x40080
	v_lshl_add_u64 v[142:143], v[206:207], 0, s[94:95]
	s_addc_u32 s25, s25, 0
	s_add_i32 s26, s52, s36
	global_load_lds_dwordx4 v[142:143], off
	v_lshl_add_u64 v[142:143], s[24:25], 0, v[232:233]
	s_mov_b32 m0, s26
	s_nop 0
	global_load_lds_dwordx4 v[142:143], off
	v_lshl_add_u64 v[142:143], s[24:25], 0, v[132:133]
	s_add_i32 m0, s26, 0x2000
	s_nop 0
	global_load_lds_dwordx4 v[142:143], off
	v_lshl_add_u64 v[142:143], v[208:209], 0, s[94:95]
	s_mov_b32 m0, s43
	s_nop 0
	global_load_lds_dwordx4 v[142:143], off
	v_lshl_add_u64 v[142:143], v[210:211], 0, s[94:95]
	s_mov_b32 m0, s44
	s_nop 0
	global_load_lds_dwordx4 v[142:143], off
	s_waitcnt vmcnt(8)
	s_waitcnt lgkmcnt(0)
	s_barrier
	s_waitcnt lgkmcnt(0)
	v_mfma_f32_16x16x32_bf16 v[60:63], v[138:141], v[174:177], v[60:63]
	v_mfma_f32_16x16x32_bf16 v[56:59], v[150:153], v[174:177], v[56:59]
	v_mfma_f32_16x16x32_bf16 v[48:51], v[138:141], v[182:185], v[48:51]
	v_mfma_f32_16x16x32_bf16 v[40:43], v[150:153], v[182:185], v[40:43]
	v_mfma_f32_16x16x32_bf16 v[32:35], v[138:141], v[190:193], v[32:35]
	v_mfma_f32_16x16x32_bf16 v[24:27], v[150:153], v[190:193], v[24:27]
	v_mfma_f32_16x16x32_bf16 v[16:19], v[138:141], v[198:201], v[16:19]
	v_mfma_f32_16x16x32_bf16 v[8:11], v[150:153], v[198:201], v[8:11]
	v_mfma_f32_16x16x32_bf16 v[60:63], v[146:149], v[178:181], v[60:63]
	v_mfma_f32_16x16x32_bf16 v[56:59], v[154:157], v[178:181], v[56:59]
	v_mfma_f32_16x16x32_bf16 v[48:51], v[146:149], v[186:189], v[48:51]
	v_mfma_f32_16x16x32_bf16 v[40:43], v[154:157], v[186:189], v[40:43]
	v_mfma_f32_16x16x32_bf16 v[32:35], v[146:149], v[194:197], v[32:35]
	v_mfma_f32_16x16x32_bf16 v[24:27], v[154:157], v[194:197], v[24:27]
	v_mfma_f32_16x16x32_bf16 v[16:19], v[146:149], v[202:205], v[16:19]
	v_mfma_f32_16x16x32_bf16 v[8:11], v[154:157], v[202:205], v[8:11]
	v_mfma_f32_16x16x32_bf16 v[52:55], v[158:161], v[174:177], v[52:55]
	v_mfma_f32_16x16x32_bf16 v[44:47], v[166:169], v[174:177], v[44:47]
	v_mfma_f32_16x16x32_bf16 v[36:39], v[158:161], v[182:185], v[36:39]
	v_mfma_f32_16x16x32_bf16 v[28:31], v[166:169], v[182:185], v[28:31]
	v_mfma_f32_16x16x32_bf16 v[20:23], v[158:161], v[190:193], v[20:23]
	v_mfma_f32_16x16x32_bf16 v[12:15], v[166:169], v[190:193], v[12:15]
	v_mfma_f32_16x16x32_bf16 v[4:7], v[158:161], v[198:201], v[4:7]
	v_mfma_f32_16x16x32_bf16 v[0:3], v[166:169], v[198:201], v[0:3]
	v_mfma_f32_16x16x32_bf16 v[52:55], v[162:165], v[178:181], v[52:55]
	v_mfma_f32_16x16x32_bf16 v[44:47], v[170:173], v[178:181], v[44:47]
	v_mfma_f32_16x16x32_bf16 v[36:39], v[162:165], v[186:189], v[36:39]
	v_mfma_f32_16x16x32_bf16 v[28:31], v[170:173], v[186:189], v[28:31]
	v_mfma_f32_16x16x32_bf16 v[20:23], v[162:165], v[194:197], v[20:23]
	v_mfma_f32_16x16x32_bf16 v[12:15], v[170:173], v[194:197], v[12:15]
	v_mfma_f32_16x16x32_bf16 v[4:7], v[162:165], v[202:205], v[4:7]
	v_mfma_f32_16x16x32_bf16 v[0:3], v[170:173], v[202:205], v[0:3]
	s_barrier
	s_add_i32 s50, s50, 2
	s_add_u32 s48, s48, 0x100
	s_addc_u32 s49, s49, 0
	s_add_u32 s22, s22, 0x100
	s_addc_u32 s23, s23, 0
	s_cmp_gt_u32 s50, 13
	s_cbranch_scc0 .LBB0_188
	s_and_b64 vcc, exec, s[10:11]
	s_cbranch_vccz .LBB0_191
	s_barrier

.LBB0_311:
	s_add_u32 s35, s26, s34
	s_addc_u32 s40, s27, 0
	s_add_u32 s38, s35, 0x100
	s_addc_u32 s39, s40, 0
	s_and_b64 s[36:37], s[30:31], exec
	s_cselect_b32 s37, s5, s39
	s_cselect_b32 s36, s17, s38
	s_add_u32 s34, s24, s34
	s_addc_u32 s38, s25, 0
	s_add_u32 s34, s34, 0x100
	s_addc_u32 s38, s38, 0
	s_add_i32 s70, 0, 0x10000
	s_and_b64 s[30:31], s[30:31], exec
	s_cselect_b32 s39, s15, s38
	s_cselect_b32 s38, s23, s34
	s_add_i32 s31, 0, 0x14000
	s_add_u32 s42, s35, 0x100080
	s_addc_u32 s43, s40, 0
	s_add_i32 s69, s70, s50
	s_add_i32 m0, s51, 0xc000
	s_add_i32 s72, s51, 0xe000
	s_add_i32 s66, s69, 0x2000
	s_add_u32 s40, s38, 0x10000
	v_add_u32_e32 v146, s70, v154
	v_add_u32_e32 v164, s31, v154
	s_addc_u32 s41, s39, 0
	s_add_i32 s68, s31, s50
	ds_read_b128 v[134:137], v146
	ds_read_b128 v[138:141], v146 offset:1024
	ds_read_b128 v[142:145], v146 offset:2048
	ds_read_b128 v[146:149], v146 offset:3072
	ds_read_b128 v[150:153], v164
	ds_read_b128 v[156:159], v164 offset:1024
	ds_read_b128 v[160:163], v164 offset:2048
	ds_read_b128 v[164:167], v164 offset:3072
	s_add_i32 s67, s68, 0x2000
	s_add_i32 s65, 0, 0x18000
	s_add_i32 s64, 0, 0x1c000
	s_add_u32 s34, s36, 0x100000
	s_addc_u32 s35, s37, 0
	s_add_i32 s63, s65, s50
	s_add_i32 s62, s63, 0x2000
	s_add_u32 s30, s38, 0x10080
	s_addc_u32 s31, s39, 0
	s_add_i32 s71, s64, s50
	s_add_i32 s70, s71, 0x2000
	v_lshl_add_u64 v[200:201], s[42:43], 0, v[128:129]
	ds_read_b128 v[168:171], v155
	ds_read_b128 v[172:175], v155 offset:1024
	ds_read_b128 v[176:179], v155 offset:2048
	ds_read_b128 v[180:183], v155 offset:3072
	ds_read_b128 v[184:187], v155 offset:4096
	ds_read_b128 v[188:191], v155 offset:5120
	ds_read_b128 v[192:195], v155 offset:6144
	ds_read_b128 v[196:199], v155 offset:7168
	global_load_lds_dwordx4 v[200:201], off
	v_lshl_add_u64 v[200:201], s[42:43], 0, v[130:131]
	s_mov_b32 m0, s72
	s_nop 0
	global_load_lds_dwordx4 v[200:201], off
	s_waitcnt vmcnt(8)
	s_waitcnt lgkmcnt(0)
	s_barrier
	s_waitcnt lgkmcnt(0)
	v_mfma_f32_16x16x32_bf16 v[124:127], v[134:137], v[168:171], v[124:127]
	v_mfma_f32_16x16x32_bf16 v[120:123], v[142:145], v[168:171], v[120:123]
	v_mfma_f32_16x16x32_bf16 v[108:111], v[134:137], v[176:179], v[108:111]
	v_mfma_f32_16x16x32_bf16 v[104:107], v[142:145], v[176:179], v[104:107]
	v_mfma_f32_16x16x32_bf16 v[92:95], v[134:137], v[184:187], v[92:95]
	v_mfma_f32_16x16x32_bf16 v[88:91], v[142:145], v[184:187], v[88:91]
	v_mfma_f32_16x16x32_bf16 v[76:79], v[134:137], v[192:195], v[76:79]
	v_mfma_f32_16x16x32_bf16 v[72:75], v[142:145], v[192:195], v[72:75]
	v_mfma_f32_16x16x32_bf16 v[124:127], v[138:141], v[172:175], v[124:127]
	v_mfma_f32_16x16x32_bf16 v[120:123], v[146:149], v[172:175], v[120:123]
	v_mfma_f32_16x16x32_bf16 v[108:111], v[138:141], v[180:183], v[108:111]
	v_mfma_f32_16x16x32_bf16 v[104:107], v[146:149], v[180:183], v[104:107]
	v_mfma_f32_16x16x32_bf16 v[92:95], v[138:141], v[188:191], v[92:95]
	v_mfma_f32_16x16x32_bf16 v[88:91], v[146:149], v[188:191], v[88:91]
	v_mfma_f32_16x16x32_bf16 v[76:79], v[138:141], v[196:199], v[76:79]
	v_mfma_f32_16x16x32_bf16 v[72:75], v[146:149], v[196:199], v[72:75]
	v_mfma_f32_16x16x32_bf16 v[116:119], v[150:153], v[168:171], v[116:119]
	v_mfma_f32_16x16x32_bf16 v[112:115], v[160:163], v[168:171], v[112:115]
	v_mfma_f32_16x16x32_bf16 v[100:103], v[150:153], v[176:179], v[100:103]
	v_mfma_f32_16x16x32_bf16 v[96:99], v[160:163], v[176:179], v[96:99]
	v_mfma_f32_16x16x32_bf16 v[84:87], v[150:153], v[184:187], v[84:87]
	v_mfma_f32_16x16x32_bf16 v[80:83], v[160:163], v[184:187], v[80:83]
	v_mfma_f32_16x16x32_bf16 v[68:71], v[150:153], v[192:195], v[68:71]
	v_mfma_f32_16x16x32_bf16 v[64:67], v[160:163], v[192:195], v[64:67]
	v_mfma_f32_16x16x32_bf16 v[116:119], v[156:159], v[172:175], v[116:119]
	v_mfma_f32_16x16x32_bf16 v[112:115], v[164:167], v[172:175], v[112:115]
	v_mfma_f32_16x16x32_bf16 v[100:103], v[156:159], v[180:183], v[100:103]
	v_mfma_f32_16x16x32_bf16 v[96:99], v[164:167], v[180:183], v[96:99]
	v_mfma_f32_16x16x32_bf16 v[84:87], v[156:159], v[188:191], v[84:87]
	v_mfma_f32_16x16x32_bf16 v[80:83], v[164:167], v[188:191], v[80:83]
	v_mfma_f32_16x16x32_bf16 v[68:71], v[156:159], v[196:199], v[68:71]
	v_mfma_f32_16x16x32_bf16 v[64:67], v[164:167], v[196:199], v[64:67]
	s_barrier
	s_mov_b32 m0, s69
	v_lshl_add_u64 v[200:201], s[38:39], 0, v[232:233]
	ds_read_b128 v[168:171], v155 offset:16384
	ds_read_b128 v[172:175], v155 offset:17408
	ds_read_b128 v[176:179], v155 offset:18432
	ds_read_b128 v[180:183], v155 offset:19456
	ds_read_b128 v[184:187], v155 offset:20480
	ds_read_b128 v[188:191], v155 offset:21504
	ds_read_b128 v[192:195], v155 offset:22528
	ds_read_b128 v[196:199], v155 offset:23552
	global_load_lds_dwordx4 v[200:201], off
	v_lshl_add_u64 v[202:203], s[38:39], 0, v[132:133]
	s_mov_b32 m0, s66
	v_lshl_add_u64 v[204:205], s[40:41], 0, v[232:233]
	global_load_lds_dwordx4 v[202:203], off
	s_mov_b32 m0, s68
	v_lshl_add_u64 v[206:207], s[36:37], 0, v[130:131]
	global_load_lds_dwordx4 v[204:205], off
	v_lshl_add_u64 v[204:205], s[40:41], 0, v[132:133]
	s_mov_b32 m0, s67
	s_nop 0
	global_load_lds_dwordx4 v[204:205], off
	v_lshl_add_u64 v[204:205], s[36:37], 0, v[128:129]
	s_mov_b32 m0, s51
	s_nop 0
	global_load_lds_dwordx4 v[204:205], off
	s_mov_b32 m0, s52
	s_nop 0
	global_load_lds_dwordx4 v[206:207], off
	s_waitcnt vmcnt(8)
	s_waitcnt lgkmcnt(0)
	s_barrier
	s_waitcnt lgkmcnt(0)
	v_mfma_f32_16x16x32_bf16 v[60:63], v[134:137], v[168:171], v[60:63]
	v_mfma_f32_16x16x32_bf16 v[56:59], v[142:145], v[168:171], v[56:59]
	v_mfma_f32_16x16x32_bf16 v[44:47], v[134:137], v[176:179], v[44:47]
	v_mfma_f32_16x16x32_bf16 v[40:43], v[142:145], v[176:179], v[40:43]
	v_mfma_f32_16x16x32_bf16 v[28:31], v[134:137], v[184:187], v[28:31]
	v_mfma_f32_16x16x32_bf16 v[24:27], v[142:145], v[184:187], v[24:27]
	v_mfma_f32_16x16x32_bf16 v[12:15], v[134:137], v[192:195], v[12:15]
	v_mfma_f32_16x16x32_bf16 v[8:11], v[142:145], v[192:195], v[8:11]
	v_mfma_f32_16x16x32_bf16 v[60:63], v[138:141], v[172:175], v[60:63]
	v_mfma_f32_16x16x32_bf16 v[56:59], v[146:149], v[172:175], v[56:59]
	v_mfma_f32_16x16x32_bf16 v[44:47], v[138:141], v[180:183], v[44:47]
	v_mfma_f32_16x16x32_bf16 v[40:43], v[146:149], v[180:183], v[40:43]
	v_mfma_f32_16x16x32_bf16 v[28:31], v[138:141], v[188:191], v[28:31]
	v_mfma_f32_16x16x32_bf16 v[24:27], v[146:149], v[188:191], v[24:27]
	v_mfma_f32_16x16x32_bf16 v[12:15], v[138:141], v[196:199], v[12:15]
	v_mfma_f32_16x16x32_bf16 v[8:11], v[146:149], v[196:199], v[8:11]
	v_mfma_f32_16x16x32_bf16 v[52:55], v[150:153], v[168:171], v[52:55]
	v_mfma_f32_16x16x32_bf16 v[48:51], v[160:163], v[168:171], v[48:51]
	v_mfma_f32_16x16x32_bf16 v[36:39], v[150:153], v[176:179], v[36:39]
	v_mfma_f32_16x16x32_bf16 v[32:35], v[160:163], v[176:179], v[32:35]
	v_mfma_f32_16x16x32_bf16 v[20:23], v[150:153], v[184:187], v[20:23]
	v_mfma_f32_16x16x32_bf16 v[16:19], v[160:163], v[184:187], v[16:19]
	v_mfma_f32_16x16x32_bf16 v[4:7], v[150:153], v[192:195], v[4:7]
	v_mfma_f32_16x16x32_bf16 v[0:3], v[160:163], v[192:195], v[0:3]
	v_mfma_f32_16x16x32_bf16 v[52:55], v[156:159], v[172:175], v[52:55]
	v_mfma_f32_16x16x32_bf16 v[48:51], v[164:167], v[172:175], v[48:51]
	v_mfma_f32_16x16x32_bf16 v[36:39], v[156:159], v[180:183], v[36:39]
	v_mfma_f32_16x16x32_bf16 v[32:35], v[164:167], v[180:183], v[32:35]
	v_mfma_f32_16x16x32_bf16 v[20:23], v[156:159], v[188:191], v[20:23]
	v_mfma_f32_16x16x32_bf16 v[16:19], v[164:167], v[188:191], v[16:19]
	v_mfma_f32_16x16x32_bf16 v[4:7], v[156:159], v[196:199], v[4:7]
	v_mfma_f32_16x16x32_bf16 v[0:3], v[164:167], v[196:199], v[0:3]
	s_barrier
	v_add_u32_e32 v146, s65, v154
	v_add_u32_e32 v164, s64, v154
	ds_read_b128 v[134:137], v146
	ds_read_b128 v[138:141], v146 offset:1024
	ds_read_b128 v[142:145], v146 offset:2048
	ds_read_b128 v[146:149], v146 offset:3072
	ds_read_b128 v[150:153], v164
	ds_read_b128 v[156:159], v164 offset:1024
	ds_read_b128 v[160:163], v164 offset:2048
	ds_read_b128 v[164:167], v164 offset:3072
	s_mov_b32 m0, s53
	v_lshl_add_u64 v[208:209], s[34:35], 0, v[128:129]
	ds_read_b128 v[168:171], v155 offset:32768
	ds_read_b128 v[172:175], v155 offset:33792
	ds_read_b128 v[176:179], v155 offset:34816
	ds_read_b128 v[180:183], v155 offset:35840
	ds_read_b128 v[184:187], v155 offset:36864
	ds_read_b128 v[188:191], v155 offset:37888
	ds_read_b128 v[192:195], v155 offset:38912
	ds_read_b128 v[196:199], v155 offset:39936
	global_load_lds_dwordx4 v[208:209], off
	v_lshl_add_u64 v[208:209], s[34:35], 0, v[130:131]
	s_mov_b32 m0, s54
	s_nop 0
	global_load_lds_dwordx4 v[208:209], off
	s_waitcnt vmcnt(8)
	s_waitcnt lgkmcnt(0)
	s_barrier
	s_waitcnt lgkmcnt(0)
	v_mfma_f32_16x16x32_bf16 v[124:127], v[134:137], v[168:171], v[124:127]
	v_mfma_f32_16x16x32_bf16 v[120:123], v[142:145], v[168:171], v[120:123]
	v_mfma_f32_16x16x32_bf16 v[108:111], v[134:137], v[176:179], v[108:111]
	v_mfma_f32_16x16x32_bf16 v[104:107], v[142:145], v[176:179], v[104:107]
	v_mfma_f32_16x16x32_bf16 v[92:95], v[134:137], v[184:187], v[92:95]
	v_mfma_f32_16x16x32_bf16 v[88:91], v[142:145], v[184:187], v[88:91]
	v_mfma_f32_16x16x32_bf16 v[76:79], v[134:137], v[192:195], v[76:79]
	v_mfma_f32_16x16x32_bf16 v[72:75], v[142:145], v[192:195], v[72:75]
	v_mfma_f32_16x16x32_bf16 v[124:127], v[138:141], v[172:175], v[124:127]
	v_mfma_f32_16x16x32_bf16 v[120:123], v[146:149], v[172:175], v[120:123]
	v_mfma_f32_16x16x32_bf16 v[108:111], v[138:141], v[180:183], v[108:111]
	v_mfma_f32_16x16x32_bf16 v[104:107], v[146:149], v[180:183], v[104:107]
	v_mfma_f32_16x16x32_bf16 v[92:95], v[138:141], v[188:191], v[92:95]
	v_mfma_f32_16x16x32_bf16 v[88:91], v[146:149], v[188:191], v[88:91]
	v_mfma_f32_16x16x32_bf16 v[76:79], v[138:141], v[196:199], v[76:79]
	v_mfma_f32_16x16x32_bf16 v[72:75], v[146:149], v[196:199], v[72:75]
	v_mfma_f32_16x16x32_bf16 v[116:119], v[150:153], v[168:171], v[116:119]
	v_mfma_f32_16x16x32_bf16 v[112:115], v[160:163], v[168:171], v[112:115]
	v_mfma_f32_16x16x32_bf16 v[100:103], v[150:153], v[176:179], v[100:103]
	v_mfma_f32_16x16x32_bf16 v[96:99], v[160:163], v[176:179], v[96:99]
	v_mfma_f32_16x16x32_bf16 v[84:87], v[150:153], v[184:187], v[84:87]
	v_mfma_f32_16x16x32_bf16 v[80:83], v[160:163], v[184:187], v[80:83]
	v_mfma_f32_16x16x32_bf16 v[68:71], v[150:153], v[192:195], v[68:71]
	v_mfma_f32_16x16x32_bf16 v[64:67], v[160:163], v[192:195], v[64:67]
	v_mfma_f32_16x16x32_bf16 v[116:119], v[156:159], v[172:175], v[116:119]
	v_mfma_f32_16x16x32_bf16 v[112:115], v[164:167], v[172:175], v[112:115]
	v_mfma_f32_16x16x32_bf16 v[100:103], v[156:159], v[180:183], v[100:103]
	v_mfma_f32_16x16x32_bf16 v[96:99], v[164:167], v[180:183], v[96:99]
	v_mfma_f32_16x16x32_bf16 v[84:87], v[156:159], v[188:191], v[84:87]
	v_mfma_f32_16x16x32_bf16 v[80:83], v[164:167], v[188:191], v[80:83]
	v_mfma_f32_16x16x32_bf16 v[68:71], v[156:159], v[196:199], v[68:71]
	v_mfma_f32_16x16x32_bf16 v[64:67], v[164:167], v[196:199], v[64:67]
	s_barrier
	s_mov_b32 m0, s63
	v_lshl_add_u64 v[200:201], v[200:201], 0, s[94:95]
	ds_read_b128 v[168:171], v155 offset:49152
	ds_read_b128 v[172:175], v155 offset:50176
	ds_read_b128 v[176:179], v155 offset:51200
	ds_read_b128 v[180:183], v155 offset:52224
	ds_read_b128 v[184:187], v155 offset:53248
	ds_read_b128 v[188:191], v155 offset:54272
	ds_read_b128 v[192:195], v155 offset:55296
	ds_read_b128 v[196:199], v155 offset:56320
	global_load_lds_dwordx4 v[200:201], off
	v_lshl_add_u64 v[200:201], v[202:203], 0, s[94:95]
	s_mov_b32 m0, s62
	s_nop 0
	global_load_lds_dwordx4 v[200:201], off
	v_lshl_add_u64 v[200:201], s[30:31], 0, v[232:233]
	s_mov_b32 m0, s71
	s_nop 0
	global_load_lds_dwordx4 v[200:201], off
	v_lshl_add_u64 v[200:201], s[30:31], 0, v[132:133]
	s_mov_b32 m0, s70
	s_nop 0
	global_load_lds_dwordx4 v[200:201], off
	v_lshl_add_u64 v[200:201], v[204:205], 0, s[94:95]
	s_mov_b32 m0, s57
	s_nop 0
	global_load_lds_dwordx4 v[200:201], off
	v_lshl_add_u64 v[200:201], v[206:207], 0, s[94:95]
	s_mov_b32 m0, s58
	s_nop 0
	global_load_lds_dwordx4 v[200:201], off
	s_waitcnt vmcnt(8)
	s_waitcnt lgkmcnt(0)
	s_barrier
	s_waitcnt lgkmcnt(0)
	v_mfma_f32_16x16x32_bf16 v[60:63], v[134:137], v[168:171], v[60:63]
	v_mfma_f32_16x16x32_bf16 v[56:59], v[142:145], v[168:171], v[56:59]
	v_mfma_f32_16x16x32_bf16 v[44:47], v[134:137], v[176:179], v[44:47]
	v_mfma_f32_16x16x32_bf16 v[40:43], v[142:145], v[176:179], v[40:43]
	v_mfma_f32_16x16x32_bf16 v[28:31], v[134:137], v[184:187], v[28:31]
	v_mfma_f32_16x16x32_bf16 v[24:27], v[142:145], v[184:187], v[24:27]
	v_mfma_f32_16x16x32_bf16 v[12:15], v[134:137], v[192:195], v[12:15]
	v_mfma_f32_16x16x32_bf16 v[8:11], v[142:145], v[192:195], v[8:11]
	v_mfma_f32_16x16x32_bf16 v[60:63], v[138:141], v[172:175], v[60:63]
	v_mfma_f32_16x16x32_bf16 v[56:59], v[146:149], v[172:175], v[56:59]
	v_mfma_f32_16x16x32_bf16 v[44:47], v[138:141], v[180:183], v[44:47]
	v_mfma_f32_16x16x32_bf16 v[40:43], v[146:149], v[180:183], v[40:43]
	v_mfma_f32_16x16x32_bf16 v[28:31], v[138:141], v[188:191], v[28:31]
	v_mfma_f32_16x16x32_bf16 v[24:27], v[146:149], v[188:191], v[24:27]
	v_mfma_f32_16x16x32_bf16 v[12:15], v[138:141], v[196:199], v[12:15]
	v_mfma_f32_16x16x32_bf16 v[8:11], v[146:149], v[196:199], v[8:11]
	v_mfma_f32_16x16x32_bf16 v[52:55], v[150:153], v[168:171], v[52:55]
	v_mfma_f32_16x16x32_bf16 v[48:51], v[160:163], v[168:171], v[48:51]
	v_mfma_f32_16x16x32_bf16 v[36:39], v[150:153], v[176:179], v[36:39]
	v_mfma_f32_16x16x32_bf16 v[32:35], v[160:163], v[176:179], v[32:35]
	v_mfma_f32_16x16x32_bf16 v[20:23], v[150:153], v[184:187], v[20:23]
	v_mfma_f32_16x16x32_bf16 v[16:19], v[160:163], v[184:187], v[16:19]
	v_mfma_f32_16x16x32_bf16 v[4:7], v[150:153], v[192:195], v[4:7]
	v_mfma_f32_16x16x32_bf16 v[0:3], v[160:163], v[192:195], v[0:3]
	v_mfma_f32_16x16x32_bf16 v[52:55], v[156:159], v[172:175], v[52:55]
	v_mfma_f32_16x16x32_bf16 v[48:51], v[164:167], v[172:175], v[48:51]
	v_mfma_f32_16x16x32_bf16 v[36:39], v[156:159], v[180:183], v[36:39]
	v_mfma_f32_16x16x32_bf16 v[32:35], v[164:167], v[180:183], v[32:35]
	v_mfma_f32_16x16x32_bf16 v[20:23], v[156:159], v[188:191], v[20:23]
	v_mfma_f32_16x16x32_bf16 v[16:19], v[164:167], v[188:191], v[16:19]
	v_mfma_f32_16x16x32_bf16 v[4:7], v[156:159], v[196:199], v[4:7]
	v_mfma_f32_16x16x32_bf16 v[0:3], v[164:167], v[196:199], v[0:3]
	s_barrier
	s_movk_i32 s34, 0x100
	s_andn2_b64 vcc, exec, s[28:29]
	s_mov_b64 s[30:31], -1
	s_mov_b64 s[28:29], 0
	s_cbranch_vccz .LBB0_311
	s_and_b64 vcc, exec, s[12:13]
	s_cbranch_vccz .LBB0_314
	s_barrier

.LBB0_369:
	s_add_u32 s35, s26, s34
	s_addc_u32 s40, s27, 0
	s_add_u32 s38, s35, 0x100
	s_addc_u32 s39, s40, 0
	s_and_b64 s[36:37], s[30:31], exec
	s_cselect_b32 s37, s5, s39
	s_cselect_b32 s36, s17, s38
	s_add_u32 s34, s24, s34
	s_addc_u32 s38, s25, 0
	s_add_u32 s34, s34, 0x100
	s_addc_u32 s38, s38, 0
	s_add_i32 s70, 0, 0x10000
	s_and_b64 s[30:31], s[30:31], exec
	s_cselect_b32 s39, s15, s38
	s_cselect_b32 s38, s23, s34
	s_add_i32 s31, 0, 0x14000
	s_add_u32 s42, s35, 0x100080
	s_addc_u32 s43, s40, 0
	s_add_i32 s69, s70, s50
	s_add_i32 m0, s51, 0xc000
	s_add_i32 s72, s51, 0xe000
	s_add_i32 s66, s69, 0x2000
	s_add_u32 s40, s38, 0x10000
	v_add_u32_e32 v146, s70, v168
	v_add_u32_e32 v162, s31, v168
	s_addc_u32 s41, s39, 0
	s_add_i32 s68, s31, s50
	ds_read_b128 v[134:137], v146
	ds_read_b128 v[138:141], v146 offset:1024
	ds_read_b128 v[142:145], v146 offset:2048
	ds_read_b128 v[146:149], v146 offset:3072
	ds_read_b128 v[150:153], v162
	ds_read_b128 v[154:157], v162 offset:1024
	ds_read_b128 v[158:161], v162 offset:2048
	ds_read_b128 v[162:165], v162 offset:3072
	s_add_i32 s67, s68, 0x2000
	s_add_i32 s65, 0, 0x18000
	s_add_i32 s64, 0, 0x1c000
	s_add_u32 s34, s36, 0x100000
	s_addc_u32 s35, s37, 0
	s_add_i32 s63, s65, s50
	s_add_i32 s62, s63, 0x2000
	s_add_u32 s30, s38, 0x10080
	s_addc_u32 s31, s39, 0
	s_add_i32 s71, s64, s50
	s_add_i32 s70, s71, 0x2000
	v_lshl_add_u64 v[166:167], s[42:43], 0, v[128:129]
	ds_read_b128 v[170:173], v169
	ds_read_b128 v[174:177], v169 offset:1024
	ds_read_b128 v[178:181], v169 offset:2048
	ds_read_b128 v[182:185], v169 offset:3072
	ds_read_b128 v[186:189], v169 offset:4096
	ds_read_b128 v[190:193], v169 offset:5120
	ds_read_b128 v[194:197], v169 offset:6144
	ds_read_b128 v[198:201], v169 offset:7168
	global_load_lds_dwordx4 v[166:167], off
	v_lshl_add_u64 v[166:167], s[42:43], 0, v[130:131]
	s_mov_b32 m0, s72
	s_nop 0
	global_load_lds_dwordx4 v[166:167], off
	s_waitcnt vmcnt(8)
	s_waitcnt lgkmcnt(0)
	s_barrier
	s_waitcnt lgkmcnt(0)
	v_mfma_f32_16x16x32_bf16 v[124:127], v[134:137], v[170:173], v[124:127]
	v_mfma_f32_16x16x32_bf16 v[120:123], v[142:145], v[170:173], v[120:123]
	v_mfma_f32_16x16x32_bf16 v[108:111], v[134:137], v[178:181], v[108:111]
	v_mfma_f32_16x16x32_bf16 v[104:107], v[142:145], v[178:181], v[104:107]
	v_mfma_f32_16x16x32_bf16 v[92:95], v[134:137], v[186:189], v[92:95]
	v_mfma_f32_16x16x32_bf16 v[88:91], v[142:145], v[186:189], v[88:91]
	v_mfma_f32_16x16x32_bf16 v[76:79], v[134:137], v[194:197], v[76:79]
	v_mfma_f32_16x16x32_bf16 v[72:75], v[142:145], v[194:197], v[72:75]
	v_mfma_f32_16x16x32_bf16 v[124:127], v[138:141], v[174:177], v[124:127]
	v_mfma_f32_16x16x32_bf16 v[120:123], v[146:149], v[174:177], v[120:123]
	v_mfma_f32_16x16x32_bf16 v[108:111], v[138:141], v[182:185], v[108:111]
	v_mfma_f32_16x16x32_bf16 v[104:107], v[146:149], v[182:185], v[104:107]
	v_mfma_f32_16x16x32_bf16 v[92:95], v[138:141], v[190:193], v[92:95]
	v_mfma_f32_16x16x32_bf16 v[88:91], v[146:149], v[190:193], v[88:91]
	v_mfma_f32_16x16x32_bf16 v[76:79], v[138:141], v[198:201], v[76:79]
	v_mfma_f32_16x16x32_bf16 v[72:75], v[146:149], v[198:201], v[72:75]
	v_mfma_f32_16x16x32_bf16 v[116:119], v[150:153], v[170:173], v[116:119]
	v_mfma_f32_16x16x32_bf16 v[112:115], v[158:161], v[170:173], v[112:115]
	v_mfma_f32_16x16x32_bf16 v[100:103], v[150:153], v[178:181], v[100:103]
	v_mfma_f32_16x16x32_bf16 v[96:99], v[158:161], v[178:181], v[96:99]
	v_mfma_f32_16x16x32_bf16 v[84:87], v[150:153], v[186:189], v[84:87]
	v_mfma_f32_16x16x32_bf16 v[80:83], v[158:161], v[186:189], v[80:83]
	v_mfma_f32_16x16x32_bf16 v[68:71], v[150:153], v[194:197], v[68:71]
	v_mfma_f32_16x16x32_bf16 v[64:67], v[158:161], v[194:197], v[64:67]
	v_mfma_f32_16x16x32_bf16 v[116:119], v[154:157], v[174:177], v[116:119]
	v_mfma_f32_16x16x32_bf16 v[112:115], v[162:165], v[174:177], v[112:115]
	v_mfma_f32_16x16x32_bf16 v[100:103], v[154:157], v[182:185], v[100:103]
	v_mfma_f32_16x16x32_bf16 v[96:99], v[162:165], v[182:185], v[96:99]
	v_mfma_f32_16x16x32_bf16 v[84:87], v[154:157], v[190:193], v[84:87]
	v_mfma_f32_16x16x32_bf16 v[80:83], v[162:165], v[190:193], v[80:83]
	v_mfma_f32_16x16x32_bf16 v[68:71], v[154:157], v[198:201], v[68:71]
	v_mfma_f32_16x16x32_bf16 v[64:67], v[162:165], v[198:201], v[64:67]
	s_barrier
	s_mov_b32 m0, s69
	v_lshl_add_u64 v[166:167], s[38:39], 0, v[232:233]
	ds_read_b128 v[170:173], v169 offset:16384
	ds_read_b128 v[174:177], v169 offset:17408
	ds_read_b128 v[178:181], v169 offset:18432
	ds_read_b128 v[182:185], v169 offset:19456
	ds_read_b128 v[186:189], v169 offset:20480
	ds_read_b128 v[190:193], v169 offset:21504
	ds_read_b128 v[194:197], v169 offset:22528
	ds_read_b128 v[198:201], v169 offset:23552
	global_load_lds_dwordx4 v[166:167], off
	v_lshl_add_u64 v[202:203], s[38:39], 0, v[132:133]
	s_mov_b32 m0, s66
	v_lshl_add_u64 v[204:205], s[40:41], 0, v[232:233]
	global_load_lds_dwordx4 v[202:203], off
	s_mov_b32 m0, s68
	v_lshl_add_u64 v[206:207], s[36:37], 0, v[130:131]
	global_load_lds_dwordx4 v[204:205], off
	v_lshl_add_u64 v[204:205], s[40:41], 0, v[132:133]
	s_mov_b32 m0, s67
	s_nop 0
	global_load_lds_dwordx4 v[204:205], off
	v_lshl_add_u64 v[204:205], s[36:37], 0, v[128:129]
	s_mov_b32 m0, s51
	s_nop 0
	global_load_lds_dwordx4 v[204:205], off
	s_mov_b32 m0, s52
	s_nop 0
	global_load_lds_dwordx4 v[206:207], off
	s_waitcnt vmcnt(8)
	s_waitcnt lgkmcnt(0)
	s_barrier
	s_waitcnt lgkmcnt(0)
	v_mfma_f32_16x16x32_bf16 v[60:63], v[134:137], v[170:173], v[60:63]
	v_mfma_f32_16x16x32_bf16 v[56:59], v[142:145], v[170:173], v[56:59]
	v_mfma_f32_16x16x32_bf16 v[44:47], v[134:137], v[178:181], v[44:47]
	v_mfma_f32_16x16x32_bf16 v[40:43], v[142:145], v[178:181], v[40:43]
	v_mfma_f32_16x16x32_bf16 v[28:31], v[134:137], v[186:189], v[28:31]
	v_mfma_f32_16x16x32_bf16 v[24:27], v[142:145], v[186:189], v[24:27]
	v_mfma_f32_16x16x32_bf16 v[12:15], v[134:137], v[194:197], v[12:15]
	v_mfma_f32_16x16x32_bf16 v[8:11], v[142:145], v[194:197], v[8:11]
	v_mfma_f32_16x16x32_bf16 v[60:63], v[138:141], v[174:177], v[60:63]
	v_mfma_f32_16x16x32_bf16 v[56:59], v[146:149], v[174:177], v[56:59]
	v_mfma_f32_16x16x32_bf16 v[44:47], v[138:141], v[182:185], v[44:47]
	v_mfma_f32_16x16x32_bf16 v[40:43], v[146:149], v[182:185], v[40:43]
	v_mfma_f32_16x16x32_bf16 v[28:31], v[138:141], v[190:193], v[28:31]
	v_mfma_f32_16x16x32_bf16 v[24:27], v[146:149], v[190:193], v[24:27]
	v_mfma_f32_16x16x32_bf16 v[12:15], v[138:141], v[198:201], v[12:15]
	v_mfma_f32_16x16x32_bf16 v[8:11], v[146:149], v[198:201], v[8:11]
	v_mfma_f32_16x16x32_bf16 v[52:55], v[150:153], v[170:173], v[52:55]
	v_mfma_f32_16x16x32_bf16 v[48:51], v[158:161], v[170:173], v[48:51]
	v_mfma_f32_16x16x32_bf16 v[36:39], v[150:153], v[178:181], v[36:39]
	v_mfma_f32_16x16x32_bf16 v[32:35], v[158:161], v[178:181], v[32:35]
	v_mfma_f32_16x16x32_bf16 v[20:23], v[150:153], v[186:189], v[20:23]
	v_mfma_f32_16x16x32_bf16 v[16:19], v[158:161], v[186:189], v[16:19]
	v_mfma_f32_16x16x32_bf16 v[4:7], v[150:153], v[194:197], v[4:7]
	v_mfma_f32_16x16x32_bf16 v[0:3], v[158:161], v[194:197], v[0:3]
	v_mfma_f32_16x16x32_bf16 v[52:55], v[154:157], v[174:177], v[52:55]
	v_mfma_f32_16x16x32_bf16 v[48:51], v[162:165], v[174:177], v[48:51]
	v_mfma_f32_16x16x32_bf16 v[36:39], v[154:157], v[182:185], v[36:39]
	v_mfma_f32_16x16x32_bf16 v[32:35], v[162:165], v[182:185], v[32:35]
	v_mfma_f32_16x16x32_bf16 v[20:23], v[154:157], v[190:193], v[20:23]
	v_mfma_f32_16x16x32_bf16 v[16:19], v[162:165], v[190:193], v[16:19]
	v_mfma_f32_16x16x32_bf16 v[4:7], v[154:157], v[198:201], v[4:7]
	v_mfma_f32_16x16x32_bf16 v[0:3], v[162:165], v[198:201], v[0:3]
	s_barrier
	v_add_u32_e32 v146, s65, v168
	v_add_u32_e32 v162, s64, v168
	ds_read_b128 v[134:137], v146
	ds_read_b128 v[138:141], v146 offset:1024
	ds_read_b128 v[142:145], v146 offset:2048
	ds_read_b128 v[146:149], v146 offset:3072
	ds_read_b128 v[150:153], v162
	ds_read_b128 v[154:157], v162 offset:1024
	ds_read_b128 v[158:161], v162 offset:2048
	ds_read_b128 v[162:165], v162 offset:3072
	s_mov_b32 m0, s53
	v_lshl_add_u64 v[208:209], s[34:35], 0, v[128:129]
	ds_read_b128 v[170:173], v169 offset:32768
	ds_read_b128 v[174:177], v169 offset:33792
	ds_read_b128 v[178:181], v169 offset:34816
	ds_read_b128 v[182:185], v169 offset:35840
	ds_read_b128 v[186:189], v169 offset:36864
	ds_read_b128 v[190:193], v169 offset:37888
	ds_read_b128 v[194:197], v169 offset:38912
	ds_read_b128 v[198:201], v169 offset:39936
	global_load_lds_dwordx4 v[208:209], off
	v_lshl_add_u64 v[208:209], s[34:35], 0, v[130:131]
	s_mov_b32 m0, s54
	s_nop 0
	global_load_lds_dwordx4 v[208:209], off
	s_waitcnt vmcnt(8)
	s_waitcnt lgkmcnt(0)
	s_barrier
	s_waitcnt lgkmcnt(0)
	v_mfma_f32_16x16x32_bf16 v[124:127], v[134:137], v[170:173], v[124:127]
	v_mfma_f32_16x16x32_bf16 v[120:123], v[142:145], v[170:173], v[120:123]
	v_mfma_f32_16x16x32_bf16 v[108:111], v[134:137], v[178:181], v[108:111]
	v_mfma_f32_16x16x32_bf16 v[104:107], v[142:145], v[178:181], v[104:107]
	v_mfma_f32_16x16x32_bf16 v[92:95], v[134:137], v[186:189], v[92:95]
	v_mfma_f32_16x16x32_bf16 v[88:91], v[142:145], v[186:189], v[88:91]
	v_mfma_f32_16x16x32_bf16 v[76:79], v[134:137], v[194:197], v[76:79]
	v_mfma_f32_16x16x32_bf16 v[72:75], v[142:145], v[194:197], v[72:75]
	v_mfma_f32_16x16x32_bf16 v[124:127], v[138:141], v[174:177], v[124:127]
	v_mfma_f32_16x16x32_bf16 v[120:123], v[146:149], v[174:177], v[120:123]
	v_mfma_f32_16x16x32_bf16 v[108:111], v[138:141], v[182:185], v[108:111]
	v_mfma_f32_16x16x32_bf16 v[104:107], v[146:149], v[182:185], v[104:107]
	v_mfma_f32_16x16x32_bf16 v[92:95], v[138:141], v[190:193], v[92:95]
	v_mfma_f32_16x16x32_bf16 v[88:91], v[146:149], v[190:193], v[88:91]
	v_mfma_f32_16x16x32_bf16 v[76:79], v[138:141], v[198:201], v[76:79]
	v_mfma_f32_16x16x32_bf16 v[72:75], v[146:149], v[198:201], v[72:75]
	v_mfma_f32_16x16x32_bf16 v[116:119], v[150:153], v[170:173], v[116:119]
	v_mfma_f32_16x16x32_bf16 v[112:115], v[158:161], v[170:173], v[112:115]
	v_mfma_f32_16x16x32_bf16 v[100:103], v[150:153], v[178:181], v[100:103]
	v_mfma_f32_16x16x32_bf16 v[96:99], v[158:161], v[178:181], v[96:99]
	v_mfma_f32_16x16x32_bf16 v[84:87], v[150:153], v[186:189], v[84:87]
	v_mfma_f32_16x16x32_bf16 v[80:83], v[158:161], v[186:189], v[80:83]
	v_mfma_f32_16x16x32_bf16 v[68:71], v[150:153], v[194:197], v[68:71]
	v_mfma_f32_16x16x32_bf16 v[64:67], v[158:161], v[194:197], v[64:67]
	v_mfma_f32_16x16x32_bf16 v[116:119], v[154:157], v[174:177], v[116:119]
	v_mfma_f32_16x16x32_bf16 v[112:115], v[162:165], v[174:177], v[112:115]
	v_mfma_f32_16x16x32_bf16 v[100:103], v[154:157], v[182:185], v[100:103]
	v_mfma_f32_16x16x32_bf16 v[96:99], v[162:165], v[182:185], v[96:99]
	v_mfma_f32_16x16x32_bf16 v[84:87], v[154:157], v[190:193], v[84:87]
	v_mfma_f32_16x16x32_bf16 v[80:83], v[162:165], v[190:193], v[80:83]
	v_mfma_f32_16x16x32_bf16 v[68:71], v[154:157], v[198:201], v[68:71]
	v_mfma_f32_16x16x32_bf16 v[64:67], v[162:165], v[198:201], v[64:67]
	s_barrier
	s_mov_b32 m0, s63
	v_lshl_add_u64 v[166:167], v[166:167], 0, s[94:95]
	ds_read_b128 v[170:173], v169 offset:49152
	ds_read_b128 v[174:177], v169 offset:50176
	ds_read_b128 v[178:181], v169 offset:51200
	ds_read_b128 v[182:185], v169 offset:52224
	ds_read_b128 v[186:189], v169 offset:53248
	ds_read_b128 v[190:193], v169 offset:54272
	ds_read_b128 v[194:197], v169 offset:55296
	ds_read_b128 v[198:201], v169 offset:56320
	global_load_lds_dwordx4 v[166:167], off
	v_lshl_add_u64 v[166:167], v[202:203], 0, s[94:95]
	s_mov_b32 m0, s62
	s_nop 0
	global_load_lds_dwordx4 v[166:167], off
	v_lshl_add_u64 v[166:167], s[30:31], 0, v[232:233]
	s_mov_b32 m0, s71
	s_nop 0
	global_load_lds_dwordx4 v[166:167], off
	v_lshl_add_u64 v[166:167], s[30:31], 0, v[132:133]
	s_mov_b32 m0, s70
	s_nop 0
	global_load_lds_dwordx4 v[166:167], off
	v_lshl_add_u64 v[166:167], v[204:205], 0, s[94:95]
	s_mov_b32 m0, s57
	s_nop 0
	global_load_lds_dwordx4 v[166:167], off
	v_lshl_add_u64 v[166:167], v[206:207], 0, s[94:95]
	s_mov_b32 m0, s58
	s_nop 0
	global_load_lds_dwordx4 v[166:167], off
	s_waitcnt vmcnt(8)
	s_waitcnt lgkmcnt(0)
	s_barrier
	s_waitcnt lgkmcnt(0)
	v_mfma_f32_16x16x32_bf16 v[60:63], v[134:137], v[170:173], v[60:63]
	v_mfma_f32_16x16x32_bf16 v[56:59], v[142:145], v[170:173], v[56:59]
	v_mfma_f32_16x16x32_bf16 v[44:47], v[134:137], v[178:181], v[44:47]
	v_mfma_f32_16x16x32_bf16 v[40:43], v[142:145], v[178:181], v[40:43]
	v_mfma_f32_16x16x32_bf16 v[28:31], v[134:137], v[186:189], v[28:31]
	v_mfma_f32_16x16x32_bf16 v[24:27], v[142:145], v[186:189], v[24:27]
	v_mfma_f32_16x16x32_bf16 v[12:15], v[134:137], v[194:197], v[12:15]
	v_mfma_f32_16x16x32_bf16 v[8:11], v[142:145], v[194:197], v[8:11]
	v_mfma_f32_16x16x32_bf16 v[60:63], v[138:141], v[174:177], v[60:63]
	v_mfma_f32_16x16x32_bf16 v[56:59], v[146:149], v[174:177], v[56:59]
	v_mfma_f32_16x16x32_bf16 v[44:47], v[138:141], v[182:185], v[44:47]
	v_mfma_f32_16x16x32_bf16 v[40:43], v[146:149], v[182:185], v[40:43]
	v_mfma_f32_16x16x32_bf16 v[28:31], v[138:141], v[190:193], v[28:31]
	v_mfma_f32_16x16x32_bf16 v[24:27], v[146:149], v[190:193], v[24:27]
	v_mfma_f32_16x16x32_bf16 v[12:15], v[138:141], v[198:201], v[12:15]
	v_mfma_f32_16x16x32_bf16 v[8:11], v[146:149], v[198:201], v[8:11]
	v_mfma_f32_16x16x32_bf16 v[52:55], v[150:153], v[170:173], v[52:55]
	v_mfma_f32_16x16x32_bf16 v[48:51], v[158:161], v[170:173], v[48:51]
	v_mfma_f32_16x16x32_bf16 v[36:39], v[150:153], v[178:181], v[36:39]
	v_mfma_f32_16x16x32_bf16 v[32:35], v[158:161], v[178:181], v[32:35]
	v_mfma_f32_16x16x32_bf16 v[20:23], v[150:153], v[186:189], v[20:23]
	v_mfma_f32_16x16x32_bf16 v[16:19], v[158:161], v[186:189], v[16:19]
	v_mfma_f32_16x16x32_bf16 v[4:7], v[150:153], v[194:197], v[4:7]
	v_mfma_f32_16x16x32_bf16 v[0:3], v[158:161], v[194:197], v[0:3]
	v_mfma_f32_16x16x32_bf16 v[52:55], v[154:157], v[174:177], v[52:55]
	v_mfma_f32_16x16x32_bf16 v[48:51], v[162:165], v[174:177], v[48:51]
	v_mfma_f32_16x16x32_bf16 v[36:39], v[154:157], v[182:185], v[36:39]
	v_mfma_f32_16x16x32_bf16 v[32:35], v[162:165], v[182:185], v[32:35]
	v_mfma_f32_16x16x32_bf16 v[20:23], v[154:157], v[190:193], v[20:23]
	v_mfma_f32_16x16x32_bf16 v[16:19], v[162:165], v[190:193], v[16:19]
	v_mfma_f32_16x16x32_bf16 v[4:7], v[154:157], v[198:201], v[4:7]
	v_mfma_f32_16x16x32_bf16 v[0:3], v[162:165], v[198:201], v[0:3]
	s_barrier
	s_movk_i32 s34, 0x100
	s_andn2_b64 vcc, exec, s[28:29]
	s_mov_b64 s[30:31], -1
	s_mov_b64 s[28:29], 0
	s_cbranch_vccz .LBB0_369
	s_and_b64 vcc, exec, s[12:13]
	s_cbranch_vccz .LBB0_372
	s_barrier

.LBB0_911:
	s_ashr_i32 s15, s14, 31
	s_lshl_b64 s[16:17], s[14:15], 19
	s_add_u32 s16, s30, s16
	s_addc_u32 s17, s31, s17
	s_and_b64 s[18:19], s[2:3], exec
	s_cselect_b32 s5, s17, s25
	s_cselect_b32 s15, s16, s24
	s_ashr_i32 s13, s12, 31
	s_lshl_b64 s[18:19], s[12:13], 19
	s_add_u32 s18, s34, s18
	s_addc_u32 s19, s35, s19
	s_and_b64 s[26:27], s[2:3], exec
	s_cselect_b32 s13, s19, s23
	s_cselect_b32 s21, s18, s22
	s_add_u32 s48, s22, 0x100
	s_addc_u32 s49, s23, 0
	s_add_u32 s22, s24, 0x40080
	s_addc_u32 s23, s25, 0
	s_mov_b32 s50, -2
	s_add_u32 s24, s22, 0xfffc0080
	s_addc_u32 s25, s23, -1
	s_add_i32 s51, 0, 0x10000
	s_cmp_eq_u32 s50, 12
	s_cselect_b32 s27, s5, s25
	s_cselect_b32 s26, s15, s24
	v_add_u32_e32 v142, s51, v144
	s_cselect_b32 s25, s13, s49
	s_cselect_b32 s24, s21, s48
	s_add_i32 s54, 0, 0x14000
	ds_read_b128 v[138:141], v142
	ds_read_b128 v[146:149], v142 offset:1024
	ds_read_b128 v[150:153], v142 offset:2048
	ds_read_b128 v[154:157], v142 offset:3072
	v_add_u32_e32 v142, s54, v144
	ds_read_b128 v[158:161], v142
	ds_read_b128 v[162:165], v142 offset:1024
	ds_read_b128 v[166:169], v142 offset:2048
	ds_read_b128 v[170:173], v142 offset:3072
	v_lshl_add_u64 v[142:143], s[22:23], 0, v[136:137]
	s_add_i32 m0, s37, 0xc000
	ds_read_b128 v[174:177], v145
	ds_read_b128 v[178:181], v145 offset:1024
	ds_read_b128 v[182:185], v145 offset:2048
	ds_read_b128 v[186:189], v145 offset:3072
	ds_read_b128 v[190:193], v145 offset:4096
	ds_read_b128 v[194:197], v145 offset:5120
	ds_read_b128 v[198:201], v145 offset:6144
	ds_read_b128 v[202:205], v145 offset:7168
	global_load_lds_dwordx4 v[142:143], off
	v_lshl_add_u64 v[142:143], s[22:23], 0, v[134:135]
	s_add_i32 m0, s37, 0xe000
	s_nop 0
	global_load_lds_dwordx4 v[142:143], off
	s_waitcnt vmcnt(8)
	s_waitcnt lgkmcnt(0)
	s_barrier
	s_waitcnt lgkmcnt(0)
	v_mfma_f32_16x16x32_bf16 v[124:127], v[138:141], v[174:177], 0
	v_mfma_f32_16x16x32_bf16 v[120:123], v[150:153], v[174:177], 0
	v_mfma_f32_16x16x32_bf16 v[108:111], v[138:141], v[182:185], 0
	v_mfma_f32_16x16x32_bf16 v[104:107], v[150:153], v[182:185], 0
	v_mfma_f32_16x16x32_bf16 v[92:95], v[138:141], v[190:193], 0
	v_mfma_f32_16x16x32_bf16 v[88:91], v[150:153], v[190:193], 0
	v_mfma_f32_16x16x32_bf16 v[76:79], v[138:141], v[198:201], 0
	v_mfma_f32_16x16x32_bf16 v[72:75], v[150:153], v[198:201], 0
	v_mfma_f32_16x16x32_bf16 v[124:127], v[146:149], v[178:181], v[124:127]
	v_mfma_f32_16x16x32_bf16 v[120:123], v[154:157], v[178:181], v[120:123]
	v_mfma_f32_16x16x32_bf16 v[108:111], v[146:149], v[186:189], v[108:111]
	v_mfma_f32_16x16x32_bf16 v[104:107], v[154:157], v[186:189], v[104:107]
	v_mfma_f32_16x16x32_bf16 v[92:95], v[146:149], v[194:197], v[92:95]
	v_mfma_f32_16x16x32_bf16 v[88:91], v[154:157], v[194:197], v[88:91]
	v_mfma_f32_16x16x32_bf16 v[76:79], v[146:149], v[202:205], v[76:79]
	v_mfma_f32_16x16x32_bf16 v[72:75], v[154:157], v[202:205], v[72:75]
	v_mfma_f32_16x16x32_bf16 v[116:119], v[158:161], v[174:177], 0
	v_mfma_f32_16x16x32_bf16 v[112:115], v[166:169], v[174:177], 0
	v_mfma_f32_16x16x32_bf16 v[100:103], v[158:161], v[182:185], 0
	v_mfma_f32_16x16x32_bf16 v[96:99], v[166:169], v[182:185], 0
	v_mfma_f32_16x16x32_bf16 v[84:87], v[158:161], v[190:193], 0
	v_mfma_f32_16x16x32_bf16 v[80:83], v[166:169], v[190:193], 0
	v_mfma_f32_16x16x32_bf16 v[68:71], v[158:161], v[198:201], 0
	v_mfma_f32_16x16x32_bf16 v[64:67], v[166:169], v[198:201], 0
	v_mfma_f32_16x16x32_bf16 v[116:119], v[162:165], v[178:181], v[116:119]
	v_mfma_f32_16x16x32_bf16 v[112:115], v[170:173], v[178:181], v[112:115]
	v_mfma_f32_16x16x32_bf16 v[100:103], v[162:165], v[186:189], v[100:103]
	v_mfma_f32_16x16x32_bf16 v[96:99], v[170:173], v[186:189], v[96:99]
	v_mfma_f32_16x16x32_bf16 v[84:87], v[162:165], v[194:197], v[84:87]
	v_mfma_f32_16x16x32_bf16 v[80:83], v[170:173], v[194:197], v[80:83]
	v_mfma_f32_16x16x32_bf16 v[68:71], v[162:165], v[202:205], v[68:71]
	v_mfma_f32_16x16x32_bf16 v[64:67], v[170:173], v[202:205], v[64:67]
	s_barrier
	s_add_i32 s51, s51, s36
	v_lshl_add_u64 v[142:143], s[24:25], 0, v[232:233]
	s_mov_b32 m0, s51
	ds_read_b128 v[174:177], v145 offset:16384
	ds_read_b128 v[178:181], v145 offset:17408
	ds_read_b128 v[182:185], v145 offset:18432
	ds_read_b128 v[186:189], v145 offset:19456
	ds_read_b128 v[190:193], v145 offset:20480
	ds_read_b128 v[194:197], v145 offset:21504
	ds_read_b128 v[198:201], v145 offset:22528
	ds_read_b128 v[202:205], v145 offset:23552
	global_load_lds_dwordx4 v[142:143], off
	s_add_i32 m0, s51, 0x2000
	s_add_u32 s52, s24, 0x40000
	v_lshl_add_u64 v[206:207], s[24:25], 0, v[132:133]
	s_addc_u32 s53, s25, 0
	s_add_i32 s51, s54, s36
	global_load_lds_dwordx4 v[206:207], off
	v_lshl_add_u64 v[208:209], s[52:53], 0, v[232:233]
	s_mov_b32 m0, s51
	v_lshl_add_u64 v[210:211], s[26:27], 0, v[130:131]
	global_load_lds_dwordx4 v[208:209], off
	v_lshl_add_u64 v[208:209], s[52:53], 0, v[132:133]
	s_add_i32 m0, s51, 0x2000
	s_nop 0
	global_load_lds_dwordx4 v[208:209], off
	v_lshl_add_u64 v[208:209], s[26:27], 0, v[128:129]
	s_waitcnt vmcnt(6)
	s_waitcnt lgkmcnt(0)
	s_barrier
	s_waitcnt lgkmcnt(0)
	v_mfma_f32_16x16x32_bf16 v[60:63], v[138:141], v[174:177], 0
	v_mfma_f32_16x16x32_bf16 v[56:59], v[150:153], v[174:177], 0
	v_mfma_f32_16x16x32_bf16 v[44:47], v[138:141], v[182:185], 0
	v_mfma_f32_16x16x32_bf16 v[40:43], v[150:153], v[182:185], 0
	v_mfma_f32_16x16x32_bf16 v[28:31], v[138:141], v[190:193], 0
	v_mfma_f32_16x16x32_bf16 v[24:27], v[150:153], v[190:193], 0
	v_mfma_f32_16x16x32_bf16 v[12:15], v[138:141], v[198:201], 0
	v_mfma_f32_16x16x32_bf16 v[8:11], v[150:153], v[198:201], 0
	v_mfma_f32_16x16x32_bf16 v[60:63], v[146:149], v[178:181], v[60:63]
	v_mfma_f32_16x16x32_bf16 v[56:59], v[154:157], v[178:181], v[56:59]
	v_mfma_f32_16x16x32_bf16 v[44:47], v[146:149], v[186:189], v[44:47]
	v_mfma_f32_16x16x32_bf16 v[40:43], v[154:157], v[186:189], v[40:43]
	v_mfma_f32_16x16x32_bf16 v[28:31], v[146:149], v[194:197], v[28:31]
	v_mfma_f32_16x16x32_bf16 v[24:27], v[154:157], v[194:197], v[24:27]
	v_mfma_f32_16x16x32_bf16 v[12:15], v[146:149], v[202:205], v[12:15]
	v_mfma_f32_16x16x32_bf16 v[8:11], v[154:157], v[202:205], v[8:11]
	v_mfma_f32_16x16x32_bf16 v[52:55], v[158:161], v[174:177], 0
	v_mfma_f32_16x16x32_bf16 v[48:51], v[166:169], v[174:177], 0
	v_mfma_f32_16x16x32_bf16 v[36:39], v[158:161], v[182:185], 0
	v_mfma_f32_16x16x32_bf16 v[32:35], v[166:169], v[182:185], 0
	v_mfma_f32_16x16x32_bf16 v[20:23], v[158:161], v[190:193], 0
	v_mfma_f32_16x16x32_bf16 v[16:19], v[166:169], v[190:193], 0
	v_mfma_f32_16x16x32_bf16 v[4:7], v[158:161], v[198:201], 0
	v_mfma_f32_16x16x32_bf16 v[0:3], v[166:169], v[198:201], 0
	v_mfma_f32_16x16x32_bf16 v[52:55], v[162:165], v[178:181], v[52:55]
	v_mfma_f32_16x16x32_bf16 v[48:51], v[170:173], v[178:181], v[48:51]
	v_mfma_f32_16x16x32_bf16 v[36:39], v[162:165], v[186:189], v[36:39]
	v_mfma_f32_16x16x32_bf16 v[32:35], v[170:173], v[186:189], v[32:35]
	v_mfma_f32_16x16x32_bf16 v[20:23], v[162:165], v[194:197], v[20:23]
	v_mfma_f32_16x16x32_bf16 v[16:19], v[170:173], v[194:197], v[16:19]
	v_mfma_f32_16x16x32_bf16 v[4:7], v[162:165], v[202:205], v[4:7]
	v_mfma_f32_16x16x32_bf16 v[0:3], v[170:173], v[202:205], v[0:3]
	s_barrier
	s_branch .Lzmid_2
.LBB0_912:
	s_add_u32 s24, s22, 0xfffc0080
	s_addc_u32 s25, s23, -1
	s_add_i32 s51, 0, 0x10000
	s_cmp_eq_u32 s50, 12
	s_cselect_b32 s27, s5, s25
	s_cselect_b32 s26, s15, s24
	v_add_u32_e32 v142, s51, v144
	s_cselect_b32 s25, s13, s49
	s_cselect_b32 s24, s21, s48
	s_add_i32 s54, 0, 0x14000
	ds_read_b128 v[138:141], v142
	ds_read_b128 v[146:149], v142 offset:1024
	ds_read_b128 v[150:153], v142 offset:2048
	ds_read_b128 v[154:157], v142 offset:3072
	v_add_u32_e32 v142, s54, v144
	ds_read_b128 v[158:161], v142
	ds_read_b128 v[162:165], v142 offset:1024
	ds_read_b128 v[166:169], v142 offset:2048
	ds_read_b128 v[170:173], v142 offset:3072
	v_lshl_add_u64 v[142:143], s[22:23], 0, v[136:137]
	s_add_i32 m0, s37, 0xc000
	ds_read_b128 v[174:177], v145
	ds_read_b128 v[178:181], v145 offset:1024
	ds_read_b128 v[182:185], v145 offset:2048
	ds_read_b128 v[186:189], v145 offset:3072
	ds_read_b128 v[190:193], v145 offset:4096
	ds_read_b128 v[194:197], v145 offset:5120
	ds_read_b128 v[198:201], v145 offset:6144
	ds_read_b128 v[202:205], v145 offset:7168
	global_load_lds_dwordx4 v[142:143], off
	v_lshl_add_u64 v[142:143], s[22:23], 0, v[134:135]
	s_add_i32 m0, s37, 0xe000
	s_nop 0
	global_load_lds_dwordx4 v[142:143], off
	s_waitcnt vmcnt(8)
	s_waitcnt lgkmcnt(0)
	s_barrier
	s_waitcnt lgkmcnt(0)
	v_mfma_f32_16x16x32_bf16 v[124:127], v[138:141], v[174:177], v[124:127]
	v_mfma_f32_16x16x32_bf16 v[120:123], v[150:153], v[174:177], v[120:123]
	v_mfma_f32_16x16x32_bf16 v[108:111], v[138:141], v[182:185], v[108:111]
	v_mfma_f32_16x16x32_bf16 v[104:107], v[150:153], v[182:185], v[104:107]
	v_mfma_f32_16x16x32_bf16 v[92:95], v[138:141], v[190:193], v[92:95]
	v_mfma_f32_16x16x32_bf16 v[88:91], v[150:153], v[190:193], v[88:91]
	v_mfma_f32_16x16x32_bf16 v[76:79], v[138:141], v[198:201], v[76:79]
	v_mfma_f32_16x16x32_bf16 v[72:75], v[150:153], v[198:201], v[72:75]
	v_mfma_f32_16x16x32_bf16 v[124:127], v[146:149], v[178:181], v[124:127]
	v_mfma_f32_16x16x32_bf16 v[120:123], v[154:157], v[178:181], v[120:123]
	v_mfma_f32_16x16x32_bf16 v[108:111], v[146:149], v[186:189], v[108:111]
	v_mfma_f32_16x16x32_bf16 v[104:107], v[154:157], v[186:189], v[104:107]
	v_mfma_f32_16x16x32_bf16 v[92:95], v[146:149], v[194:197], v[92:95]
	v_mfma_f32_16x16x32_bf16 v[88:91], v[154:157], v[194:197], v[88:91]
	v_mfma_f32_16x16x32_bf16 v[76:79], v[146:149], v[202:205], v[76:79]
	v_mfma_f32_16x16x32_bf16 v[72:75], v[154:157], v[202:205], v[72:75]
	v_mfma_f32_16x16x32_bf16 v[116:119], v[158:161], v[174:177], v[116:119]
	v_mfma_f32_16x16x32_bf16 v[112:115], v[166:169], v[174:177], v[112:115]
	v_mfma_f32_16x16x32_bf16 v[100:103], v[158:161], v[182:185], v[100:103]
	v_mfma_f32_16x16x32_bf16 v[96:99], v[166:169], v[182:185], v[96:99]
	v_mfma_f32_16x16x32_bf16 v[84:87], v[158:161], v[190:193], v[84:87]
	v_mfma_f32_16x16x32_bf16 v[80:83], v[166:169], v[190:193], v[80:83]
	v_mfma_f32_16x16x32_bf16 v[68:71], v[158:161], v[198:201], v[68:71]
	v_mfma_f32_16x16x32_bf16 v[64:67], v[166:169], v[198:201], v[64:67]
	v_mfma_f32_16x16x32_bf16 v[116:119], v[162:165], v[178:181], v[116:119]
	v_mfma_f32_16x16x32_bf16 v[112:115], v[170:173], v[178:181], v[112:115]
	v_mfma_f32_16x16x32_bf16 v[100:103], v[162:165], v[186:189], v[100:103]
	v_mfma_f32_16x16x32_bf16 v[96:99], v[170:173], v[186:189], v[96:99]
	v_mfma_f32_16x16x32_bf16 v[84:87], v[162:165], v[194:197], v[84:87]
	v_mfma_f32_16x16x32_bf16 v[80:83], v[170:173], v[194:197], v[80:83]
	v_mfma_f32_16x16x32_bf16 v[68:71], v[162:165], v[202:205], v[68:71]
	v_mfma_f32_16x16x32_bf16 v[64:67], v[170:173], v[202:205], v[64:67]
	s_barrier
	s_add_i32 s51, s51, s36
	v_lshl_add_u64 v[142:143], s[24:25], 0, v[232:233]
	s_mov_b32 m0, s51
	ds_read_b128 v[174:177], v145 offset:16384
	ds_read_b128 v[178:181], v145 offset:17408
	ds_read_b128 v[182:185], v145 offset:18432
	ds_read_b128 v[186:189], v145 offset:19456
	ds_read_b128 v[190:193], v145 offset:20480
	ds_read_b128 v[194:197], v145 offset:21504
	ds_read_b128 v[198:201], v145 offset:22528
	ds_read_b128 v[202:205], v145 offset:23552
	global_load_lds_dwordx4 v[142:143], off
	s_add_i32 m0, s51, 0x2000
	s_add_u32 s52, s24, 0x40000
	v_lshl_add_u64 v[206:207], s[24:25], 0, v[132:133]
	s_addc_u32 s53, s25, 0
	s_add_i32 s51, s54, s36
	global_load_lds_dwordx4 v[206:207], off
	v_lshl_add_u64 v[208:209], s[52:53], 0, v[232:233]
	s_mov_b32 m0, s51
	v_lshl_add_u64 v[210:211], s[26:27], 0, v[130:131]
	global_load_lds_dwordx4 v[208:209], off
	v_lshl_add_u64 v[208:209], s[52:53], 0, v[132:133]
	s_add_i32 m0, s51, 0x2000
	s_nop 0
	global_load_lds_dwordx4 v[208:209], off
	v_lshl_add_u64 v[208:209], s[26:27], 0, v[128:129]
	s_waitcnt vmcnt(6)
	s_waitcnt lgkmcnt(0)
	s_barrier
	s_waitcnt lgkmcnt(0)
	v_mfma_f32_16x16x32_bf16 v[60:63], v[138:141], v[174:177], v[60:63]
	v_mfma_f32_16x16x32_bf16 v[56:59], v[150:153], v[174:177], v[56:59]
	v_mfma_f32_16x16x32_bf16 v[44:47], v[138:141], v[182:185], v[44:47]
	v_mfma_f32_16x16x32_bf16 v[40:43], v[150:153], v[182:185], v[40:43]
	v_mfma_f32_16x16x32_bf16 v[28:31], v[138:141], v[190:193], v[28:31]
	v_mfma_f32_16x16x32_bf16 v[24:27], v[150:153], v[190:193], v[24:27]
	v_mfma_f32_16x16x32_bf16 v[12:15], v[138:141], v[198:201], v[12:15]
	v_mfma_f32_16x16x32_bf16 v[8:11], v[150:153], v[198:201], v[8:11]
	v_mfma_f32_16x16x32_bf16 v[60:63], v[146:149], v[178:181], v[60:63]
	v_mfma_f32_16x16x32_bf16 v[56:59], v[154:157], v[178:181], v[56:59]
	v_mfma_f32_16x16x32_bf16 v[44:47], v[146:149], v[186:189], v[44:47]
	v_mfma_f32_16x16x32_bf16 v[40:43], v[154:157], v[186:189], v[40:43]
	v_mfma_f32_16x16x32_bf16 v[28:31], v[146:149], v[194:197], v[28:31]
	v_mfma_f32_16x16x32_bf16 v[24:27], v[154:157], v[194:197], v[24:27]
	v_mfma_f32_16x16x32_bf16 v[12:15], v[146:149], v[202:205], v[12:15]
	v_mfma_f32_16x16x32_bf16 v[8:11], v[154:157], v[202:205], v[8:11]
	v_mfma_f32_16x16x32_bf16 v[52:55], v[158:161], v[174:177], v[52:55]
	v_mfma_f32_16x16x32_bf16 v[48:51], v[166:169], v[174:177], v[48:51]
	v_mfma_f32_16x16x32_bf16 v[36:39], v[158:161], v[182:185], v[36:39]
	v_mfma_f32_16x16x32_bf16 v[32:35], v[166:169], v[182:185], v[32:35]
	v_mfma_f32_16x16x32_bf16 v[20:23], v[158:161], v[190:193], v[20:23]
	v_mfma_f32_16x16x32_bf16 v[16:19], v[166:169], v[190:193], v[16:19]
	v_mfma_f32_16x16x32_bf16 v[4:7], v[158:161], v[198:201], v[4:7]
	v_mfma_f32_16x16x32_bf16 v[0:3], v[166:169], v[198:201], v[0:3]
	v_mfma_f32_16x16x32_bf16 v[52:55], v[162:165], v[178:181], v[52:55]
	v_mfma_f32_16x16x32_bf16 v[48:51], v[170:173], v[178:181], v[48:51]
	v_mfma_f32_16x16x32_bf16 v[36:39], v[162:165], v[186:189], v[36:39]
	v_mfma_f32_16x16x32_bf16 v[32:35], v[170:173], v[186:189], v[32:35]
	v_mfma_f32_16x16x32_bf16 v[20:23], v[162:165], v[194:197], v[20:23]
	v_mfma_f32_16x16x32_bf16 v[16:19], v[170:173], v[194:197], v[16:19]
	v_mfma_f32_16x16x32_bf16 v[4:7], v[162:165], v[202:205], v[4:7]
	v_mfma_f32_16x16x32_bf16 v[0:3], v[170:173], v[202:205], v[0:3]
	s_barrier
.Lzmid_2:
	s_add_i32 s51, 0, 0x18000
	s_add_i32 s52, 0, 0x1c000
	v_add_u32_e32 v154, s51, v144
	v_add_u32_e32 v170, s52, v144
	ds_read_b128 v[138:141], v154
	ds_read_b128 v[146:149], v154 offset:1024
	ds_read_b128 v[150:153], v154 offset:2048
	ds_read_b128 v[154:157], v154 offset:3072
	ds_read_b128 v[158:161], v170
	ds_read_b128 v[162:165], v170 offset:1024
	ds_read_b128 v[166:169], v170 offset:2048
	ds_read_b128 v[170:173], v170 offset:3072
	s_add_u32 s26, s26, 0x40000
	s_addc_u32 s27, s27, 0
	s_mov_b32 m0, s37
	s_nop 0
	global_load_lds_dwordx4 v[208:209], off
	s_mov_b32 m0, s38
	s_nop 0
	global_load_lds_dwordx4 v[210:211], off
	s_mov_b32 m0, s39
	v_lshl_add_u64 v[212:213], s[26:27], 0, v[128:129]
	ds_read_b128 v[174:177], v145 offset:32768
	ds_read_b128 v[178:181], v145 offset:33792
	ds_read_b128 v[182:185], v145 offset:34816
	ds_read_b128 v[186:189], v145 offset:35840
	ds_read_b128 v[190:193], v145 offset:36864
	ds_read_b128 v[194:197], v145 offset:37888
	ds_read_b128 v[198:201], v145 offset:38912
	ds_read_b128 v[202:205], v145 offset:39936
	global_load_lds_dwordx4 v[212:213], off
	v_lshl_add_u64 v[212:213], s[26:27], 0, v[130:131]
	s_mov_b32 m0, s40
	s_nop 0
	global_load_lds_dwordx4 v[212:213], off
	s_waitcnt vmcnt(8)
	s_waitcnt lgkmcnt(0)
	s_barrier
	s_waitcnt lgkmcnt(0)
	v_mfma_f32_16x16x32_bf16 v[124:127], v[138:141], v[174:177], v[124:127]
	v_mfma_f32_16x16x32_bf16 v[120:123], v[150:153], v[174:177], v[120:123]
	v_mfma_f32_16x16x32_bf16 v[108:111], v[138:141], v[182:185], v[108:111]
	v_mfma_f32_16x16x32_bf16 v[104:107], v[150:153], v[182:185], v[104:107]
	v_mfma_f32_16x16x32_bf16 v[92:95], v[138:141], v[190:193], v[92:95]
	v_mfma_f32_16x16x32_bf16 v[88:91], v[150:153], v[190:193], v[88:91]
	v_mfma_f32_16x16x32_bf16 v[76:79], v[138:141], v[198:201], v[76:79]
	v_mfma_f32_16x16x32_bf16 v[72:75], v[150:153], v[198:201], v[72:75]
	v_mfma_f32_16x16x32_bf16 v[124:127], v[146:149], v[178:181], v[124:127]
	v_mfma_f32_16x16x32_bf16 v[120:123], v[154:157], v[178:181], v[120:123]
	v_mfma_f32_16x16x32_bf16 v[108:111], v[146:149], v[186:189], v[108:111]
	v_mfma_f32_16x16x32_bf16 v[104:107], v[154:157], v[186:189], v[104:107]
	v_mfma_f32_16x16x32_bf16 v[92:95], v[146:149], v[194:197], v[92:95]
	v_mfma_f32_16x16x32_bf16 v[88:91], v[154:157], v[194:197], v[88:91]
	v_mfma_f32_16x16x32_bf16 v[76:79], v[146:149], v[202:205], v[76:79]
	v_mfma_f32_16x16x32_bf16 v[72:75], v[154:157], v[202:205], v[72:75]
	v_mfma_f32_16x16x32_bf16 v[116:119], v[158:161], v[174:177], v[116:119]
	v_mfma_f32_16x16x32_bf16 v[112:115], v[166:169], v[174:177], v[112:115]
	v_mfma_f32_16x16x32_bf16 v[100:103], v[158:161], v[182:185], v[100:103]
	v_mfma_f32_16x16x32_bf16 v[96:99], v[166:169], v[182:185], v[96:99]
	v_mfma_f32_16x16x32_bf16 v[84:87], v[158:161], v[190:193], v[84:87]
	v_mfma_f32_16x16x32_bf16 v[80:83], v[166:169], v[190:193], v[80:83]
	v_mfma_f32_16x16x32_bf16 v[68:71], v[158:161], v[198:201], v[68:71]
	v_mfma_f32_16x16x32_bf16 v[64:67], v[166:169], v[198:201], v[64:67]
	v_mfma_f32_16x16x32_bf16 v[116:119], v[162:165], v[178:181], v[116:119]
	v_mfma_f32_16x16x32_bf16 v[112:115], v[170:173], v[178:181], v[112:115]
	v_mfma_f32_16x16x32_bf16 v[100:103], v[162:165], v[186:189], v[100:103]
	v_mfma_f32_16x16x32_bf16 v[96:99], v[170:173], v[186:189], v[96:99]
	v_mfma_f32_16x16x32_bf16 v[84:87], v[162:165], v[194:197], v[84:87]
	v_mfma_f32_16x16x32_bf16 v[80:83], v[170:173], v[194:197], v[80:83]
	v_mfma_f32_16x16x32_bf16 v[68:71], v[162:165], v[202:205], v[68:71]
	v_mfma_f32_16x16x32_bf16 v[64:67], v[170:173], v[202:205], v[64:67]
	s_barrier
	s_add_i32 s26, s51, s36
	v_lshl_add_u64 v[142:143], v[142:143], 0, s[94:95]
	s_mov_b32 m0, s26
	ds_read_b128 v[174:177], v145 offset:49152
	ds_read_b128 v[178:181], v145 offset:50176
	ds_read_b128 v[182:185], v145 offset:51200
	ds_read_b128 v[186:189], v145 offset:52224
	ds_read_b128 v[190:193], v145 offset:53248
	ds_read_b128 v[194:197], v145 offset:54272
	ds_read_b128 v[198:201], v145 offset:55296
	ds_read_b128 v[202:205], v145 offset:56320
	global_load_lds_dwordx4 v[142:143], off
	s_add_i32 m0, s26, 0x2000
	s_add_u32 s24, s24, 0x40080
	v_lshl_add_u64 v[142:143], v[206:207], 0, s[94:95]
	s_addc_u32 s25, s25, 0
	s_add_i32 s26, s52, s36
	global_load_lds_dwordx4 v[142:143], off
	v_lshl_add_u64 v[142:143], s[24:25], 0, v[232:233]
	s_mov_b32 m0, s26
	s_nop 0
	global_load_lds_dwordx4 v[142:143], off
	v_lshl_add_u64 v[142:143], s[24:25], 0, v[132:133]
	s_add_i32 m0, s26, 0x2000
	s_nop 0
	global_load_lds_dwordx4 v[142:143], off
	v_lshl_add_u64 v[142:143], v[208:209], 0, s[94:95]
	s_mov_b32 m0, s43
	s_nop 0
	global_load_lds_dwordx4 v[142:143], off
	v_lshl_add_u64 v[142:143], v[210:211], 0, s[94:95]
	s_mov_b32 m0, s44
	s_nop 0
	global_load_lds_dwordx4 v[142:143], off
	s_waitcnt vmcnt(8)
	s_waitcnt lgkmcnt(0)
	s_barrier
	s_waitcnt lgkmcnt(0)
	v_mfma_f32_16x16x32_bf16 v[60:63], v[138:141], v[174:177], v[60:63]
	v_mfma_f32_16x16x32_bf16 v[56:59], v[150:153], v[174:177], v[56:59]
	v_mfma_f32_16x16x32_bf16 v[44:47], v[138:141], v[182:185], v[44:47]
	v_mfma_f32_16x16x32_bf16 v[40:43], v[150:153], v[182:185], v[40:43]
	v_mfma_f32_16x16x32_bf16 v[28:31], v[138:141], v[190:193], v[28:31]
	v_mfma_f32_16x16x32_bf16 v[24:27], v[150:153], v[190:193], v[24:27]
	v_mfma_f32_16x16x32_bf16 v[12:15], v[138:141], v[198:201], v[12:15]
	v_mfma_f32_16x16x32_bf16 v[8:11], v[150:153], v[198:201], v[8:11]
	v_mfma_f32_16x16x32_bf16 v[60:63], v[146:149], v[178:181], v[60:63]
	v_mfma_f32_16x16x32_bf16 v[56:59], v[154:157], v[178:181], v[56:59]
	v_mfma_f32_16x16x32_bf16 v[44:47], v[146:149], v[186:189], v[44:47]
	v_mfma_f32_16x16x32_bf16 v[40:43], v[154:157], v[186:189], v[40:43]
	v_mfma_f32_16x16x32_bf16 v[28:31], v[146:149], v[194:197], v[28:31]
	v_mfma_f32_16x16x32_bf16 v[24:27], v[154:157], v[194:197], v[24:27]
	v_mfma_f32_16x16x32_bf16 v[12:15], v[146:149], v[202:205], v[12:15]
	v_mfma_f32_16x16x32_bf16 v[8:11], v[154:157], v[202:205], v[8:11]
	v_mfma_f32_16x16x32_bf16 v[52:55], v[158:161], v[174:177], v[52:55]
	v_mfma_f32_16x16x32_bf16 v[48:51], v[166:169], v[174:177], v[48:51]
	v_mfma_f32_16x16x32_bf16 v[36:39], v[158:161], v[182:185], v[36:39]
	v_mfma_f32_16x16x32_bf16 v[32:35], v[166:169], v[182:185], v[32:35]
	v_mfma_f32_16x16x32_bf16 v[20:23], v[158:161], v[190:193], v[20:23]
	v_mfma_f32_16x16x32_bf16 v[16:19], v[166:169], v[190:193], v[16:19]
	v_mfma_f32_16x16x32_bf16 v[4:7], v[158:161], v[198:201], v[4:7]
	v_mfma_f32_16x16x32_bf16 v[0:3], v[166:169], v[198:201], v[0:3]
	v_mfma_f32_16x16x32_bf16 v[52:55], v[162:165], v[178:181], v[52:55]
	v_mfma_f32_16x16x32_bf16 v[48:51], v[170:173], v[178:181], v[48:51]
	v_mfma_f32_16x16x32_bf16 v[36:39], v[162:165], v[186:189], v[36:39]
	v_mfma_f32_16x16x32_bf16 v[32:35], v[170:173], v[186:189], v[32:35]
	v_mfma_f32_16x16x32_bf16 v[20:23], v[162:165], v[194:197], v[20:23]
	v_mfma_f32_16x16x32_bf16 v[16:19], v[170:173], v[194:197], v[16:19]
	v_mfma_f32_16x16x32_bf16 v[4:7], v[162:165], v[202:205], v[4:7]
	v_mfma_f32_16x16x32_bf16 v[0:3], v[170:173], v[202:205], v[0:3]
	s_barrier
	s_add_i32 s50, s50, 2
	s_add_u32 s48, s48, 0x100
	s_addc_u32 s49, s49, 0
	s_add_u32 s22, s22, 0x100
	s_addc_u32 s23, s23, 0
	s_cmp_gt_u32 s50, 13
	s_cbranch_scc0 .LBB0_912
	s_and_b64 vcc, exec, s[10:11]
	s_cbranch_vccz .LBB0_915
	s_barrier

.LBB0_1018:
	s_ashr_i32 s15, s14, 31
	s_ashr_i32 s13, s12, 31
	s_lshl_b64 s[16:17], s[14:15], 19
	s_lshl_b64 s[18:19], s[12:13], 9
	s_add_u32 s13, s34, s16
	s_addc_u32 s15, s35, s17
	s_add_u32 s16, s13, s18
	s_addc_u32 s17, s15, s19
	s_and_b64 s[18:19], s[2:3], exec
	s_cselect_b32 s29, s17, s23
	s_cselect_b32 s28, s16, s22
	s_lshl_b32 s13, s12, 2
	s_add_i32 s18, s13, s51
	s_ashr_i32 s19, s18, 31
	s_lshl_b64 s[18:19], s[18:19], 17
	s_add_u32 s18, s36, s18
	s_addc_u32 s19, s37, s19
	s_and_b64 s[26:27], s[2:3], exec
	s_cselect_b32 s27, s19, s25
	s_cselect_b32 s26, s18, s24
	s_add_i32 s15, 0, 0x10000
	s_add_i32 s21, 0, 0x14000
	v_add_u32_e32 v253, 0x10000, v174
	v_add_u32_e32 v252, 0x14000, v174
	ds_read_b128 v[128:131], v253
	ds_read_b128 v[132:135], v253 offset:1024
	ds_read_b128 v[136:139], v253 offset:2048
	ds_read_b128 v[140:143], v253 offset:3072
	ds_read_b128 v[144:147], v252
	ds_read_b128 v[148:151], v252 offset:1024
	ds_read_b128 v[152:155], v252 offset:2048
	ds_read_b128 v[156:159], v252 offset:3072
	s_add_u32 s52, s22, 0x40080
	s_addc_u32 s53, s23, 0
	s_add_i32 s55, s39, 0xc000
	s_waitcnt vmcnt(0)
	s_mov_b32 m0, s55
	s_add_i32 s13, s39, 0xe000
	ds_read_b128 v[168:171], v175
	ds_read_b128 v[176:179], v175 offset:1024
	ds_read_b128 v[180:183], v175 offset:2048
	ds_read_b128 v[184:187], v175 offset:3072
	ds_read_b128 v[188:191], v175 offset:4096
	ds_read_b128 v[192:195], v175 offset:5120
	ds_read_b128 v[196:199], v175 offset:6144
	ds_read_b128 v[200:203], v175 offset:7168
	global_load_lds_dwordx4 v160, s[52:53]
	s_mov_b32 m0, s13
	s_nop 0
	global_load_lds_dwordx4 v162, s[52:53]
	s_waitcnt vmcnt(8)
	s_waitcnt lgkmcnt(0)
	s_barrier
	s_waitcnt lgkmcnt(0)
	v_mfma_f32_16x16x32_bf16 v[0:3], v[128:131], v[168:171], 0
	v_mfma_f32_16x16x32_bf16 v[4:7], v[136:139], v[168:171], 0
	v_mfma_f32_16x16x32_bf16 v[16:19], v[128:131], v[180:183], 0
	v_mfma_f32_16x16x32_bf16 v[20:23], v[136:139], v[180:183], 0
	v_mfma_f32_16x16x32_bf16 v[32:35], v[128:131], v[188:191], 0
	v_mfma_f32_16x16x32_bf16 v[36:39], v[136:139], v[188:191], 0
	v_mfma_f32_16x16x32_bf16 v[48:51], v[128:131], v[196:199], 0
	v_mfma_f32_16x16x32_bf16 v[52:55], v[136:139], v[196:199], 0
	v_mfma_f32_16x16x32_bf16 v[0:3], v[132:135], v[176:179], v[0:3]
	v_mfma_f32_16x16x32_bf16 v[4:7], v[140:143], v[176:179], v[4:7]
	v_mfma_f32_16x16x32_bf16 v[16:19], v[132:135], v[184:187], v[16:19]
	v_mfma_f32_16x16x32_bf16 v[20:23], v[140:143], v[184:187], v[20:23]
	v_mfma_f32_16x16x32_bf16 v[32:35], v[132:135], v[192:195], v[32:35]
	v_mfma_f32_16x16x32_bf16 v[36:39], v[140:143], v[192:195], v[36:39]
	v_mfma_f32_16x16x32_bf16 v[48:51], v[132:135], v[200:203], v[48:51]
	v_mfma_f32_16x16x32_bf16 v[52:55], v[140:143], v[200:203], v[52:55]
	v_mfma_f32_16x16x32_bf16 v[8:11], v[144:147], v[168:171], 0
	v_mfma_f32_16x16x32_bf16 v[12:15], v[152:155], v[168:171], 0
	v_mfma_f32_16x16x32_bf16 v[8:11], v[148:151], v[176:179], v[8:11]
	v_mfma_f32_16x16x32_bf16 v[12:15], v[156:159], v[176:179], v[12:15]
	v_mfma_f32_16x16x32_bf16 v[24:27], v[144:147], v[180:183], 0
	v_mfma_f32_16x16x32_bf16 v[28:31], v[152:155], v[180:183], 0
	v_mfma_f32_16x16x32_bf16 v[24:27], v[148:151], v[184:187], v[24:27]
	v_mfma_f32_16x16x32_bf16 v[28:31], v[156:159], v[184:187], v[28:31]
	v_mfma_f32_16x16x32_bf16 v[40:43], v[144:147], v[188:191], 0
	v_mfma_f32_16x16x32_bf16 v[44:47], v[152:155], v[188:191], 0
	v_mfma_f32_16x16x32_bf16 v[40:43], v[148:151], v[192:195], v[40:43]
	v_mfma_f32_16x16x32_bf16 v[44:47], v[156:159], v[192:195], v[44:47]
	v_mfma_f32_16x16x32_bf16 v[56:59], v[144:147], v[196:199], 0
	v_mfma_f32_16x16x32_bf16 v[60:63], v[152:155], v[196:199], 0
	v_mfma_f32_16x16x32_bf16 v[56:59], v[148:151], v[200:203], v[56:59]
	v_mfma_f32_16x16x32_bf16 v[60:63], v[156:159], v[200:203], v[60:63]
	s_barrier
	s_add_i32 s53, s15, s38
	s_mov_b64 s[58:59], 0x100
	s_add_i32 s15, s53, 0x2000
	s_add_u32 s68, s24, s58
	s_addc_u32 s69, s25, s59
	s_mov_b32 m0, s53
	s_add_u32 s70, s24, s58
	s_addc_u32 s71, s25, s59
	s_add_u32 s56, s24, 0x10100
	ds_read_b128 v[168:171], v175 offset:16384
	ds_read_b128 v[176:179], v175 offset:17408
	ds_read_b128 v[180:183], v175 offset:18432
	ds_read_b128 v[184:187], v175 offset:19456
	ds_read_b128 v[188:191], v175 offset:20480
	ds_read_b128 v[192:195], v175 offset:21504
	ds_read_b128 v[196:199], v175 offset:22528
	ds_read_b128 v[200:203], v175 offset:23552
	global_load_lds_dwordx4 v232, s[68:69]
	s_mov_b32 m0, s15
	s_addc_u32 s57, s25, 0
	s_add_i32 s21, s21, s38
	global_load_lds_dwordx4 v164, s[70:71]
	s_mov_b32 m0, s21
	s_add_i32 s52, s21, 0x2000
	global_load_lds_dwordx4 v232, s[56:57]
	s_mov_b32 m0, s52
	global_load_lds_dwordx4 v164, s[56:57]
	s_add_u32 s68, s22, s58
	s_addc_u32 s69, s23, s59
	s_mov_b32 m0, s39
	global_load_lds_dwordx4 v160, s[68:69]
	s_add_u32 s68, s22, s58
	s_addc_u32 s69, s23, s59
	s_mov_b32 m0, s40
	s_nop 0
	global_load_lds_dwordx4 v162, s[68:69]
	s_waitcnt vmcnt(8)
	s_waitcnt lgkmcnt(0)
	s_barrier
	s_waitcnt lgkmcnt(0)
	v_mfma_f32_16x16x32_bf16 v[64:67], v[128:131], v[168:171], 0
	v_mfma_f32_16x16x32_bf16 v[80:83], v[128:131], v[180:183], 0
	v_mfma_f32_16x16x32_bf16 v[96:99], v[128:131], v[188:191], 0
	v_mfma_f32_16x16x32_bf16 v[112:115], v[128:131], v[196:199], 0
	v_mfma_f32_16x16x32_bf16 v[64:67], v[132:135], v[176:179], v[64:67]
	v_mfma_f32_16x16x32_bf16 v[68:71], v[136:139], v[168:171], 0
	v_mfma_f32_16x16x32_bf16 v[80:83], v[132:135], v[184:187], v[80:83]
	v_mfma_f32_16x16x32_bf16 v[84:87], v[136:139], v[180:183], 0
	v_mfma_f32_16x16x32_bf16 v[96:99], v[132:135], v[192:195], v[96:99]
	v_mfma_f32_16x16x32_bf16 v[112:115], v[132:135], v[200:203], v[112:115]
	v_mfma_f32_16x16x32_bf16 v[116:119], v[136:139], v[196:199], 0
	v_mfma_f32_16x16x32_bf16 v[68:71], v[140:143], v[176:179], v[68:71]
	v_mfma_f32_16x16x32_bf16 v[84:87], v[140:143], v[184:187], v[84:87]
	v_mfma_f32_16x16x32_bf16 v[100:103], v[136:139], v[188:191], 0
	v_mfma_f32_16x16x32_bf16 v[116:119], v[140:143], v[200:203], v[116:119]
	v_mfma_f32_16x16x32_bf16 v[100:103], v[140:143], v[192:195], v[100:103]
	v_mfma_f32_16x16x32_bf16 v[72:75], v[144:147], v[168:171], 0
	v_mfma_f32_16x16x32_bf16 v[76:79], v[152:155], v[168:171], 0
	v_mfma_f32_16x16x32_bf16 v[72:75], v[148:151], v[176:179], v[72:75]
	v_mfma_f32_16x16x32_bf16 v[76:79], v[156:159], v[176:179], v[76:79]
	v_mfma_f32_16x16x32_bf16 v[88:91], v[144:147], v[180:183], 0
	v_mfma_f32_16x16x32_bf16 v[92:95], v[152:155], v[180:183], 0
	v_mfma_f32_16x16x32_bf16 v[104:107], v[144:147], v[188:191], 0
	v_mfma_f32_16x16x32_bf16 v[120:123], v[144:147], v[196:199], 0
	v_mfma_f32_16x16x32_bf16 v[88:91], v[148:151], v[184:187], v[88:91]
	v_mfma_f32_16x16x32_bf16 v[92:95], v[156:159], v[184:187], v[92:95]
	v_mfma_f32_16x16x32_bf16 v[104:107], v[148:151], v[192:195], v[104:107]
	v_mfma_f32_16x16x32_bf16 v[108:111], v[152:155], v[188:191], 0
	v_mfma_f32_16x16x32_bf16 v[120:123], v[148:151], v[200:203], v[120:123]
	v_mfma_f32_16x16x32_bf16 v[124:127], v[152:155], v[196:199], 0
	v_mfma_f32_16x16x32_bf16 v[108:111], v[156:159], v[192:195], v[108:111]
	v_mfma_f32_16x16x32_bf16 v[124:127], v[156:159], v[200:203], v[124:127]
	s_barrier
	s_add_i32 s54, 0, 0x18000
	s_add_i32 s60, 0, 0x1c000
	v_add_u32_e32 v253, 0x18000, v174
	v_add_u32_e32 v252, 0x1c000, v174
	ds_read_b128 v[128:131], v253
	ds_read_b128 v[132:135], v253 offset:1024
	ds_read_b128 v[136:139], v253 offset:2048
	ds_read_b128 v[140:143], v253 offset:3072
	ds_read_b128 v[144:147], v252
	ds_read_b128 v[148:151], v252 offset:1024
	ds_read_b128 v[152:155], v252 offset:2048
	ds_read_b128 v[156:159], v252 offset:3072
	s_add_u32 s56, s22, 0x40100
	s_addc_u32 s57, s23, 0
	s_mov_b32 m0, s41
	ds_read_b128 v[168:171], v175 offset:32768
	ds_read_b128 v[176:179], v175 offset:33792
	ds_read_b128 v[180:183], v175 offset:34816
	ds_read_b128 v[184:187], v175 offset:35840
	ds_read_b128 v[188:191], v175 offset:36864
	ds_read_b128 v[192:195], v175 offset:37888
	ds_read_b128 v[196:199], v175 offset:38912
	ds_read_b128 v[200:203], v175 offset:39936
	global_load_lds_dwordx4 v160, s[56:57]
	s_mov_b32 m0, s42
	s_nop 0
	global_load_lds_dwordx4 v162, s[56:57]
	s_waitcnt vmcnt(8)
	s_waitcnt lgkmcnt(0)
	s_barrier
	s_waitcnt lgkmcnt(0)
	v_mfma_f32_16x16x32_bf16 v[0:3], v[128:131], v[168:171], v[0:3]
	v_mfma_f32_16x16x32_bf16 v[4:7], v[136:139], v[168:171], v[4:7]
	v_mfma_f32_16x16x32_bf16 v[16:19], v[128:131], v[180:183], v[16:19]
	v_mfma_f32_16x16x32_bf16 v[20:23], v[136:139], v[180:183], v[20:23]
	v_mfma_f32_16x16x32_bf16 v[32:35], v[128:131], v[188:191], v[32:35]
	v_mfma_f32_16x16x32_bf16 v[36:39], v[136:139], v[188:191], v[36:39]
	v_mfma_f32_16x16x32_bf16 v[48:51], v[128:131], v[196:199], v[48:51]
	v_mfma_f32_16x16x32_bf16 v[52:55], v[136:139], v[196:199], v[52:55]
	v_mfma_f32_16x16x32_bf16 v[0:3], v[132:135], v[176:179], v[0:3]
	v_mfma_f32_16x16x32_bf16 v[4:7], v[140:143], v[176:179], v[4:7]
	v_mfma_f32_16x16x32_bf16 v[16:19], v[132:135], v[184:187], v[16:19]
	v_mfma_f32_16x16x32_bf16 v[20:23], v[140:143], v[184:187], v[20:23]
	v_mfma_f32_16x16x32_bf16 v[32:35], v[132:135], v[192:195], v[32:35]
	v_mfma_f32_16x16x32_bf16 v[36:39], v[140:143], v[192:195], v[36:39]
	v_mfma_f32_16x16x32_bf16 v[48:51], v[132:135], v[200:203], v[48:51]
	v_mfma_f32_16x16x32_bf16 v[52:55], v[140:143], v[200:203], v[52:55]
	v_mfma_f32_16x16x32_bf16 v[8:11], v[144:147], v[168:171], v[8:11]
	v_mfma_f32_16x16x32_bf16 v[24:27], v[144:147], v[180:183], v[24:27]
	v_mfma_f32_16x16x32_bf16 v[28:31], v[152:155], v[180:183], v[28:31]
	v_mfma_f32_16x16x32_bf16 v[44:47], v[152:155], v[188:191], v[44:47]
	v_mfma_f32_16x16x32_bf16 v[56:59], v[144:147], v[196:199], v[56:59]
	v_mfma_f32_16x16x32_bf16 v[60:63], v[152:155], v[196:199], v[60:63]
	v_mfma_f32_16x16x32_bf16 v[8:11], v[148:151], v[176:179], v[8:11]
	v_mfma_f32_16x16x32_bf16 v[12:15], v[152:155], v[168:171], v[12:15]
	v_mfma_f32_16x16x32_bf16 v[24:27], v[148:151], v[184:187], v[24:27]
	v_mfma_f32_16x16x32_bf16 v[28:31], v[156:159], v[184:187], v[28:31]
	v_mfma_f32_16x16x32_bf16 v[40:43], v[144:147], v[188:191], v[40:43]
	v_mfma_f32_16x16x32_bf16 v[44:47], v[156:159], v[192:195], v[44:47]
	v_mfma_f32_16x16x32_bf16 v[56:59], v[148:151], v[200:203], v[56:59]
	v_mfma_f32_16x16x32_bf16 v[60:63], v[156:159], v[200:203], v[60:63]
	v_mfma_f32_16x16x32_bf16 v[12:15], v[156:159], v[176:179], v[12:15]
	v_mfma_f32_16x16x32_bf16 v[40:43], v[148:151], v[192:195], v[40:43]
	s_barrier
	s_add_i32 s56, s54, s38
	s_mov_b64 s[62:63], 0x180
	s_add_i32 s54, s56, 0x2000
	s_add_u32 s68, s24, s62
	s_addc_u32 s69, s25, s63
	s_mov_b32 m0, s56
	s_add_u32 s70, s24, s62
	s_addc_u32 s71, s25, s63
	s_add_u32 s58, s24, 0x10180
	ds_read_b128 v[168:171], v175 offset:49152
	ds_read_b128 v[176:179], v175 offset:50176
	ds_read_b128 v[180:183], v175 offset:51200
	ds_read_b128 v[184:187], v175 offset:52224
	ds_read_b128 v[188:191], v175 offset:53248
	ds_read_b128 v[192:195], v175 offset:54272
	ds_read_b128 v[196:199], v175 offset:55296
	ds_read_b128 v[200:203], v175 offset:56320
	global_load_lds_dwordx4 v232, s[68:69]
	s_mov_b32 m0, s54
	s_addc_u32 s59, s25, 0
	s_add_i32 s24, s60, s38
	global_load_lds_dwordx4 v164, s[70:71]
	s_mov_b32 m0, s24
	s_add_i32 s25, s24, 0x2000
	global_load_lds_dwordx4 v232, s[58:59]
	s_mov_b32 m0, s25
	s_nop 0
	global_load_lds_dwordx4 v164, s[58:59]
	s_add_u32 s68, s22, s62
	s_addc_u32 s69, s23, s63
	s_mov_b32 m0, s47
	s_nop 0
	global_load_lds_dwordx4 v160, s[68:69]
	s_add_u32 s68, s22, s62
	s_addc_u32 s69, s23, s63
	s_mov_b32 m0, s48
	s_nop 0
	global_load_lds_dwordx4 v162, s[68:69]
	s_waitcnt vmcnt(8)
	s_waitcnt lgkmcnt(0)
	s_barrier
	s_waitcnt lgkmcnt(0)
	v_mfma_f32_16x16x32_bf16 v[64:67], v[128:131], v[168:171], v[64:67]
	v_mfma_f32_16x16x32_bf16 v[68:71], v[136:139], v[168:171], v[68:71]
	v_mfma_f32_16x16x32_bf16 v[84:87], v[136:139], v[180:183], v[84:87]
	v_mfma_f32_16x16x32_bf16 v[96:99], v[128:131], v[188:191], v[96:99]
	v_mfma_f32_16x16x32_bf16 v[112:115], v[128:131], v[196:199], v[112:115]
	v_mfma_f32_16x16x32_bf16 v[116:119], v[136:139], v[196:199], v[116:119]
	v_mfma_f32_16x16x32_bf16 v[64:67], v[132:135], v[176:179], v[64:67]
	v_mfma_f32_16x16x32_bf16 v[68:71], v[140:143], v[176:179], v[68:71]
	v_mfma_f32_16x16x32_bf16 v[80:83], v[128:131], v[180:183], v[80:83]
	v_mfma_f32_16x16x32_bf16 v[84:87], v[140:143], v[184:187], v[84:87]
	v_mfma_f32_16x16x32_bf16 v[96:99], v[132:135], v[192:195], v[96:99]
	v_mfma_f32_16x16x32_bf16 v[100:103], v[136:139], v[188:191], v[100:103]
	v_mfma_f32_16x16x32_bf16 v[112:115], v[132:135], v[200:203], v[112:115]
	v_mfma_f32_16x16x32_bf16 v[116:119], v[140:143], v[200:203], v[116:119]
	v_mfma_f32_16x16x32_bf16 v[80:83], v[132:135], v[184:187], v[80:83]
	v_mfma_f32_16x16x32_bf16 v[100:103], v[140:143], v[192:195], v[100:103]
	v_mfma_f32_16x16x32_bf16 v[72:75], v[144:147], v[168:171], v[72:75]
	v_mfma_f32_16x16x32_bf16 v[76:79], v[152:155], v[168:171], v[76:79]
	v_mfma_f32_16x16x32_bf16 v[88:91], v[144:147], v[180:183], v[88:91]
	v_mfma_f32_16x16x32_bf16 v[92:95], v[152:155], v[180:183], v[92:95]
	v_mfma_f32_16x16x32_bf16 v[104:107], v[144:147], v[188:191], v[104:107]
	v_mfma_f32_16x16x32_bf16 v[108:111], v[152:155], v[188:191], v[108:111]
	v_mfma_f32_16x16x32_bf16 v[124:127], v[152:155], v[196:199], v[124:127]
	v_mfma_f32_16x16x32_bf16 v[72:75], v[148:151], v[176:179], v[72:75]
	v_mfma_f32_16x16x32_bf16 v[76:79], v[156:159], v[176:179], v[76:79]
	v_mfma_f32_16x16x32_bf16 v[92:95], v[156:159], v[184:187], v[92:95]
	v_mfma_f32_16x16x32_bf16 v[104:107], v[148:151], v[192:195], v[104:107]
	v_mfma_f32_16x16x32_bf16 v[108:111], v[156:159], v[192:195], v[108:111]
	v_mfma_f32_16x16x32_bf16 v[120:123], v[144:147], v[196:199], v[120:123]
	v_mfma_f32_16x16x32_bf16 v[124:127], v[156:159], v[200:203], v[124:127]
	v_mfma_f32_16x16x32_bf16 v[88:91], v[148:151], v[184:187], v[88:91]
	v_mfma_f32_16x16x32_bf16 v[120:123], v[148:151], v[200:203], v[120:123]
	s_barrier
	v_add_u32_e32 v253, 0x10000, v174
	ds_read_b128 v[128:131], v253
	ds_read_b128 v[132:135], v253 offset:1024
	ds_read_b128 v[136:139], v253 offset:2048
	ds_read_b128 v[140:143], v253 offset:3072
	v_add_u32_e32 v253, 0x14000, v174
	ds_read_b128 v[144:147], v253
	ds_read_b128 v[148:151], v253 offset:1024
	ds_read_b128 v[152:155], v253 offset:2048
	ds_read_b128 v[156:159], v253 offset:3072
	s_add_u32 s22, s22, 0x40180
	s_addc_u32 s23, s23, 0
	s_mov_b32 m0, s55
	ds_read_b128 v[168:171], v175
	ds_read_b128 v[176:179], v175 offset:1024
	ds_read_b128 v[180:183], v175 offset:2048
	ds_read_b128 v[184:187], v175 offset:3072
	ds_read_b128 v[188:191], v175 offset:4096
	ds_read_b128 v[192:195], v175 offset:5120
	ds_read_b128 v[196:199], v175 offset:6144
	ds_read_b128 v[200:203], v175 offset:7168
	global_load_lds_dwordx4 v160, s[22:23]
	s_mov_b32 m0, s13
	s_nop 0
	global_load_lds_dwordx4 v162, s[22:23]
	s_waitcnt vmcnt(8)
	s_waitcnt lgkmcnt(0)
	s_barrier
	s_waitcnt lgkmcnt(0)
	v_mfma_f32_16x16x32_bf16 v[0:3], v[128:131], v[168:171], v[0:3]
	v_mfma_f32_16x16x32_bf16 v[4:7], v[136:139], v[168:171], v[4:7]
	v_mfma_f32_16x16x32_bf16 v[16:19], v[128:131], v[180:183], v[16:19]
	v_mfma_f32_16x16x32_bf16 v[20:23], v[136:139], v[180:183], v[20:23]
	v_mfma_f32_16x16x32_bf16 v[32:35], v[128:131], v[188:191], v[32:35]
	v_mfma_f32_16x16x32_bf16 v[36:39], v[136:139], v[188:191], v[36:39]
	v_mfma_f32_16x16x32_bf16 v[48:51], v[128:131], v[196:199], v[48:51]
	v_mfma_f32_16x16x32_bf16 v[0:3], v[132:135], v[176:179], v[0:3]
	v_mfma_f32_16x16x32_bf16 v[4:7], v[140:143], v[176:179], v[4:7]
	v_mfma_f32_16x16x32_bf16 v[16:19], v[132:135], v[184:187], v[16:19]
	v_mfma_f32_16x16x32_bf16 v[20:23], v[140:143], v[184:187], v[20:23]
	v_mfma_f32_16x16x32_bf16 v[32:35], v[132:135], v[192:195], v[32:35]
	v_mfma_f32_16x16x32_bf16 v[36:39], v[140:143], v[192:195], v[36:39]
	v_mfma_f32_16x16x32_bf16 v[48:51], v[132:135], v[200:203], v[48:51]
	v_mfma_f32_16x16x32_bf16 v[52:55], v[136:139], v[196:199], v[52:55]
	v_mfma_f32_16x16x32_bf16 v[52:55], v[140:143], v[200:203], v[52:55]
	v_mfma_f32_16x16x32_bf16 v[8:11], v[144:147], v[168:171], v[8:11]
	v_mfma_f32_16x16x32_bf16 v[24:27], v[144:147], v[180:183], v[24:27]
	v_mfma_f32_16x16x32_bf16 v[28:31], v[152:155], v[180:183], v[28:31]
	v_mfma_f32_16x16x32_bf16 v[44:47], v[152:155], v[188:191], v[44:47]
	v_mfma_f32_16x16x32_bf16 v[56:59], v[144:147], v[196:199], v[56:59]
	v_mfma_f32_16x16x32_bf16 v[60:63], v[152:155], v[196:199], v[60:63]
	v_mfma_f32_16x16x32_bf16 v[8:11], v[148:151], v[176:179], v[8:11]
	v_mfma_f32_16x16x32_bf16 v[12:15], v[152:155], v[168:171], v[12:15]
	v_mfma_f32_16x16x32_bf16 v[24:27], v[148:151], v[184:187], v[24:27]
	v_mfma_f32_16x16x32_bf16 v[28:31], v[156:159], v[184:187], v[28:31]
	v_mfma_f32_16x16x32_bf16 v[40:43], v[144:147], v[188:191], v[40:43]
	v_mfma_f32_16x16x32_bf16 v[44:47], v[156:159], v[192:195], v[44:47]
	v_mfma_f32_16x16x32_bf16 v[56:59], v[148:151], v[200:203], v[56:59]
	v_mfma_f32_16x16x32_bf16 v[60:63], v[156:159], v[200:203], v[60:63]
	v_mfma_f32_16x16x32_bf16 v[12:15], v[156:159], v[176:179], v[12:15]
	v_mfma_f32_16x16x32_bf16 v[40:43], v[148:151], v[192:195], v[40:43]
	s_barrier
	s_mov_b32 m0, s53
	s_add_u32 s22, s26, 0x10000
	ds_read_b128 v[168:171], v175 offset:16384
	ds_read_b128 v[176:179], v175 offset:17408
	ds_read_b128 v[180:183], v175 offset:18432
	ds_read_b128 v[184:187], v175 offset:19456
	ds_read_b128 v[188:191], v175 offset:20480
	ds_read_b128 v[192:195], v175 offset:21504
	ds_read_b128 v[196:199], v175 offset:22528
	ds_read_b128 v[200:203], v175 offset:23552
	global_load_lds_dwordx4 v232, s[26:27]
	s_mov_b32 m0, s15
	s_addc_u32 s23, s27, 0
	global_load_lds_dwordx4 v164, s[26:27]
	s_mov_b32 m0, s21
	s_nop 0
	global_load_lds_dwordx4 v232, s[22:23]
	s_mov_b32 m0, s52
	s_nop 0
	global_load_lds_dwordx4 v164, s[22:23]
	s_mov_b32 m0, s39
	s_nop 0
	global_load_lds_dwordx4 v160, s[28:29]
	s_mov_b32 m0, s40
	s_nop 0
	global_load_lds_dwordx4 v162, s[28:29]
	s_waitcnt vmcnt(8)
	s_waitcnt lgkmcnt(0)
	s_barrier
	s_waitcnt lgkmcnt(0)
	v_mfma_f32_16x16x32_bf16 v[64:67], v[128:131], v[168:171], v[64:67]
	v_mfma_f32_16x16x32_bf16 v[64:67], v[132:135], v[176:179], v[64:67]
	v_mfma_f32_16x16x32_bf16 v[68:71], v[136:139], v[168:171], v[68:71]
	v_mfma_f32_16x16x32_bf16 v[68:71], v[140:143], v[176:179], v[68:71]
	v_mfma_f32_16x16x32_bf16 v[80:83], v[128:131], v[180:183], v[80:83]
	v_mfma_f32_16x16x32_bf16 v[80:83], v[132:135], v[184:187], v[80:83]
	v_mfma_f32_16x16x32_bf16 v[84:87], v[136:139], v[180:183], v[84:87]
	v_mfma_f32_16x16x32_bf16 v[84:87], v[140:143], v[184:187], v[84:87]
	v_mfma_f32_16x16x32_bf16 v[96:99], v[128:131], v[188:191], v[96:99]
	v_mfma_f32_16x16x32_bf16 v[112:115], v[128:131], v[196:199], v[112:115]
	v_mfma_f32_16x16x32_bf16 v[116:119], v[136:139], v[196:199], v[116:119]
	v_mfma_f32_16x16x32_bf16 v[96:99], v[132:135], v[192:195], v[96:99]
	v_mfma_f32_16x16x32_bf16 v[100:103], v[136:139], v[188:191], v[100:103]
	v_mfma_f32_16x16x32_bf16 v[112:115], v[132:135], v[200:203], v[112:115]
	v_mfma_f32_16x16x32_bf16 v[116:119], v[140:143], v[200:203], v[116:119]
	v_mfma_f32_16x16x32_bf16 v[100:103], v[140:143], v[192:195], v[100:103]
	v_mfma_f32_16x16x32_bf16 v[72:75], v[144:147], v[168:171], v[72:75]
	v_mfma_f32_16x16x32_bf16 v[72:75], v[148:151], v[176:179], v[72:75]
	v_mfma_f32_16x16x32_bf16 v[76:79], v[152:155], v[168:171], v[76:79]
	v_mfma_f32_16x16x32_bf16 v[76:79], v[156:159], v[176:179], v[76:79]
	v_mfma_f32_16x16x32_bf16 v[88:91], v[144:147], v[180:183], v[88:91]
	v_mfma_f32_16x16x32_bf16 v[88:91], v[148:151], v[184:187], v[88:91]
	v_mfma_f32_16x16x32_bf16 v[92:95], v[152:155], v[180:183], v[92:95]
	v_mfma_f32_16x16x32_bf16 v[92:95], v[156:159], v[184:187], v[92:95]
	v_mfma_f32_16x16x32_bf16 v[104:107], v[144:147], v[188:191], v[104:107]
	v_mfma_f32_16x16x32_bf16 v[104:107], v[148:151], v[192:195], v[104:107]
	v_mfma_f32_16x16x32_bf16 v[108:111], v[152:155], v[188:191], v[108:111]
	v_mfma_f32_16x16x32_bf16 v[108:111], v[156:159], v[192:195], v[108:111]
	v_mfma_f32_16x16x32_bf16 v[120:123], v[144:147], v[196:199], v[120:123]
	v_mfma_f32_16x16x32_bf16 v[120:123], v[148:151], v[200:203], v[120:123]
	v_mfma_f32_16x16x32_bf16 v[124:127], v[152:155], v[196:199], v[124:127]
	v_mfma_f32_16x16x32_bf16 v[124:127], v[156:159], v[200:203], v[124:127]
	s_barrier
	s_nop 4
	v_add_u32_e32 v253, 0x18000, v174
	ds_read_b128 v[128:131], v253
	ds_read_b128 v[132:135], v253 offset:1024
	ds_read_b128 v[136:139], v253 offset:2048
	ds_read_b128 v[140:143], v253 offset:3072
	v_add_u32_e32 v253, 0x1c000, v174
	ds_read_b128 v[144:147], v253
	ds_read_b128 v[148:151], v253 offset:1024
	ds_read_b128 v[152:155], v253 offset:2048
	ds_read_b128 v[156:159], v253 offset:3072
	s_add_u32 s22, s28, 0x40000
	s_addc_u32 s23, s29, 0
	s_mov_b32 m0, s41
	ds_read_b128 v[168:171], v175 offset:32768
	ds_read_b128 v[176:179], v175 offset:33792
	ds_read_b128 v[180:183], v175 offset:34816
	ds_read_b128 v[184:187], v175 offset:35840
	ds_read_b128 v[188:191], v175 offset:36864
	ds_read_b128 v[192:195], v175 offset:37888
	ds_read_b128 v[196:199], v175 offset:38912
	ds_read_b128 v[200:203], v175 offset:39936
	global_load_lds_dwordx4 v160, s[22:23]
	s_mov_b32 m0, s42
	s_nop 0
	global_load_lds_dwordx4 v162, s[22:23]
	s_waitcnt vmcnt(8)
	s_waitcnt lgkmcnt(0)
	s_barrier
	s_waitcnt lgkmcnt(0)
	v_mfma_f32_16x16x32_bf16 v[0:3], v[128:131], v[168:171], v[0:3]
	v_mfma_f32_16x16x32_bf16 v[0:3], v[132:135], v[176:179], v[0:3]
	v_mfma_f32_16x16x32_bf16 v[4:7], v[136:139], v[168:171], v[4:7]
	v_mfma_f32_16x16x32_bf16 v[4:7], v[140:143], v[176:179], v[4:7]
	v_mfma_f32_16x16x32_bf16 v[16:19], v[128:131], v[180:183], v[16:19]
	v_mfma_f32_16x16x32_bf16 v[16:19], v[132:135], v[184:187], v[16:19]
	v_mfma_f32_16x16x32_bf16 v[20:23], v[136:139], v[180:183], v[20:23]
	v_mfma_f32_16x16x32_bf16 v[20:23], v[140:143], v[184:187], v[20:23]
	v_mfma_f32_16x16x32_bf16 v[32:35], v[128:131], v[188:191], v[32:35]
	v_mfma_f32_16x16x32_bf16 v[32:35], v[132:135], v[192:195], v[32:35]
	v_mfma_f32_16x16x32_bf16 v[36:39], v[136:139], v[188:191], v[36:39]
	v_mfma_f32_16x16x32_bf16 v[36:39], v[140:143], v[192:195], v[36:39]
	v_mfma_f32_16x16x32_bf16 v[48:51], v[128:131], v[196:199], v[48:51]
	v_mfma_f32_16x16x32_bf16 v[48:51], v[132:135], v[200:203], v[48:51]
	v_mfma_f32_16x16x32_bf16 v[52:55], v[136:139], v[196:199], v[52:55]
	v_mfma_f32_16x16x32_bf16 v[52:55], v[140:143], v[200:203], v[52:55]
	v_mfma_f32_16x16x32_bf16 v[12:15], v[152:155], v[168:171], v[12:15]
	v_mfma_f32_16x16x32_bf16 v[12:15], v[156:159], v[176:179], v[12:15]
	v_mfma_f32_16x16x32_bf16 v[24:27], v[144:147], v[180:183], v[24:27]
	v_mfma_f32_16x16x32_bf16 v[24:27], v[148:151], v[184:187], v[24:27]
	v_mfma_f32_16x16x32_bf16 v[28:31], v[152:155], v[180:183], v[28:31]
	v_mfma_f32_16x16x32_bf16 v[8:11], v[144:147], v[168:171], v[8:11]
	v_mfma_f32_16x16x32_bf16 v[28:31], v[156:159], v[184:187], v[28:31]
	v_mfma_f32_16x16x32_bf16 v[40:43], v[144:147], v[188:191], v[40:43]
	v_mfma_f32_16x16x32_bf16 v[8:11], v[148:151], v[176:179], v[8:11]
	v_mfma_f32_16x16x32_bf16 v[40:43], v[148:151], v[192:195], v[40:43]
	v_mfma_f32_16x16x32_bf16 v[44:47], v[152:155], v[188:191], v[44:47]
	v_mfma_f32_16x16x32_bf16 v[44:47], v[156:159], v[192:195], v[44:47]
	v_mfma_f32_16x16x32_bf16 v[56:59], v[144:147], v[196:199], v[56:59]
	v_mfma_f32_16x16x32_bf16 v[56:59], v[148:151], v[200:203], v[56:59]
	v_mfma_f32_16x16x32_bf16 v[60:63], v[152:155], v[196:199], v[60:63]
	v_mfma_f32_16x16x32_bf16 v[60:63], v[156:159], v[200:203], v[60:63]
	s_barrier
	s_mov_b32 m0, s56
	s_add_u32 s68, s26, s94
	s_addc_u32 s69, s27, s95
	s_add_u32 s70, s26, s94
	s_addc_u32 s71, s27, s95
	s_add_u32 s22, s26, 0x10080
	s_nop 1
	ds_read_b128 v[168:171], v175 offset:49152
	ds_read_b128 v[176:179], v175 offset:50176
	ds_read_b128 v[180:183], v175 offset:51200
	ds_read_b128 v[184:187], v175 offset:52224
	ds_read_b128 v[188:191], v175 offset:53248
	ds_read_b128 v[192:195], v175 offset:54272
	ds_read_b128 v[196:199], v175 offset:55296
	ds_read_b128 v[200:203], v175 offset:56320
	global_load_lds_dwordx4 v232, s[68:69]
	s_mov_b32 m0, s54
	s_addc_u32 s23, s27, 0
	global_load_lds_dwordx4 v164, s[70:71]
	s_mov_b32 m0, s24
	s_nop 0
	global_load_lds_dwordx4 v232, s[22:23]
	s_mov_b32 m0, s25
	s_nop 0
	global_load_lds_dwordx4 v164, s[22:23]
	s_add_u32 s68, s28, s94
	s_addc_u32 s69, s29, s95
	s_mov_b32 m0, s47
	s_nop 0
	global_load_lds_dwordx4 v160, s[68:69]
	s_add_u32 s68, s28, s94
	s_addc_u32 s69, s29, s95
	s_mov_b32 m0, s48
	s_nop 0
	global_load_lds_dwordx4 v162, s[68:69]
	s_waitcnt vmcnt(8)
	s_waitcnt lgkmcnt(0)
	s_barrier
	s_waitcnt lgkmcnt(0)
	v_mfma_f32_16x16x32_bf16 v[64:67], v[128:131], v[168:171], v[64:67]
	v_mfma_f32_16x16x32_bf16 v[64:67], v[132:135], v[176:179], v[64:67]
	v_mfma_f32_16x16x32_bf16 v[68:71], v[136:139], v[168:171], v[68:71]
	v_mfma_f32_16x16x32_bf16 v[68:71], v[140:143], v[176:179], v[68:71]
	v_mfma_f32_16x16x32_bf16 v[80:83], v[128:131], v[180:183], v[80:83]
	v_mfma_f32_16x16x32_bf16 v[80:83], v[132:135], v[184:187], v[80:83]
	v_mfma_f32_16x16x32_bf16 v[84:87], v[136:139], v[180:183], v[84:87]
	v_mfma_f32_16x16x32_bf16 v[84:87], v[140:143], v[184:187], v[84:87]
	v_mfma_f32_16x16x32_bf16 v[96:99], v[128:131], v[188:191], v[96:99]
	v_mfma_f32_16x16x32_bf16 v[112:115], v[128:131], v[196:199], v[112:115]
	v_mfma_f32_16x16x32_bf16 v[96:99], v[132:135], v[192:195], v[96:99]
	v_mfma_f32_16x16x32_bf16 v[100:103], v[136:139], v[188:191], v[100:103]
	v_mfma_f32_16x16x32_bf16 v[112:115], v[132:135], v[200:203], v[112:115]
	v_mfma_f32_16x16x32_bf16 v[116:119], v[136:139], v[196:199], v[116:119]
	v_mfma_f32_16x16x32_bf16 v[100:103], v[140:143], v[192:195], v[100:103]
	v_mfma_f32_16x16x32_bf16 v[116:119], v[140:143], v[200:203], v[116:119]
	v_mfma_f32_16x16x32_bf16 v[72:75], v[144:147], v[168:171], v[72:75]
	v_mfma_f32_16x16x32_bf16 v[72:75], v[148:151], v[176:179], v[72:75]
	v_mfma_f32_16x16x32_bf16 v[76:79], v[152:155], v[168:171], v[76:79]
	v_mfma_f32_16x16x32_bf16 v[76:79], v[156:159], v[176:179], v[76:79]
	v_mfma_f32_16x16x32_bf16 v[88:91], v[144:147], v[180:183], v[88:91]
	v_mfma_f32_16x16x32_bf16 v[88:91], v[148:151], v[184:187], v[88:91]
	v_mfma_f32_16x16x32_bf16 v[92:95], v[152:155], v[180:183], v[92:95]
	v_mfma_f32_16x16x32_bf16 v[92:95], v[156:159], v[184:187], v[92:95]
	v_mfma_f32_16x16x32_bf16 v[104:107], v[144:147], v[188:191], v[104:107]
	v_mfma_f32_16x16x32_bf16 v[104:107], v[148:151], v[192:195], v[104:107]
	v_mfma_f32_16x16x32_bf16 v[108:111], v[152:155], v[188:191], v[108:111]
	v_mfma_f32_16x16x32_bf16 v[108:111], v[156:159], v[192:195], v[108:111]
	v_mfma_f32_16x16x32_bf16 v[120:123], v[144:147], v[196:199], v[120:123]
	v_mfma_f32_16x16x32_bf16 v[120:123], v[148:151], v[200:203], v[120:123]
	v_mfma_f32_16x16x32_bf16 v[124:127], v[152:155], v[196:199], v[124:127]
	v_mfma_f32_16x16x32_bf16 v[124:127], v[156:159], v[200:203], v[124:127]
	s_barrier
	s_andn2_b64 vcc, exec, s[10:11]
	s_cbranch_vccnz .LBB0_1020
	s_barrier

.LBB0_1163:
	s_ashr_i32 s23, s22, 31
	s_lshl_b64 s[24:25], s[22:23], 19
	s_add_u32 s24, s42, s24
	s_addc_u32 s25, s43, s25
	s_and_b64 s[26:27], s[4:5], exec
	s_cselect_b32 s23, s25, s35
	s_cselect_b32 s56, s24, s34
	s_ashr_i32 s21, s20, 31
	s_lshl_b64 s[26:27], s[20:21], 19
	s_add_u32 s26, s44, s26
	s_addc_u32 s27, s45, s27
	s_and_b64 s[36:37], s[4:5], exec
	s_cselect_b32 s21, s27, s31
	s_cselect_b32 s57, s26, s30
	s_add_u32 s58, s30, 0x100
	s_addc_u32 s59, s31, 0
	s_add_u32 s30, s34, 0x40080
	s_addc_u32 s31, s35, 0
	s_mov_b32 s60, -2
	s_waitcnt vmcnt(0)
	s_add_u32 s34, s30, 0xfffc0080
	s_addc_u32 s35, s31, -1
	s_add_i32 s61, 0, 0x10000
	s_cmp_eq_u32 s60, 12
	s_cselect_b32 s37, s23, s35
	s_cselect_b32 s36, s56, s34
	s_cselect_b32 s35, s21, s59
	s_cselect_b32 s34, s57, s58
	s_add_i32 s64, 0, 0x14000
	v_add_u32_e32 v140, s61, v174
	v_add_u32_e32 v166, s64, v174
	ds_read_b128 v[128:131], v140
	ds_read_b128 v[132:135], v140 offset:1024
	ds_read_b128 v[136:139], v140 offset:2048
	ds_read_b128 v[140:143], v140 offset:3072
	ds_read_b128 v[154:157], v166
	ds_read_b128 v[158:161], v166 offset:1024
	ds_read_b128 v[162:165], v166 offset:2048
	ds_read_b128 v[166:169], v166 offset:3072
	v_lshl_add_u64 v[204:205], s[30:31], 0, v[152:153]
	s_add_i32 m0, s29, 0xc000
	ds_read_b128 v[170:173], v175
	ds_read_b128 v[176:179], v175 offset:1024
	ds_read_b128 v[180:183], v175 offset:2048
	ds_read_b128 v[184:187], v175 offset:3072
	ds_read_b128 v[188:191], v175 offset:4096
	ds_read_b128 v[192:195], v175 offset:5120
	ds_read_b128 v[196:199], v175 offset:6144
	ds_read_b128 v[200:203], v175 offset:7168
	global_load_lds_dwordx4 v[204:205], off
	v_lshl_add_u64 v[204:205], s[30:31], 0, v[150:151]
	s_add_i32 m0, s29, 0xe000
	s_nop 0
	global_load_lds_dwordx4 v[204:205], off
	s_waitcnt vmcnt(8)
	s_waitcnt lgkmcnt(0)
	s_barrier
	s_waitcnt lgkmcnt(0)
	v_mfma_f32_16x16x32_bf16 v[124:127], v[128:131], v[170:173], 0
	v_mfma_f32_16x16x32_bf16 v[120:123], v[136:139], v[170:173], 0
	v_mfma_f32_16x16x32_bf16 v[108:111], v[128:131], v[180:183], 0
	v_mfma_f32_16x16x32_bf16 v[104:107], v[136:139], v[180:183], 0
	v_mfma_f32_16x16x32_bf16 v[92:95], v[128:131], v[188:191], 0
	v_mfma_f32_16x16x32_bf16 v[88:91], v[136:139], v[188:191], 0
	v_mfma_f32_16x16x32_bf16 v[80:83], v[128:131], v[196:199], 0
	v_mfma_f32_16x16x32_bf16 v[72:75], v[136:139], v[196:199], 0
	v_mfma_f32_16x16x32_bf16 v[124:127], v[132:135], v[176:179], v[124:127]
	v_mfma_f32_16x16x32_bf16 v[120:123], v[140:143], v[176:179], v[120:123]
	v_mfma_f32_16x16x32_bf16 v[108:111], v[132:135], v[184:187], v[108:111]
	v_mfma_f32_16x16x32_bf16 v[104:107], v[140:143], v[184:187], v[104:107]
	v_mfma_f32_16x16x32_bf16 v[92:95], v[132:135], v[192:195], v[92:95]
	v_mfma_f32_16x16x32_bf16 v[88:91], v[140:143], v[192:195], v[88:91]
	v_mfma_f32_16x16x32_bf16 v[80:83], v[132:135], v[200:203], v[80:83]
	v_mfma_f32_16x16x32_bf16 v[72:75], v[140:143], v[200:203], v[72:75]
	v_mfma_f32_16x16x32_bf16 v[116:119], v[154:157], v[170:173], 0
	v_mfma_f32_16x16x32_bf16 v[112:115], v[162:165], v[170:173], 0
	v_mfma_f32_16x16x32_bf16 v[100:103], v[154:157], v[180:183], 0
	v_mfma_f32_16x16x32_bf16 v[96:99], v[162:165], v[180:183], 0
	v_mfma_f32_16x16x32_bf16 v[84:87], v[154:157], v[188:191], 0
	v_mfma_f32_16x16x32_bf16 v[76:79], v[162:165], v[188:191], 0
	v_mfma_f32_16x16x32_bf16 v[68:71], v[154:157], v[196:199], 0
	v_mfma_f32_16x16x32_bf16 v[64:67], v[162:165], v[196:199], 0
	v_mfma_f32_16x16x32_bf16 v[116:119], v[158:161], v[176:179], v[116:119]
	v_mfma_f32_16x16x32_bf16 v[112:115], v[166:169], v[176:179], v[112:115]
	v_mfma_f32_16x16x32_bf16 v[100:103], v[158:161], v[184:187], v[100:103]
	v_mfma_f32_16x16x32_bf16 v[96:99], v[166:169], v[184:187], v[96:99]
	v_mfma_f32_16x16x32_bf16 v[84:87], v[158:161], v[192:195], v[84:87]
	v_mfma_f32_16x16x32_bf16 v[76:79], v[166:169], v[192:195], v[76:79]
	v_mfma_f32_16x16x32_bf16 v[68:71], v[158:161], v[200:203], v[68:71]
	v_mfma_f32_16x16x32_bf16 v[64:67], v[166:169], v[200:203], v[64:67]
	s_barrier
	s_add_i32 s61, s61, s41
	v_lshl_add_u64 v[204:205], s[34:35], 0, v[232:233]
	s_mov_b32 m0, s61
	ds_read_b128 v[170:173], v175 offset:16384
	ds_read_b128 v[176:179], v175 offset:17408
	ds_read_b128 v[180:183], v175 offset:18432
	ds_read_b128 v[184:187], v175 offset:19456
	ds_read_b128 v[188:191], v175 offset:20480
	ds_read_b128 v[192:195], v175 offset:21504
	ds_read_b128 v[196:199], v175 offset:22528
	ds_read_b128 v[200:203], v175 offset:23552
	global_load_lds_dwordx4 v[204:205], off
	s_add_i32 m0, s61, 0x2000
	s_add_u32 s62, s34, 0x40000
	v_lshl_add_u64 v[206:207], s[34:35], 0, v[148:149]
	s_addc_u32 s63, s35, 0
	s_add_i32 s61, s64, s41
	global_load_lds_dwordx4 v[206:207], off
	v_lshl_add_u64 v[208:209], s[62:63], 0, v[232:233]
	s_mov_b32 m0, s61
	v_lshl_add_u64 v[210:211], s[36:37], 0, v[146:147]
	global_load_lds_dwordx4 v[208:209], off
	v_lshl_add_u64 v[208:209], s[62:63], 0, v[148:149]
	s_add_i32 m0, s61, 0x2000
	s_nop 0
	global_load_lds_dwordx4 v[208:209], off
	v_lshl_add_u64 v[208:209], s[36:37], 0, v[144:145]
	s_waitcnt vmcnt(6)
	s_waitcnt lgkmcnt(0)
	s_barrier
	s_waitcnt lgkmcnt(0)
	v_mfma_f32_16x16x32_bf16 v[60:63], v[128:131], v[170:173], 0
	v_mfma_f32_16x16x32_bf16 v[56:59], v[136:139], v[170:173], 0
	v_mfma_f32_16x16x32_bf16 v[48:51], v[128:131], v[180:183], 0
	v_mfma_f32_16x16x32_bf16 v[40:43], v[136:139], v[180:183], 0
	v_mfma_f32_16x16x32_bf16 v[28:31], v[128:131], v[188:191], 0
	v_mfma_f32_16x16x32_bf16 v[24:27], v[136:139], v[188:191], 0
	v_mfma_f32_16x16x32_bf16 v[16:19], v[128:131], v[196:199], 0
	v_mfma_f32_16x16x32_bf16 v[8:11], v[136:139], v[196:199], 0
	v_mfma_f32_16x16x32_bf16 v[60:63], v[132:135], v[176:179], v[60:63]
	v_mfma_f32_16x16x32_bf16 v[56:59], v[140:143], v[176:179], v[56:59]
	v_mfma_f32_16x16x32_bf16 v[48:51], v[132:135], v[184:187], v[48:51]
	v_mfma_f32_16x16x32_bf16 v[40:43], v[140:143], v[184:187], v[40:43]
	v_mfma_f32_16x16x32_bf16 v[28:31], v[132:135], v[192:195], v[28:31]
	v_mfma_f32_16x16x32_bf16 v[24:27], v[140:143], v[192:195], v[24:27]
	v_mfma_f32_16x16x32_bf16 v[16:19], v[132:135], v[200:203], v[16:19]
	v_mfma_f32_16x16x32_bf16 v[8:11], v[140:143], v[200:203], v[8:11]
	v_mfma_f32_16x16x32_bf16 v[52:55], v[154:157], v[170:173], 0
	v_mfma_f32_16x16x32_bf16 v[44:47], v[162:165], v[170:173], 0
	v_mfma_f32_16x16x32_bf16 v[36:39], v[154:157], v[180:183], 0
	v_mfma_f32_16x16x32_bf16 v[32:35], v[162:165], v[180:183], 0
	v_mfma_f32_16x16x32_bf16 v[20:23], v[154:157], v[188:191], 0
	v_mfma_f32_16x16x32_bf16 v[12:15], v[162:165], v[188:191], 0
	v_mfma_f32_16x16x32_bf16 v[4:7], v[154:157], v[196:199], 0
	v_mfma_f32_16x16x32_bf16 v[0:3], v[162:165], v[196:199], 0
	v_mfma_f32_16x16x32_bf16 v[52:55], v[158:161], v[176:179], v[52:55]
	v_mfma_f32_16x16x32_bf16 v[44:47], v[166:169], v[176:179], v[44:47]
	v_mfma_f32_16x16x32_bf16 v[36:39], v[158:161], v[184:187], v[36:39]
	v_mfma_f32_16x16x32_bf16 v[32:35], v[166:169], v[184:187], v[32:35]
	v_mfma_f32_16x16x32_bf16 v[20:23], v[158:161], v[192:195], v[20:23]
	v_mfma_f32_16x16x32_bf16 v[12:15], v[166:169], v[192:195], v[12:15]
	v_mfma_f32_16x16x32_bf16 v[4:7], v[158:161], v[200:203], v[4:7]
	v_mfma_f32_16x16x32_bf16 v[0:3], v[166:169], v[200:203], v[0:3]
	s_barrier
	s_branch .Lzmid_3
.LBB0_1164:
	s_add_u32 s34, s30, 0xfffc0080
	s_addc_u32 s35, s31, -1
	s_add_i32 s61, 0, 0x10000
	s_cmp_eq_u32 s60, 12
	s_cselect_b32 s37, s23, s35
	s_cselect_b32 s36, s56, s34
	s_cselect_b32 s35, s21, s59
	s_cselect_b32 s34, s57, s58
	s_add_i32 s64, 0, 0x14000
	v_add_u32_e32 v140, s61, v174
	v_add_u32_e32 v166, s64, v174
	ds_read_b128 v[128:131], v140
	ds_read_b128 v[132:135], v140 offset:1024
	ds_read_b128 v[136:139], v140 offset:2048
	ds_read_b128 v[140:143], v140 offset:3072
	ds_read_b128 v[154:157], v166
	ds_read_b128 v[158:161], v166 offset:1024
	ds_read_b128 v[162:165], v166 offset:2048
	ds_read_b128 v[166:169], v166 offset:3072
	v_lshl_add_u64 v[204:205], s[30:31], 0, v[152:153]
	s_add_i32 m0, s29, 0xc000
	ds_read_b128 v[170:173], v175
	ds_read_b128 v[176:179], v175 offset:1024
	ds_read_b128 v[180:183], v175 offset:2048
	ds_read_b128 v[184:187], v175 offset:3072
	ds_read_b128 v[188:191], v175 offset:4096
	ds_read_b128 v[192:195], v175 offset:5120
	ds_read_b128 v[196:199], v175 offset:6144
	ds_read_b128 v[200:203], v175 offset:7168
	global_load_lds_dwordx4 v[204:205], off
	v_lshl_add_u64 v[204:205], s[30:31], 0, v[150:151]
	s_add_i32 m0, s29, 0xe000
	s_nop 0
	global_load_lds_dwordx4 v[204:205], off
	s_waitcnt vmcnt(8)
	s_waitcnt lgkmcnt(0)
	s_barrier
	s_waitcnt lgkmcnt(0)
	v_mfma_f32_16x16x32_bf16 v[124:127], v[128:131], v[170:173], v[124:127]
	v_mfma_f32_16x16x32_bf16 v[120:123], v[136:139], v[170:173], v[120:123]
	v_mfma_f32_16x16x32_bf16 v[108:111], v[128:131], v[180:183], v[108:111]
	v_mfma_f32_16x16x32_bf16 v[104:107], v[136:139], v[180:183], v[104:107]
	v_mfma_f32_16x16x32_bf16 v[92:95], v[128:131], v[188:191], v[92:95]
	v_mfma_f32_16x16x32_bf16 v[88:91], v[136:139], v[188:191], v[88:91]
	v_mfma_f32_16x16x32_bf16 v[80:83], v[128:131], v[196:199], v[80:83]
	v_mfma_f32_16x16x32_bf16 v[72:75], v[136:139], v[196:199], v[72:75]
	v_mfma_f32_16x16x32_bf16 v[124:127], v[132:135], v[176:179], v[124:127]
	v_mfma_f32_16x16x32_bf16 v[120:123], v[140:143], v[176:179], v[120:123]
	v_mfma_f32_16x16x32_bf16 v[108:111], v[132:135], v[184:187], v[108:111]
	v_mfma_f32_16x16x32_bf16 v[104:107], v[140:143], v[184:187], v[104:107]
	v_mfma_f32_16x16x32_bf16 v[92:95], v[132:135], v[192:195], v[92:95]
	v_mfma_f32_16x16x32_bf16 v[88:91], v[140:143], v[192:195], v[88:91]
	v_mfma_f32_16x16x32_bf16 v[80:83], v[132:135], v[200:203], v[80:83]
	v_mfma_f32_16x16x32_bf16 v[72:75], v[140:143], v[200:203], v[72:75]
	v_mfma_f32_16x16x32_bf16 v[116:119], v[154:157], v[170:173], v[116:119]
	v_mfma_f32_16x16x32_bf16 v[112:115], v[162:165], v[170:173], v[112:115]
	v_mfma_f32_16x16x32_bf16 v[100:103], v[154:157], v[180:183], v[100:103]
	v_mfma_f32_16x16x32_bf16 v[96:99], v[162:165], v[180:183], v[96:99]
	v_mfma_f32_16x16x32_bf16 v[84:87], v[154:157], v[188:191], v[84:87]
	v_mfma_f32_16x16x32_bf16 v[76:79], v[162:165], v[188:191], v[76:79]
	v_mfma_f32_16x16x32_bf16 v[68:71], v[154:157], v[196:199], v[68:71]
	v_mfma_f32_16x16x32_bf16 v[64:67], v[162:165], v[196:199], v[64:67]
	v_mfma_f32_16x16x32_bf16 v[116:119], v[158:161], v[176:179], v[116:119]
	v_mfma_f32_16x16x32_bf16 v[112:115], v[166:169], v[176:179], v[112:115]
	v_mfma_f32_16x16x32_bf16 v[100:103], v[158:161], v[184:187], v[100:103]
	v_mfma_f32_16x16x32_bf16 v[96:99], v[166:169], v[184:187], v[96:99]
	v_mfma_f32_16x16x32_bf16 v[84:87], v[158:161], v[192:195], v[84:87]
	v_mfma_f32_16x16x32_bf16 v[76:79], v[166:169], v[192:195], v[76:79]
	v_mfma_f32_16x16x32_bf16 v[68:71], v[158:161], v[200:203], v[68:71]
	v_mfma_f32_16x16x32_bf16 v[64:67], v[166:169], v[200:203], v[64:67]
	s_barrier
	s_add_i32 s61, s61, s41
	v_lshl_add_u64 v[204:205], s[34:35], 0, v[232:233]
	s_mov_b32 m0, s61
	ds_read_b128 v[170:173], v175 offset:16384
	ds_read_b128 v[176:179], v175 offset:17408
	ds_read_b128 v[180:183], v175 offset:18432
	ds_read_b128 v[184:187], v175 offset:19456
	ds_read_b128 v[188:191], v175 offset:20480
	ds_read_b128 v[192:195], v175 offset:21504
	ds_read_b128 v[196:199], v175 offset:22528
	ds_read_b128 v[200:203], v175 offset:23552
	global_load_lds_dwordx4 v[204:205], off
	s_add_i32 m0, s61, 0x2000
	s_add_u32 s62, s34, 0x40000
	v_lshl_add_u64 v[206:207], s[34:35], 0, v[148:149]
	s_addc_u32 s63, s35, 0
	s_add_i32 s61, s64, s41
	global_load_lds_dwordx4 v[206:207], off
	v_lshl_add_u64 v[208:209], s[62:63], 0, v[232:233]
	s_mov_b32 m0, s61
	v_lshl_add_u64 v[210:211], s[36:37], 0, v[146:147]
	global_load_lds_dwordx4 v[208:209], off
	v_lshl_add_u64 v[208:209], s[62:63], 0, v[148:149]
	s_add_i32 m0, s61, 0x2000
	s_nop 0
	global_load_lds_dwordx4 v[208:209], off
	v_lshl_add_u64 v[208:209], s[36:37], 0, v[144:145]
	s_waitcnt vmcnt(6)
	s_waitcnt lgkmcnt(0)
	s_barrier
	s_waitcnt lgkmcnt(0)
	v_mfma_f32_16x16x32_bf16 v[60:63], v[128:131], v[170:173], v[60:63]
	v_mfma_f32_16x16x32_bf16 v[56:59], v[136:139], v[170:173], v[56:59]
	v_mfma_f32_16x16x32_bf16 v[48:51], v[128:131], v[180:183], v[48:51]
	v_mfma_f32_16x16x32_bf16 v[40:43], v[136:139], v[180:183], v[40:43]
	v_mfma_f32_16x16x32_bf16 v[28:31], v[128:131], v[188:191], v[28:31]
	v_mfma_f32_16x16x32_bf16 v[24:27], v[136:139], v[188:191], v[24:27]
	v_mfma_f32_16x16x32_bf16 v[16:19], v[128:131], v[196:199], v[16:19]
	v_mfma_f32_16x16x32_bf16 v[8:11], v[136:139], v[196:199], v[8:11]
	v_mfma_f32_16x16x32_bf16 v[60:63], v[132:135], v[176:179], v[60:63]
	v_mfma_f32_16x16x32_bf16 v[56:59], v[140:143], v[176:179], v[56:59]
	v_mfma_f32_16x16x32_bf16 v[48:51], v[132:135], v[184:187], v[48:51]
	v_mfma_f32_16x16x32_bf16 v[40:43], v[140:143], v[184:187], v[40:43]
	v_mfma_f32_16x16x32_bf16 v[28:31], v[132:135], v[192:195], v[28:31]
	v_mfma_f32_16x16x32_bf16 v[24:27], v[140:143], v[192:195], v[24:27]
	v_mfma_f32_16x16x32_bf16 v[16:19], v[132:135], v[200:203], v[16:19]
	v_mfma_f32_16x16x32_bf16 v[8:11], v[140:143], v[200:203], v[8:11]
	v_mfma_f32_16x16x32_bf16 v[52:55], v[154:157], v[170:173], v[52:55]
	v_mfma_f32_16x16x32_bf16 v[44:47], v[162:165], v[170:173], v[44:47]
	v_mfma_f32_16x16x32_bf16 v[36:39], v[154:157], v[180:183], v[36:39]
	v_mfma_f32_16x16x32_bf16 v[32:35], v[162:165], v[180:183], v[32:35]
	v_mfma_f32_16x16x32_bf16 v[20:23], v[154:157], v[188:191], v[20:23]
	v_mfma_f32_16x16x32_bf16 v[12:15], v[162:165], v[188:191], v[12:15]
	v_mfma_f32_16x16x32_bf16 v[4:7], v[154:157], v[196:199], v[4:7]
	v_mfma_f32_16x16x32_bf16 v[0:3], v[162:165], v[196:199], v[0:3]
	v_mfma_f32_16x16x32_bf16 v[52:55], v[158:161], v[176:179], v[52:55]
	v_mfma_f32_16x16x32_bf16 v[44:47], v[166:169], v[176:179], v[44:47]
	v_mfma_f32_16x16x32_bf16 v[36:39], v[158:161], v[184:187], v[36:39]
	v_mfma_f32_16x16x32_bf16 v[32:35], v[166:169], v[184:187], v[32:35]
	v_mfma_f32_16x16x32_bf16 v[20:23], v[158:161], v[192:195], v[20:23]
	v_mfma_f32_16x16x32_bf16 v[12:15], v[166:169], v[192:195], v[12:15]
	v_mfma_f32_16x16x32_bf16 v[4:7], v[158:161], v[200:203], v[4:7]
	v_mfma_f32_16x16x32_bf16 v[0:3], v[166:169], v[200:203], v[0:3]
	s_barrier
.Lzmid_3:
	s_add_i32 s61, 0, 0x18000
	s_add_i32 s62, 0, 0x1c000
	v_add_u32_e32 v140, s61, v174
	v_add_u32_e32 v166, s62, v174
	ds_read_b128 v[128:131], v140
	ds_read_b128 v[132:135], v140 offset:1024
	ds_read_b128 v[136:139], v140 offset:2048
	ds_read_b128 v[140:143], v140 offset:3072
	ds_read_b128 v[154:157], v166
	ds_read_b128 v[158:161], v166 offset:1024
	ds_read_b128 v[162:165], v166 offset:2048
	ds_read_b128 v[166:169], v166 offset:3072
	s_add_u32 s36, s36, 0x40000
	s_addc_u32 s37, s37, 0
	s_mov_b32 m0, s29
	s_nop 0
	global_load_lds_dwordx4 v[208:209], off
	s_mov_b32 m0, s46
	s_nop 0
	global_load_lds_dwordx4 v[210:211], off
	s_mov_b32 m0, s47
	v_lshl_add_u64 v[212:213], s[36:37], 0, v[144:145]
	ds_read_b128 v[170:173], v175 offset:32768
	ds_read_b128 v[176:179], v175 offset:33792
	ds_read_b128 v[180:183], v175 offset:34816
	ds_read_b128 v[184:187], v175 offset:35840
	ds_read_b128 v[188:191], v175 offset:36864
	ds_read_b128 v[192:195], v175 offset:37888
	ds_read_b128 v[196:199], v175 offset:38912
	ds_read_b128 v[200:203], v175 offset:39936
	global_load_lds_dwordx4 v[212:213], off
	v_lshl_add_u64 v[212:213], s[36:37], 0, v[146:147]
	s_mov_b32 m0, s48
	s_nop 0
	global_load_lds_dwordx4 v[212:213], off
	s_waitcnt vmcnt(8)
	s_waitcnt lgkmcnt(0)
	s_barrier
	s_waitcnt lgkmcnt(0)
	v_mfma_f32_16x16x32_bf16 v[124:127], v[128:131], v[170:173], v[124:127]
	v_mfma_f32_16x16x32_bf16 v[120:123], v[136:139], v[170:173], v[120:123]
	v_mfma_f32_16x16x32_bf16 v[108:111], v[128:131], v[180:183], v[108:111]
	v_mfma_f32_16x16x32_bf16 v[104:107], v[136:139], v[180:183], v[104:107]
	v_mfma_f32_16x16x32_bf16 v[92:95], v[128:131], v[188:191], v[92:95]
	v_mfma_f32_16x16x32_bf16 v[88:91], v[136:139], v[188:191], v[88:91]
	v_mfma_f32_16x16x32_bf16 v[80:83], v[128:131], v[196:199], v[80:83]
	v_mfma_f32_16x16x32_bf16 v[72:75], v[136:139], v[196:199], v[72:75]
	v_mfma_f32_16x16x32_bf16 v[124:127], v[132:135], v[176:179], v[124:127]
	v_mfma_f32_16x16x32_bf16 v[120:123], v[140:143], v[176:179], v[120:123]
	v_mfma_f32_16x16x32_bf16 v[108:111], v[132:135], v[184:187], v[108:111]
	v_mfma_f32_16x16x32_bf16 v[104:107], v[140:143], v[184:187], v[104:107]
	v_mfma_f32_16x16x32_bf16 v[92:95], v[132:135], v[192:195], v[92:95]
	v_mfma_f32_16x16x32_bf16 v[88:91], v[140:143], v[192:195], v[88:91]
	v_mfma_f32_16x16x32_bf16 v[80:83], v[132:135], v[200:203], v[80:83]
	v_mfma_f32_16x16x32_bf16 v[72:75], v[140:143], v[200:203], v[72:75]
	v_mfma_f32_16x16x32_bf16 v[116:119], v[154:157], v[170:173], v[116:119]
	v_mfma_f32_16x16x32_bf16 v[112:115], v[162:165], v[170:173], v[112:115]
	v_mfma_f32_16x16x32_bf16 v[100:103], v[154:157], v[180:183], v[100:103]
	v_mfma_f32_16x16x32_bf16 v[96:99], v[162:165], v[180:183], v[96:99]
	v_mfma_f32_16x16x32_bf16 v[84:87], v[154:157], v[188:191], v[84:87]
	v_mfma_f32_16x16x32_bf16 v[76:79], v[162:165], v[188:191], v[76:79]
	v_mfma_f32_16x16x32_bf16 v[68:71], v[154:157], v[196:199], v[68:71]
	v_mfma_f32_16x16x32_bf16 v[64:67], v[162:165], v[196:199], v[64:67]
	v_mfma_f32_16x16x32_bf16 v[116:119], v[158:161], v[176:179], v[116:119]
	v_mfma_f32_16x16x32_bf16 v[112:115], v[166:169], v[176:179], v[112:115]
	v_mfma_f32_16x16x32_bf16 v[100:103], v[158:161], v[184:187], v[100:103]
	v_mfma_f32_16x16x32_bf16 v[96:99], v[166:169], v[184:187], v[96:99]
	v_mfma_f32_16x16x32_bf16 v[84:87], v[158:161], v[192:195], v[84:87]
	v_mfma_f32_16x16x32_bf16 v[76:79], v[166:169], v[192:195], v[76:79]
	v_mfma_f32_16x16x32_bf16 v[68:71], v[158:161], v[200:203], v[68:71]
	v_mfma_f32_16x16x32_bf16 v[64:67], v[166:169], v[200:203], v[64:67]
	s_barrier
	s_add_i32 s36, s61, s41
	v_lshl_add_u64 v[204:205], v[204:205], 0, s[94:95]
	s_mov_b32 m0, s36
	ds_read_b128 v[170:173], v175 offset:49152
	ds_read_b128 v[176:179], v175 offset:50176
	ds_read_b128 v[180:183], v175 offset:51200
	ds_read_b128 v[184:187], v175 offset:52224
	ds_read_b128 v[188:191], v175 offset:53248
	ds_read_b128 v[192:195], v175 offset:54272
	ds_read_b128 v[196:199], v175 offset:55296
	ds_read_b128 v[200:203], v175 offset:56320
	global_load_lds_dwordx4 v[204:205], off
	s_add_i32 m0, s36, 0x2000
	s_add_u32 s34, s34, 0x40080
	v_lshl_add_u64 v[204:205], v[206:207], 0, s[94:95]
	s_addc_u32 s35, s35, 0
	s_add_i32 s36, s62, s41
	global_load_lds_dwordx4 v[204:205], off
	v_lshl_add_u64 v[204:205], s[34:35], 0, v[232:233]
	s_mov_b32 m0, s36
	s_nop 0
	global_load_lds_dwordx4 v[204:205], off
	v_lshl_add_u64 v[204:205], s[34:35], 0, v[148:149]
	s_add_i32 m0, s36, 0x2000
	s_nop 0
	global_load_lds_dwordx4 v[204:205], off
	v_lshl_add_u64 v[204:205], v[208:209], 0, s[94:95]
	s_mov_b32 m0, s51
	s_nop 0
	global_load_lds_dwordx4 v[204:205], off
	v_lshl_add_u64 v[204:205], v[210:211], 0, s[94:95]
	s_mov_b32 m0, s52
	s_nop 0
	global_load_lds_dwordx4 v[204:205], off
	s_waitcnt vmcnt(8)
	s_waitcnt lgkmcnt(0)
	s_barrier
	s_waitcnt lgkmcnt(0)
	v_mfma_f32_16x16x32_bf16 v[60:63], v[128:131], v[170:173], v[60:63]
	v_mfma_f32_16x16x32_bf16 v[56:59], v[136:139], v[170:173], v[56:59]
	v_mfma_f32_16x16x32_bf16 v[48:51], v[128:131], v[180:183], v[48:51]
	v_mfma_f32_16x16x32_bf16 v[40:43], v[136:139], v[180:183], v[40:43]
	v_mfma_f32_16x16x32_bf16 v[28:31], v[128:131], v[188:191], v[28:31]
	v_mfma_f32_16x16x32_bf16 v[24:27], v[136:139], v[188:191], v[24:27]
	v_mfma_f32_16x16x32_bf16 v[16:19], v[128:131], v[196:199], v[16:19]
	v_mfma_f32_16x16x32_bf16 v[8:11], v[136:139], v[196:199], v[8:11]
	v_mfma_f32_16x16x32_bf16 v[60:63], v[132:135], v[176:179], v[60:63]
	v_mfma_f32_16x16x32_bf16 v[56:59], v[140:143], v[176:179], v[56:59]
	v_mfma_f32_16x16x32_bf16 v[48:51], v[132:135], v[184:187], v[48:51]
	v_mfma_f32_16x16x32_bf16 v[40:43], v[140:143], v[184:187], v[40:43]
	v_mfma_f32_16x16x32_bf16 v[28:31], v[132:135], v[192:195], v[28:31]
	v_mfma_f32_16x16x32_bf16 v[24:27], v[140:143], v[192:195], v[24:27]
	v_mfma_f32_16x16x32_bf16 v[16:19], v[132:135], v[200:203], v[16:19]
	v_mfma_f32_16x16x32_bf16 v[8:11], v[140:143], v[200:203], v[8:11]
	v_mfma_f32_16x16x32_bf16 v[52:55], v[154:157], v[170:173], v[52:55]
	v_mfma_f32_16x16x32_bf16 v[44:47], v[162:165], v[170:173], v[44:47]
	v_mfma_f32_16x16x32_bf16 v[36:39], v[154:157], v[180:183], v[36:39]
	v_mfma_f32_16x16x32_bf16 v[32:35], v[162:165], v[180:183], v[32:35]
	v_mfma_f32_16x16x32_bf16 v[20:23], v[154:157], v[188:191], v[20:23]
	v_mfma_f32_16x16x32_bf16 v[12:15], v[162:165], v[188:191], v[12:15]
	v_mfma_f32_16x16x32_bf16 v[4:7], v[154:157], v[196:199], v[4:7]
	v_mfma_f32_16x16x32_bf16 v[0:3], v[162:165], v[196:199], v[0:3]
	v_mfma_f32_16x16x32_bf16 v[52:55], v[158:161], v[176:179], v[52:55]
	v_mfma_f32_16x16x32_bf16 v[44:47], v[166:169], v[176:179], v[44:47]
	v_mfma_f32_16x16x32_bf16 v[36:39], v[158:161], v[184:187], v[36:39]
	v_mfma_f32_16x16x32_bf16 v[32:35], v[166:169], v[184:187], v[32:35]
	v_mfma_f32_16x16x32_bf16 v[20:23], v[158:161], v[192:195], v[20:23]
	v_mfma_f32_16x16x32_bf16 v[12:15], v[166:169], v[192:195], v[12:15]
	v_mfma_f32_16x16x32_bf16 v[4:7], v[158:161], v[200:203], v[4:7]
	v_mfma_f32_16x16x32_bf16 v[0:3], v[166:169], v[200:203], v[0:3]
	s_barrier
	s_add_i32 s60, s60, 2
	s_add_u32 s58, s58, 0x100
	s_addc_u32 s59, s59, 0
	s_add_u32 s30, s30, 0x100
	s_addc_u32 s31, s31, 0
	s_cmp_gt_u32 s60, 13
	s_cbranch_scc0 .LBB0_1164
	s_and_b64 vcc, exec, s[18:19]
	s_cbranch_vccz .LBB0_1167
	s_barrier

.LBB0_1306:
	s_ashr_i32 s17, s16, 31
	s_lshl_b64 s[18:19], s[16:17], 19
	s_add_u32 s18, s34, s18
	s_addc_u32 s19, s35, s19
	s_and_b64 s[20:21], s[4:5], exec
	s_cselect_b32 s7, s19, s27
	s_cselect_b32 s17, s18, s26
	s_ashr_i32 s15, s14, 31
	s_lshl_b64 s[20:21], s[14:15], 19
	s_add_u32 s20, s36, s20
	s_addc_u32 s21, s37, s21
	s_and_b64 s[28:29], s[4:5], exec
	s_cselect_b32 s15, s21, s25
	s_cselect_b32 s23, s20, s24
	s_add_u32 s50, s24, 0x100
	s_addc_u32 s51, s25, 0
	s_add_u32 s24, s26, 0x40080
	s_addc_u32 s25, s27, 0
	s_mov_b32 s52, -2
	s_add_u32 s26, s24, 0xfffc0080
	s_addc_u32 s27, s25, -1
	s_add_i32 s53, 0, 0x10000
	s_cmp_eq_u32 s52, 12
	s_cselect_b32 s29, s7, s27
	s_cselect_b32 s28, s17, s26
	v_add_u32_e32 v142, s53, v144
	s_cselect_b32 s27, s15, s51
	s_cselect_b32 s26, s23, s50
	s_add_i32 s56, 0, 0x14000
	ds_read_b128 v[138:141], v142
	ds_read_b128 v[146:149], v142 offset:1024
	ds_read_b128 v[150:153], v142 offset:2048
	ds_read_b128 v[154:157], v142 offset:3072
	v_add_u32_e32 v142, s56, v144
	ds_read_b128 v[158:161], v142
	ds_read_b128 v[162:165], v142 offset:1024
	ds_read_b128 v[166:169], v142 offset:2048
	ds_read_b128 v[170:173], v142 offset:3072
	v_lshl_add_u64 v[142:143], s[24:25], 0, v[136:137]
	s_add_i32 m0, s39, 0xc000
	ds_read_b128 v[174:177], v145
	ds_read_b128 v[178:181], v145 offset:1024
	ds_read_b128 v[182:185], v145 offset:2048
	ds_read_b128 v[186:189], v145 offset:3072
	ds_read_b128 v[190:193], v145 offset:4096
	ds_read_b128 v[194:197], v145 offset:5120
	ds_read_b128 v[198:201], v145 offset:6144
	ds_read_b128 v[202:205], v145 offset:7168
	global_load_lds_dwordx4 v[142:143], off
	v_lshl_add_u64 v[142:143], s[24:25], 0, v[134:135]
	s_add_i32 m0, s39, 0xe000
	s_nop 0
	global_load_lds_dwordx4 v[142:143], off
	s_waitcnt vmcnt(8)
	s_waitcnt lgkmcnt(0)
	s_barrier
	s_waitcnt lgkmcnt(0)
	v_mfma_f32_16x16x32_bf16 v[124:127], v[138:141], v[174:177], 0
	v_mfma_f32_16x16x32_bf16 v[120:123], v[150:153], v[174:177], 0
	v_mfma_f32_16x16x32_bf16 v[108:111], v[138:141], v[182:185], 0
	v_mfma_f32_16x16x32_bf16 v[104:107], v[150:153], v[182:185], 0
	v_mfma_f32_16x16x32_bf16 v[92:95], v[138:141], v[190:193], 0
	v_mfma_f32_16x16x32_bf16 v[88:91], v[150:153], v[190:193], 0
	v_mfma_f32_16x16x32_bf16 v[76:79], v[138:141], v[198:201], 0
	v_mfma_f32_16x16x32_bf16 v[72:75], v[150:153], v[198:201], 0
	v_mfma_f32_16x16x32_bf16 v[124:127], v[146:149], v[178:181], v[124:127]
	v_mfma_f32_16x16x32_bf16 v[120:123], v[154:157], v[178:181], v[120:123]
	v_mfma_f32_16x16x32_bf16 v[108:111], v[146:149], v[186:189], v[108:111]
	v_mfma_f32_16x16x32_bf16 v[104:107], v[154:157], v[186:189], v[104:107]
	v_mfma_f32_16x16x32_bf16 v[92:95], v[146:149], v[194:197], v[92:95]
	v_mfma_f32_16x16x32_bf16 v[88:91], v[154:157], v[194:197], v[88:91]
	v_mfma_f32_16x16x32_bf16 v[76:79], v[146:149], v[202:205], v[76:79]
	v_mfma_f32_16x16x32_bf16 v[72:75], v[154:157], v[202:205], v[72:75]
	v_mfma_f32_16x16x32_bf16 v[116:119], v[158:161], v[174:177], 0
	v_mfma_f32_16x16x32_bf16 v[112:115], v[166:169], v[174:177], 0
	v_mfma_f32_16x16x32_bf16 v[100:103], v[158:161], v[182:185], 0
	v_mfma_f32_16x16x32_bf16 v[96:99], v[166:169], v[182:185], 0
	v_mfma_f32_16x16x32_bf16 v[84:87], v[158:161], v[190:193], 0
	v_mfma_f32_16x16x32_bf16 v[80:83], v[166:169], v[190:193], 0
	v_mfma_f32_16x16x32_bf16 v[68:71], v[158:161], v[198:201], 0
	v_mfma_f32_16x16x32_bf16 v[64:67], v[166:169], v[198:201], 0
	v_mfma_f32_16x16x32_bf16 v[116:119], v[162:165], v[178:181], v[116:119]
	v_mfma_f32_16x16x32_bf16 v[112:115], v[170:173], v[178:181], v[112:115]
	v_mfma_f32_16x16x32_bf16 v[100:103], v[162:165], v[186:189], v[100:103]
	v_mfma_f32_16x16x32_bf16 v[96:99], v[170:173], v[186:189], v[96:99]
	v_mfma_f32_16x16x32_bf16 v[84:87], v[162:165], v[194:197], v[84:87]
	v_mfma_f32_16x16x32_bf16 v[80:83], v[170:173], v[194:197], v[80:83]
	v_mfma_f32_16x16x32_bf16 v[68:71], v[162:165], v[202:205], v[68:71]
	v_mfma_f32_16x16x32_bf16 v[64:67], v[170:173], v[202:205], v[64:67]
	s_barrier
	s_add_i32 s53, s53, s38
	v_lshl_add_u64 v[142:143], s[26:27], 0, v[232:233]
	s_mov_b32 m0, s53
	ds_read_b128 v[174:177], v145 offset:16384
	ds_read_b128 v[178:181], v145 offset:17408
	ds_read_b128 v[182:185], v145 offset:18432
	ds_read_b128 v[186:189], v145 offset:19456
	ds_read_b128 v[190:193], v145 offset:20480
	ds_read_b128 v[194:197], v145 offset:21504
	ds_read_b128 v[198:201], v145 offset:22528
	ds_read_b128 v[202:205], v145 offset:23552
	global_load_lds_dwordx4 v[142:143], off
	s_add_i32 m0, s53, 0x2000
	s_add_u32 s54, s26, 0x40000
	v_lshl_add_u64 v[206:207], s[26:27], 0, v[132:133]
	s_addc_u32 s55, s27, 0
	s_add_i32 s53, s56, s38
	global_load_lds_dwordx4 v[206:207], off
	v_lshl_add_u64 v[208:209], s[54:55], 0, v[232:233]
	s_mov_b32 m0, s53
	v_lshl_add_u64 v[210:211], s[28:29], 0, v[130:131]
	global_load_lds_dwordx4 v[208:209], off
	v_lshl_add_u64 v[208:209], s[54:55], 0, v[132:133]
	s_add_i32 m0, s53, 0x2000
	s_nop 0
	global_load_lds_dwordx4 v[208:209], off
	v_lshl_add_u64 v[208:209], s[28:29], 0, v[128:129]
	s_waitcnt vmcnt(6)
	s_waitcnt lgkmcnt(0)
	s_barrier
	s_waitcnt lgkmcnt(0)
	v_mfma_f32_16x16x32_bf16 v[60:63], v[138:141], v[174:177], 0
	v_mfma_f32_16x16x32_bf16 v[56:59], v[150:153], v[174:177], 0
	v_mfma_f32_16x16x32_bf16 v[44:47], v[138:141], v[182:185], 0
	v_mfma_f32_16x16x32_bf16 v[40:43], v[150:153], v[182:185], 0
	v_mfma_f32_16x16x32_bf16 v[28:31], v[138:141], v[190:193], 0
	v_mfma_f32_16x16x32_bf16 v[24:27], v[150:153], v[190:193], 0
	v_mfma_f32_16x16x32_bf16 v[12:15], v[138:141], v[198:201], 0
	v_mfma_f32_16x16x32_bf16 v[8:11], v[150:153], v[198:201], 0
	v_mfma_f32_16x16x32_bf16 v[60:63], v[146:149], v[178:181], v[60:63]
	v_mfma_f32_16x16x32_bf16 v[56:59], v[154:157], v[178:181], v[56:59]
	v_mfma_f32_16x16x32_bf16 v[44:47], v[146:149], v[186:189], v[44:47]
	v_mfma_f32_16x16x32_bf16 v[40:43], v[154:157], v[186:189], v[40:43]
	v_mfma_f32_16x16x32_bf16 v[28:31], v[146:149], v[194:197], v[28:31]
	v_mfma_f32_16x16x32_bf16 v[24:27], v[154:157], v[194:197], v[24:27]
	v_mfma_f32_16x16x32_bf16 v[12:15], v[146:149], v[202:205], v[12:15]
	v_mfma_f32_16x16x32_bf16 v[8:11], v[154:157], v[202:205], v[8:11]
	v_mfma_f32_16x16x32_bf16 v[52:55], v[158:161], v[174:177], 0
	v_mfma_f32_16x16x32_bf16 v[48:51], v[166:169], v[174:177], 0
	v_mfma_f32_16x16x32_bf16 v[36:39], v[158:161], v[182:185], 0
	v_mfma_f32_16x16x32_bf16 v[32:35], v[166:169], v[182:185], 0
	v_mfma_f32_16x16x32_bf16 v[20:23], v[158:161], v[190:193], 0
	v_mfma_f32_16x16x32_bf16 v[16:19], v[166:169], v[190:193], 0
	v_mfma_f32_16x16x32_bf16 v[4:7], v[158:161], v[198:201], 0
	v_mfma_f32_16x16x32_bf16 v[0:3], v[166:169], v[198:201], 0
	v_mfma_f32_16x16x32_bf16 v[52:55], v[162:165], v[178:181], v[52:55]
	v_mfma_f32_16x16x32_bf16 v[48:51], v[170:173], v[178:181], v[48:51]
	v_mfma_f32_16x16x32_bf16 v[36:39], v[162:165], v[186:189], v[36:39]
	v_mfma_f32_16x16x32_bf16 v[32:35], v[170:173], v[186:189], v[32:35]
	v_mfma_f32_16x16x32_bf16 v[20:23], v[162:165], v[194:197], v[20:23]
	v_mfma_f32_16x16x32_bf16 v[16:19], v[170:173], v[194:197], v[16:19]
	v_mfma_f32_16x16x32_bf16 v[4:7], v[162:165], v[202:205], v[4:7]
	v_mfma_f32_16x16x32_bf16 v[0:3], v[170:173], v[202:205], v[0:3]
	s_barrier
	s_branch .Lzmid_4
.LBB0_1307:
	s_add_u32 s26, s24, 0xfffc0080
	s_addc_u32 s27, s25, -1
	s_add_i32 s53, 0, 0x10000
	s_cmp_eq_u32 s52, 12
	s_cselect_b32 s29, s7, s27
	s_cselect_b32 s28, s17, s26
	v_add_u32_e32 v142, s53, v144
	s_cselect_b32 s27, s15, s51
	s_cselect_b32 s26, s23, s50
	s_add_i32 s56, 0, 0x14000
	ds_read_b128 v[138:141], v142
	ds_read_b128 v[146:149], v142 offset:1024
	ds_read_b128 v[150:153], v142 offset:2048
	ds_read_b128 v[154:157], v142 offset:3072
	v_add_u32_e32 v142, s56, v144
	ds_read_b128 v[158:161], v142
	ds_read_b128 v[162:165], v142 offset:1024
	ds_read_b128 v[166:169], v142 offset:2048
	ds_read_b128 v[170:173], v142 offset:3072
	v_lshl_add_u64 v[142:143], s[24:25], 0, v[136:137]
	s_add_i32 m0, s39, 0xc000
	ds_read_b128 v[174:177], v145
	ds_read_b128 v[178:181], v145 offset:1024
	ds_read_b128 v[182:185], v145 offset:2048
	ds_read_b128 v[186:189], v145 offset:3072
	ds_read_b128 v[190:193], v145 offset:4096
	ds_read_b128 v[194:197], v145 offset:5120
	ds_read_b128 v[198:201], v145 offset:6144
	ds_read_b128 v[202:205], v145 offset:7168
	global_load_lds_dwordx4 v[142:143], off
	v_lshl_add_u64 v[142:143], s[24:25], 0, v[134:135]
	s_add_i32 m0, s39, 0xe000
	s_nop 0
	global_load_lds_dwordx4 v[142:143], off
	s_waitcnt vmcnt(8)
	s_waitcnt lgkmcnt(0)
	s_barrier
	s_waitcnt lgkmcnt(0)
	v_mfma_f32_16x16x32_bf16 v[124:127], v[138:141], v[174:177], v[124:127]
	v_mfma_f32_16x16x32_bf16 v[120:123], v[150:153], v[174:177], v[120:123]
	v_mfma_f32_16x16x32_bf16 v[108:111], v[138:141], v[182:185], v[108:111]
	v_mfma_f32_16x16x32_bf16 v[104:107], v[150:153], v[182:185], v[104:107]
	v_mfma_f32_16x16x32_bf16 v[92:95], v[138:141], v[190:193], v[92:95]
	v_mfma_f32_16x16x32_bf16 v[88:91], v[150:153], v[190:193], v[88:91]
	v_mfma_f32_16x16x32_bf16 v[76:79], v[138:141], v[198:201], v[76:79]
	v_mfma_f32_16x16x32_bf16 v[72:75], v[150:153], v[198:201], v[72:75]
	v_mfma_f32_16x16x32_bf16 v[124:127], v[146:149], v[178:181], v[124:127]
	v_mfma_f32_16x16x32_bf16 v[120:123], v[154:157], v[178:181], v[120:123]
	v_mfma_f32_16x16x32_bf16 v[108:111], v[146:149], v[186:189], v[108:111]
	v_mfma_f32_16x16x32_bf16 v[104:107], v[154:157], v[186:189], v[104:107]
	v_mfma_f32_16x16x32_bf16 v[92:95], v[146:149], v[194:197], v[92:95]
	v_mfma_f32_16x16x32_bf16 v[88:91], v[154:157], v[194:197], v[88:91]
	v_mfma_f32_16x16x32_bf16 v[76:79], v[146:149], v[202:205], v[76:79]
	v_mfma_f32_16x16x32_bf16 v[72:75], v[154:157], v[202:205], v[72:75]
	v_mfma_f32_16x16x32_bf16 v[116:119], v[158:161], v[174:177], v[116:119]
	v_mfma_f32_16x16x32_bf16 v[112:115], v[166:169], v[174:177], v[112:115]
	v_mfma_f32_16x16x32_bf16 v[100:103], v[158:161], v[182:185], v[100:103]
	v_mfma_f32_16x16x32_bf16 v[96:99], v[166:169], v[182:185], v[96:99]
	v_mfma_f32_16x16x32_bf16 v[84:87], v[158:161], v[190:193], v[84:87]
	v_mfma_f32_16x16x32_bf16 v[80:83], v[166:169], v[190:193], v[80:83]
	v_mfma_f32_16x16x32_bf16 v[68:71], v[158:161], v[198:201], v[68:71]
	v_mfma_f32_16x16x32_bf16 v[64:67], v[166:169], v[198:201], v[64:67]
	v_mfma_f32_16x16x32_bf16 v[116:119], v[162:165], v[178:181], v[116:119]
	v_mfma_f32_16x16x32_bf16 v[112:115], v[170:173], v[178:181], v[112:115]
	v_mfma_f32_16x16x32_bf16 v[100:103], v[162:165], v[186:189], v[100:103]
	v_mfma_f32_16x16x32_bf16 v[96:99], v[170:173], v[186:189], v[96:99]
	v_mfma_f32_16x16x32_bf16 v[84:87], v[162:165], v[194:197], v[84:87]
	v_mfma_f32_16x16x32_bf16 v[80:83], v[170:173], v[194:197], v[80:83]
	v_mfma_f32_16x16x32_bf16 v[68:71], v[162:165], v[202:205], v[68:71]
	v_mfma_f32_16x16x32_bf16 v[64:67], v[170:173], v[202:205], v[64:67]
	s_barrier
	s_add_i32 s53, s53, s38
	v_lshl_add_u64 v[142:143], s[26:27], 0, v[232:233]
	s_mov_b32 m0, s53
	ds_read_b128 v[174:177], v145 offset:16384
	ds_read_b128 v[178:181], v145 offset:17408
	ds_read_b128 v[182:185], v145 offset:18432
	ds_read_b128 v[186:189], v145 offset:19456
	ds_read_b128 v[190:193], v145 offset:20480
	ds_read_b128 v[194:197], v145 offset:21504
	ds_read_b128 v[198:201], v145 offset:22528
	ds_read_b128 v[202:205], v145 offset:23552
	global_load_lds_dwordx4 v[142:143], off
	s_add_i32 m0, s53, 0x2000
	s_add_u32 s54, s26, 0x40000
	v_lshl_add_u64 v[206:207], s[26:27], 0, v[132:133]
	s_addc_u32 s55, s27, 0
	s_add_i32 s53, s56, s38
	global_load_lds_dwordx4 v[206:207], off
	v_lshl_add_u64 v[208:209], s[54:55], 0, v[232:233]
	s_mov_b32 m0, s53
	v_lshl_add_u64 v[210:211], s[28:29], 0, v[130:131]
	global_load_lds_dwordx4 v[208:209], off
	v_lshl_add_u64 v[208:209], s[54:55], 0, v[132:133]
	s_add_i32 m0, s53, 0x2000
	s_nop 0
	global_load_lds_dwordx4 v[208:209], off
	v_lshl_add_u64 v[208:209], s[28:29], 0, v[128:129]
	s_waitcnt vmcnt(6)
	s_waitcnt lgkmcnt(0)
	s_barrier
	s_waitcnt lgkmcnt(0)
	v_mfma_f32_16x16x32_bf16 v[60:63], v[138:141], v[174:177], v[60:63]
	v_mfma_f32_16x16x32_bf16 v[56:59], v[150:153], v[174:177], v[56:59]
	v_mfma_f32_16x16x32_bf16 v[44:47], v[138:141], v[182:185], v[44:47]
	v_mfma_f32_16x16x32_bf16 v[40:43], v[150:153], v[182:185], v[40:43]
	v_mfma_f32_16x16x32_bf16 v[28:31], v[138:141], v[190:193], v[28:31]
	v_mfma_f32_16x16x32_bf16 v[24:27], v[150:153], v[190:193], v[24:27]
	v_mfma_f32_16x16x32_bf16 v[12:15], v[138:141], v[198:201], v[12:15]
	v_mfma_f32_16x16x32_bf16 v[8:11], v[150:153], v[198:201], v[8:11]
	v_mfma_f32_16x16x32_bf16 v[60:63], v[146:149], v[178:181], v[60:63]
	v_mfma_f32_16x16x32_bf16 v[56:59], v[154:157], v[178:181], v[56:59]
	v_mfma_f32_16x16x32_bf16 v[44:47], v[146:149], v[186:189], v[44:47]
	v_mfma_f32_16x16x32_bf16 v[40:43], v[154:157], v[186:189], v[40:43]
	v_mfma_f32_16x16x32_bf16 v[28:31], v[146:149], v[194:197], v[28:31]
	v_mfma_f32_16x16x32_bf16 v[24:27], v[154:157], v[194:197], v[24:27]
	v_mfma_f32_16x16x32_bf16 v[12:15], v[146:149], v[202:205], v[12:15]
	v_mfma_f32_16x16x32_bf16 v[8:11], v[154:157], v[202:205], v[8:11]
	v_mfma_f32_16x16x32_bf16 v[52:55], v[158:161], v[174:177], v[52:55]
	v_mfma_f32_16x16x32_bf16 v[48:51], v[166:169], v[174:177], v[48:51]
	v_mfma_f32_16x16x32_bf16 v[36:39], v[158:161], v[182:185], v[36:39]
	v_mfma_f32_16x16x32_bf16 v[32:35], v[166:169], v[182:185], v[32:35]
	v_mfma_f32_16x16x32_bf16 v[20:23], v[158:161], v[190:193], v[20:23]
	v_mfma_f32_16x16x32_bf16 v[16:19], v[166:169], v[190:193], v[16:19]
	v_mfma_f32_16x16x32_bf16 v[4:7], v[158:161], v[198:201], v[4:7]
	v_mfma_f32_16x16x32_bf16 v[0:3], v[166:169], v[198:201], v[0:3]
	v_mfma_f32_16x16x32_bf16 v[52:55], v[162:165], v[178:181], v[52:55]
	v_mfma_f32_16x16x32_bf16 v[48:51], v[170:173], v[178:181], v[48:51]
	v_mfma_f32_16x16x32_bf16 v[36:39], v[162:165], v[186:189], v[36:39]
	v_mfma_f32_16x16x32_bf16 v[32:35], v[170:173], v[186:189], v[32:35]
	v_mfma_f32_16x16x32_bf16 v[20:23], v[162:165], v[194:197], v[20:23]
	v_mfma_f32_16x16x32_bf16 v[16:19], v[170:173], v[194:197], v[16:19]
	v_mfma_f32_16x16x32_bf16 v[4:7], v[162:165], v[202:205], v[4:7]
	v_mfma_f32_16x16x32_bf16 v[0:3], v[170:173], v[202:205], v[0:3]
	s_barrier
.Lzmid_4:
	s_add_i32 s53, 0, 0x18000
	s_add_i32 s54, 0, 0x1c000
	v_add_u32_e32 v154, s53, v144
	v_add_u32_e32 v170, s54, v144
	ds_read_b128 v[138:141], v154
	ds_read_b128 v[146:149], v154 offset:1024
	ds_read_b128 v[150:153], v154 offset:2048
	ds_read_b128 v[154:157], v154 offset:3072
	ds_read_b128 v[158:161], v170
	ds_read_b128 v[162:165], v170 offset:1024
	ds_read_b128 v[166:169], v170 offset:2048
	ds_read_b128 v[170:173], v170 offset:3072
	s_add_u32 s28, s28, 0x40000
	s_addc_u32 s29, s29, 0
	s_mov_b32 m0, s39
	s_nop 0
	global_load_lds_dwordx4 v[208:209], off
	s_mov_b32 m0, s40
	s_nop 0
	global_load_lds_dwordx4 v[210:211], off
	s_mov_b32 m0, s41
	v_lshl_add_u64 v[212:213], s[28:29], 0, v[128:129]
	ds_read_b128 v[174:177], v145 offset:32768
	ds_read_b128 v[178:181], v145 offset:33792
	ds_read_b128 v[182:185], v145 offset:34816
	ds_read_b128 v[186:189], v145 offset:35840
	ds_read_b128 v[190:193], v145 offset:36864
	ds_read_b128 v[194:197], v145 offset:37888
	ds_read_b128 v[198:201], v145 offset:38912
	ds_read_b128 v[202:205], v145 offset:39936
	global_load_lds_dwordx4 v[212:213], off
	v_lshl_add_u64 v[212:213], s[28:29], 0, v[130:131]
	s_mov_b32 m0, s42
	s_nop 0
	global_load_lds_dwordx4 v[212:213], off
	s_waitcnt vmcnt(8)
	s_waitcnt lgkmcnt(0)
	s_barrier
	s_waitcnt lgkmcnt(0)
	v_mfma_f32_16x16x32_bf16 v[124:127], v[138:141], v[174:177], v[124:127]
	v_mfma_f32_16x16x32_bf16 v[120:123], v[150:153], v[174:177], v[120:123]
	v_mfma_f32_16x16x32_bf16 v[108:111], v[138:141], v[182:185], v[108:111]
	v_mfma_f32_16x16x32_bf16 v[104:107], v[150:153], v[182:185], v[104:107]
	v_mfma_f32_16x16x32_bf16 v[92:95], v[138:141], v[190:193], v[92:95]
	v_mfma_f32_16x16x32_bf16 v[88:91], v[150:153], v[190:193], v[88:91]
	v_mfma_f32_16x16x32_bf16 v[76:79], v[138:141], v[198:201], v[76:79]
	v_mfma_f32_16x16x32_bf16 v[72:75], v[150:153], v[198:201], v[72:75]
	v_mfma_f32_16x16x32_bf16 v[124:127], v[146:149], v[178:181], v[124:127]
	v_mfma_f32_16x16x32_bf16 v[120:123], v[154:157], v[178:181], v[120:123]
	v_mfma_f32_16x16x32_bf16 v[108:111], v[146:149], v[186:189], v[108:111]
	v_mfma_f32_16x16x32_bf16 v[104:107], v[154:157], v[186:189], v[104:107]
	v_mfma_f32_16x16x32_bf16 v[92:95], v[146:149], v[194:197], v[92:95]
	v_mfma_f32_16x16x32_bf16 v[88:91], v[154:157], v[194:197], v[88:91]
	v_mfma_f32_16x16x32_bf16 v[76:79], v[146:149], v[202:205], v[76:79]
	v_mfma_f32_16x16x32_bf16 v[72:75], v[154:157], v[202:205], v[72:75]
	v_mfma_f32_16x16x32_bf16 v[116:119], v[158:161], v[174:177], v[116:119]
	v_mfma_f32_16x16x32_bf16 v[112:115], v[166:169], v[174:177], v[112:115]
	v_mfma_f32_16x16x32_bf16 v[100:103], v[158:161], v[182:185], v[100:103]
	v_mfma_f32_16x16x32_bf16 v[96:99], v[166:169], v[182:185], v[96:99]
	v_mfma_f32_16x16x32_bf16 v[84:87], v[158:161], v[190:193], v[84:87]
	v_mfma_f32_16x16x32_bf16 v[80:83], v[166:169], v[190:193], v[80:83]
	v_mfma_f32_16x16x32_bf16 v[68:71], v[158:161], v[198:201], v[68:71]
	v_mfma_f32_16x16x32_bf16 v[64:67], v[166:169], v[198:201], v[64:67]
	v_mfma_f32_16x16x32_bf16 v[116:119], v[162:165], v[178:181], v[116:119]
	v_mfma_f32_16x16x32_bf16 v[112:115], v[170:173], v[178:181], v[112:115]
	v_mfma_f32_16x16x32_bf16 v[100:103], v[162:165], v[186:189], v[100:103]
	v_mfma_f32_16x16x32_bf16 v[96:99], v[170:173], v[186:189], v[96:99]
	v_mfma_f32_16x16x32_bf16 v[84:87], v[162:165], v[194:197], v[84:87]
	v_mfma_f32_16x16x32_bf16 v[80:83], v[170:173], v[194:197], v[80:83]
	v_mfma_f32_16x16x32_bf16 v[68:71], v[162:165], v[202:205], v[68:71]
	v_mfma_f32_16x16x32_bf16 v[64:67], v[170:173], v[202:205], v[64:67]
	s_barrier
	s_add_i32 s28, s53, s38
	v_lshl_add_u64 v[142:143], v[142:143], 0, s[94:95]
	s_mov_b32 m0, s28
	ds_read_b128 v[174:177], v145 offset:49152
	ds_read_b128 v[178:181], v145 offset:50176
	ds_read_b128 v[182:185], v145 offset:51200
	ds_read_b128 v[186:189], v145 offset:52224
	ds_read_b128 v[190:193], v145 offset:53248
	ds_read_b128 v[194:197], v145 offset:54272
	ds_read_b128 v[198:201], v145 offset:55296
	ds_read_b128 v[202:205], v145 offset:56320
	global_load_lds_dwordx4 v[142:143], off
	s_add_i32 m0, s28, 0x2000
	s_add_u32 s26, s26, 0x40080
	v_lshl_add_u64 v[142:143], v[206:207], 0, s[94:95]
	s_addc_u32 s27, s27, 0
	s_add_i32 s28, s54, s38
	global_load_lds_dwordx4 v[142:143], off
	v_lshl_add_u64 v[142:143], s[26:27], 0, v[232:233]
	s_mov_b32 m0, s28
	s_nop 0
	global_load_lds_dwordx4 v[142:143], off
	v_lshl_add_u64 v[142:143], s[26:27], 0, v[132:133]
	s_add_i32 m0, s28, 0x2000
	s_nop 0
	global_load_lds_dwordx4 v[142:143], off
	v_lshl_add_u64 v[142:143], v[208:209], 0, s[94:95]
	s_mov_b32 m0, s45
	s_nop 0
	global_load_lds_dwordx4 v[142:143], off
	v_lshl_add_u64 v[142:143], v[210:211], 0, s[94:95]
	s_mov_b32 m0, s46
	s_nop 0
	global_load_lds_dwordx4 v[142:143], off
	s_waitcnt vmcnt(8)
	s_waitcnt lgkmcnt(0)
	s_barrier
	s_waitcnt lgkmcnt(0)
	v_mfma_f32_16x16x32_bf16 v[60:63], v[138:141], v[174:177], v[60:63]
	v_mfma_f32_16x16x32_bf16 v[56:59], v[150:153], v[174:177], v[56:59]
	v_mfma_f32_16x16x32_bf16 v[44:47], v[138:141], v[182:185], v[44:47]
	v_mfma_f32_16x16x32_bf16 v[40:43], v[150:153], v[182:185], v[40:43]
	v_mfma_f32_16x16x32_bf16 v[28:31], v[138:141], v[190:193], v[28:31]
	v_mfma_f32_16x16x32_bf16 v[24:27], v[150:153], v[190:193], v[24:27]
	v_mfma_f32_16x16x32_bf16 v[12:15], v[138:141], v[198:201], v[12:15]
	v_mfma_f32_16x16x32_bf16 v[8:11], v[150:153], v[198:201], v[8:11]
	v_mfma_f32_16x16x32_bf16 v[60:63], v[146:149], v[178:181], v[60:63]
	v_mfma_f32_16x16x32_bf16 v[56:59], v[154:157], v[178:181], v[56:59]
	v_mfma_f32_16x16x32_bf16 v[44:47], v[146:149], v[186:189], v[44:47]
	v_mfma_f32_16x16x32_bf16 v[40:43], v[154:157], v[186:189], v[40:43]
	v_mfma_f32_16x16x32_bf16 v[28:31], v[146:149], v[194:197], v[28:31]
	v_mfma_f32_16x16x32_bf16 v[24:27], v[154:157], v[194:197], v[24:27]
	v_mfma_f32_16x16x32_bf16 v[12:15], v[146:149], v[202:205], v[12:15]
	v_mfma_f32_16x16x32_bf16 v[8:11], v[154:157], v[202:205], v[8:11]
	v_mfma_f32_16x16x32_bf16 v[52:55], v[158:161], v[174:177], v[52:55]
	v_mfma_f32_16x16x32_bf16 v[48:51], v[166:169], v[174:177], v[48:51]
	v_mfma_f32_16x16x32_bf16 v[36:39], v[158:161], v[182:185], v[36:39]
	v_mfma_f32_16x16x32_bf16 v[32:35], v[166:169], v[182:185], v[32:35]
	v_mfma_f32_16x16x32_bf16 v[20:23], v[158:161], v[190:193], v[20:23]
	v_mfma_f32_16x16x32_bf16 v[16:19], v[166:169], v[190:193], v[16:19]
	v_mfma_f32_16x16x32_bf16 v[4:7], v[158:161], v[198:201], v[4:7]
	v_mfma_f32_16x16x32_bf16 v[0:3], v[166:169], v[198:201], v[0:3]
	v_mfma_f32_16x16x32_bf16 v[52:55], v[162:165], v[178:181], v[52:55]
	v_mfma_f32_16x16x32_bf16 v[48:51], v[170:173], v[178:181], v[48:51]
	v_mfma_f32_16x16x32_bf16 v[36:39], v[162:165], v[186:189], v[36:39]
	v_mfma_f32_16x16x32_bf16 v[32:35], v[170:173], v[186:189], v[32:35]
	v_mfma_f32_16x16x32_bf16 v[20:23], v[162:165], v[194:197], v[20:23]
	v_mfma_f32_16x16x32_bf16 v[16:19], v[170:173], v[194:197], v[16:19]
	v_mfma_f32_16x16x32_bf16 v[4:7], v[162:165], v[202:205], v[4:7]
	v_mfma_f32_16x16x32_bf16 v[0:3], v[170:173], v[202:205], v[0:3]
	s_barrier
	s_add_i32 s52, s52, 2
	s_add_u32 s50, s50, 0x100
	s_addc_u32 s51, s51, 0
	s_add_u32 s24, s24, 0x100
	s_addc_u32 s25, s25, 0
	s_cmp_gt_u32 s52, 13
	s_cbranch_scc0 .LBB0_1307
	s_and_b64 vcc, exec, s[12:13]
	s_cbranch_vccz .LBB0_1310
	s_barrier

.LBB0_1420:
	s_ashr_i32 s17, s16, 31
	s_lshl_b64 s[18:19], s[16:17], 17
	s_add_u32 s18, s35, s18
	s_addc_u32 s19, s36, s19
	s_and_b64 s[20:21], s[4:5], exec
	s_cselect_b32 s31, s19, s25
	s_cselect_b32 s30, s18, s24
	s_ashr_i32 s15, s14, 31
	s_lshl_b64 s[20:21], s[14:15], 17
	s_add_u32 s20, s37, s20
	s_addc_u32 s21, s38, s21
	s_and_b64 s[28:29], s[4:5], exec
	s_cselect_b32 s29, s21, s27
	s_cselect_b32 s28, s20, s26
	s_add_i32 s17, 0, 0x10000
	s_add_i32 s49, 0, 0x14000
	v_add_u32_e32 v210, s17, v164
	v_add_u32_e32 v211, s49, v164
	ds_read_b128 v[0:3], v210
	ds_read_b128 v[4:7], v210 offset:1024
	ds_read_b128 v[8:11], v210 offset:2048
	ds_read_b128 v[12:15], v210 offset:3072
	ds_read_b128 v[16:19], v211
	ds_read_b128 v[20:23], v211 offset:1024
	ds_read_b128 v[24:27], v211 offset:2048
	ds_read_b128 v[28:31], v211 offset:3072
	v_mov_b64_e32 v[246:247], 0xff
	v_mov_b32_e32 v250, 0x3727c5ac
	s_add_u32 s50, s24, 0x10080
	s_addc_u32 s51, s25, 0
	s_add_i32 s53, s40, 0xc000
	s_waitcnt vmcnt(0)
	v_lshl_add_u64 v[64:65], s[50:51], 0, v[148:149]
	s_mov_b32 m0, s53
	s_add_i32 s15, s40, 0xe000
	ds_read_b128 v[32:35], v165
	ds_read_b128 v[36:39], v165 offset:1024
	ds_read_b128 v[40:43], v165 offset:2048
	ds_read_b128 v[44:47], v165 offset:3072
	ds_read_b128 v[48:51], v165 offset:4096
	ds_read_b128 v[52:55], v165 offset:5120
	ds_read_b128 v[56:59], v165 offset:6144
	ds_read_b128 v[60:63], v165 offset:7168
	global_load_lds_dwordx4 v[64:65], off
	v_lshl_add_u64 v[64:65], s[50:51], 0, v[150:151]
	s_mov_b32 m0, s15
	s_nop 0
	global_load_lds_dwordx4 v[64:65], off
	s_waitcnt vmcnt(8)
	s_waitcnt lgkmcnt(0)
	s_barrier
	s_waitcnt lgkmcnt(0)
	v_mfma_f32_16x16x32_bf16 v[64:67], v[0:3], v[32:35], 0
	v_mfma_f32_16x16x32_bf16 v[68:71], v[8:11], v[32:35], 0
	v_mfma_f32_16x16x32_bf16 v[72:75], v[0:3], v[40:43], 0
	v_mfma_f32_16x16x32_bf16 v[76:79], v[8:11], v[40:43], 0
	v_mfma_f32_16x16x32_bf16 v[80:83], v[0:3], v[48:51], 0
	v_mfma_f32_16x16x32_bf16 v[84:87], v[8:11], v[48:51], 0
	v_mfma_f32_16x16x32_bf16 v[88:91], v[0:3], v[56:59], 0
	v_mfma_f32_16x16x32_bf16 v[92:95], v[8:11], v[56:59], 0
	v_mfma_f32_16x16x32_bf16 v[64:67], v[4:7], v[36:39], v[64:67]
	v_mfma_f32_16x16x32_bf16 v[68:71], v[12:15], v[36:39], v[68:71]
	v_mfma_f32_16x16x32_bf16 v[72:75], v[4:7], v[44:47], v[72:75]
	v_mfma_f32_16x16x32_bf16 v[76:79], v[12:15], v[44:47], v[76:79]
	v_mfma_f32_16x16x32_bf16 v[80:83], v[4:7], v[52:55], v[80:83]
	v_mfma_f32_16x16x32_bf16 v[84:87], v[12:15], v[52:55], v[84:87]
	v_mfma_f32_16x16x32_bf16 v[88:91], v[4:7], v[60:63], v[88:91]
	v_mfma_f32_16x16x32_bf16 v[92:95], v[12:15], v[60:63], v[92:95]
	v_mfma_f32_16x16x32_bf16 v[96:99], v[16:19], v[32:35], 0
	v_mfma_f32_16x16x32_bf16 v[32:35], v[24:27], v[32:35], 0
	v_mfma_f32_16x16x32_bf16 v[96:99], v[20:23], v[36:39], v[96:99]
	v_mfma_f32_16x16x32_bf16 v[32:35], v[28:31], v[36:39], v[32:35]
	v_mfma_f32_16x16x32_bf16 v[36:39], v[16:19], v[40:43], 0
	v_mfma_f32_16x16x32_bf16 v[40:43], v[24:27], v[40:43], 0
	v_mfma_f32_16x16x32_bf16 v[36:39], v[20:23], v[44:47], v[36:39]
	v_mfma_f32_16x16x32_bf16 v[40:43], v[28:31], v[44:47], v[40:43]
	v_mfma_f32_16x16x32_bf16 v[44:47], v[16:19], v[48:51], 0
	v_mfma_f32_16x16x32_bf16 v[48:51], v[24:27], v[48:51], 0
	v_mfma_f32_16x16x32_bf16 v[44:47], v[20:23], v[52:55], v[44:47]
	v_mfma_f32_16x16x32_bf16 v[48:51], v[28:31], v[52:55], v[48:51]
	v_mfma_f32_16x16x32_bf16 v[52:55], v[16:19], v[56:59], 0
	v_mfma_f32_16x16x32_bf16 v[56:59], v[24:27], v[56:59], 0
	v_mfma_f32_16x16x32_bf16 v[52:55], v[20:23], v[60:63], v[52:55]
	v_mfma_f32_16x16x32_bf16 v[56:59], v[28:31], v[60:63], v[56:59]
	s_barrier
	s_add_i32 s51, s17, s39
	v_lshl_add_u64 v[162:163], s[26:27], 0, v[232:233]
	s_mov_b64 s[56:57], 0x100
	s_add_i32 s17, s51, 0x2000
	v_lshl_add_u64 v[128:129], v[162:163], 0, s[56:57]
	s_mov_b32 m0, s51
	v_lshl_add_u64 v[202:203], s[26:27], 0, v[152:153]
	s_add_u32 s54, s26, 0x10100
	ds_read_b128 v[60:63], v165 offset:16384
	ds_read_b128 v[100:103], v165 offset:17408
	ds_read_b128 v[104:107], v165 offset:18432
	ds_read_b128 v[108:111], v165 offset:19456
	ds_read_b128 v[112:115], v165 offset:20480
	ds_read_b128 v[116:119], v165 offset:21504
	ds_read_b128 v[120:123], v165 offset:22528
	ds_read_b128 v[124:127], v165 offset:23552
	global_load_lds_dwordx4 v[128:129], off
	v_lshl_add_u64 v[128:129], v[202:203], 0, s[56:57]
	s_mov_b32 m0, s17
	s_addc_u32 s55, s27, 0
	s_add_i32 s49, s49, s39
	global_load_lds_dwordx4 v[128:129], off
	v_lshl_add_u64 v[128:129], s[54:55], 0, v[232:233]
	s_mov_b32 m0, s49
	s_add_i32 s50, s49, 0x2000
	global_load_lds_dwordx4 v[128:129], off
	v_lshl_add_u64 v[128:129], s[54:55], 0, v[152:153]
	s_mov_b32 m0, s50
	v_lshl_add_u64 v[204:205], s[24:25], 0, v[148:149]
	global_load_lds_dwordx4 v[128:129], off
	v_lshl_add_u64 v[128:129], v[204:205], 0, s[56:57]
	s_mov_b32 m0, s40
	v_lshl_add_u64 v[206:207], s[24:25], 0, v[150:151]
	global_load_lds_dwordx4 v[128:129], off
	v_lshl_add_u64 v[128:129], v[206:207], 0, s[56:57]
	s_mov_b32 m0, s41
	s_nop 0
	global_load_lds_dwordx4 v[128:129], off
	s_waitcnt vmcnt(8)
	s_waitcnt lgkmcnt(0)
	s_barrier
	s_waitcnt lgkmcnt(0)
	v_mfma_f32_16x16x32_bf16 v[128:131], v[0:3], v[60:63], 0
	v_mfma_f32_16x16x32_bf16 v[136:139], v[0:3], v[104:107], 0
	v_mfma_f32_16x16x32_bf16 v[144:147], v[0:3], v[112:115], 0
	v_mfma_f32_16x16x32_bf16 v[0:3], v[0:3], v[120:123], 0
	v_mfma_f32_16x16x32_bf16 v[128:131], v[4:7], v[100:103], v[128:131]
	v_mfma_f32_16x16x32_bf16 v[132:135], v[8:11], v[60:63], 0
	v_mfma_f32_16x16x32_bf16 v[136:139], v[4:7], v[108:111], v[136:139]
	v_mfma_f32_16x16x32_bf16 v[140:143], v[8:11], v[104:107], 0
	v_mfma_f32_16x16x32_bf16 v[144:147], v[4:7], v[116:119], v[144:147]
	v_mfma_f32_16x16x32_bf16 v[0:3], v[4:7], v[124:127], v[0:3]
	v_mfma_f32_16x16x32_bf16 v[4:7], v[8:11], v[120:123], 0
	v_mfma_f32_16x16x32_bf16 v[132:135], v[12:15], v[100:103], v[132:135]
	v_mfma_f32_16x16x32_bf16 v[140:143], v[12:15], v[108:111], v[140:143]
	v_mfma_f32_16x16x32_bf16 v[154:157], v[8:11], v[112:115], 0
	v_mfma_f32_16x16x32_bf16 v[4:7], v[12:15], v[124:127], v[4:7]
	v_mfma_f32_16x16x32_bf16 v[154:157], v[12:15], v[116:119], v[154:157]
	v_mfma_f32_16x16x32_bf16 v[8:11], v[16:19], v[60:63], 0
	v_mfma_f32_16x16x32_bf16 v[12:15], v[24:27], v[60:63], 0
	v_mfma_f32_16x16x32_bf16 v[8:11], v[20:23], v[100:103], v[8:11]
	v_mfma_f32_16x16x32_bf16 v[12:15], v[28:31], v[100:103], v[12:15]
	v_mfma_f32_16x16x32_bf16 v[60:63], v[16:19], v[104:107], 0
	v_mfma_f32_16x16x32_bf16 v[100:103], v[24:27], v[104:107], 0
	v_mfma_f32_16x16x32_bf16 v[104:107], v[16:19], v[112:115], 0
	v_mfma_f32_16x16x32_bf16 v[16:19], v[16:19], v[120:123], 0
	v_mfma_f32_16x16x32_bf16 v[60:63], v[20:23], v[108:111], v[60:63]
	v_mfma_f32_16x16x32_bf16 v[104:107], v[20:23], v[116:119], v[104:107]
	v_mfma_f32_16x16x32_bf16 v[16:19], v[20:23], v[124:127], v[16:19]
	v_mfma_f32_16x16x32_bf16 v[20:23], v[24:27], v[120:123], 0
	v_mfma_f32_16x16x32_bf16 v[100:103], v[28:31], v[108:111], v[100:103]
	v_mfma_f32_16x16x32_bf16 v[108:111], v[24:27], v[112:115], 0
	v_mfma_f32_16x16x32_bf16 v[20:23], v[28:31], v[124:127], v[20:23]
	v_mfma_f32_16x16x32_bf16 v[108:111], v[28:31], v[116:119], v[108:111]
	s_barrier
	s_add_i32 s52, 0, 0x18000
	s_add_i32 s58, 0, 0x1c000
	v_add_u32_e32 v222, s52, v164
	v_add_u32_e32 v223, s58, v164
	ds_read_b128 v[24:27], v222
	ds_read_b128 v[28:31], v222 offset:1024
	ds_read_b128 v[112:115], v222 offset:2048
	ds_read_b128 v[116:119], v222 offset:3072
	ds_read_b128 v[120:123], v223
	ds_read_b128 v[124:127], v223 offset:1024
	ds_read_b128 v[158:161], v223 offset:2048
	ds_read_b128 v[166:169], v223 offset:3072
	s_add_u32 s54, s24, 0x10100
	s_addc_u32 s55, s25, 0
	s_mov_b32 m0, s42
	v_lshl_add_u64 v[208:209], s[54:55], 0, v[148:149]
	ds_read_b128 v[170:173], v165 offset:32768
	ds_read_b128 v[174:177], v165 offset:33792
	ds_read_b128 v[178:181], v165 offset:34816
	ds_read_b128 v[182:185], v165 offset:35840
	ds_read_b128 v[186:189], v165 offset:36864
	ds_read_b128 v[190:193], v165 offset:37888
	ds_read_b128 v[194:197], v165 offset:38912
	ds_read_b128 v[198:201], v165 offset:39936
	global_load_lds_dwordx4 v[208:209], off
	v_lshl_add_u64 v[208:209], s[54:55], 0, v[150:151]
	s_mov_b32 m0, s43
	s_nop 0
	global_load_lds_dwordx4 v[208:209], off
	s_waitcnt vmcnt(8)
	s_waitcnt lgkmcnt(0)
	s_barrier
	s_waitcnt lgkmcnt(0)
	v_mfma_f32_16x16x32_bf16 v[64:67], v[24:27], v[170:173], v[64:67]
	v_mfma_f32_16x16x32_bf16 v[68:71], v[112:115], v[170:173], v[68:71]
	v_mfma_f32_16x16x32_bf16 v[72:75], v[24:27], v[178:181], v[72:75]
	v_mfma_f32_16x16x32_bf16 v[76:79], v[112:115], v[178:181], v[76:79]
	v_mfma_f32_16x16x32_bf16 v[80:83], v[24:27], v[186:189], v[80:83]
	v_mfma_f32_16x16x32_bf16 v[84:87], v[112:115], v[186:189], v[84:87]
	v_mfma_f32_16x16x32_bf16 v[88:91], v[24:27], v[194:197], v[88:91]
	v_mfma_f32_16x16x32_bf16 v[92:95], v[112:115], v[194:197], v[92:95]
	v_mfma_f32_16x16x32_bf16 v[64:67], v[28:31], v[174:177], v[64:67]
	v_mfma_f32_16x16x32_bf16 v[68:71], v[116:119], v[174:177], v[68:71]
	v_mfma_f32_16x16x32_bf16 v[72:75], v[28:31], v[182:185], v[72:75]
	v_mfma_f32_16x16x32_bf16 v[76:79], v[116:119], v[182:185], v[76:79]
	v_mfma_f32_16x16x32_bf16 v[80:83], v[28:31], v[190:193], v[80:83]
	v_mfma_f32_16x16x32_bf16 v[84:87], v[116:119], v[190:193], v[84:87]
	v_mfma_f32_16x16x32_bf16 v[88:91], v[28:31], v[198:201], v[88:91]
	v_mfma_f32_16x16x32_bf16 v[92:95], v[116:119], v[198:201], v[92:95]
	v_mfma_f32_16x16x32_bf16 v[96:99], v[120:123], v[170:173], v[96:99]
	v_mfma_f32_16x16x32_bf16 v[32:35], v[158:161], v[170:173], v[32:35]
	v_mfma_f32_16x16x32_bf16 v[36:39], v[120:123], v[178:181], v[36:39]
	v_mfma_f32_16x16x32_bf16 v[40:43], v[158:161], v[178:181], v[40:43]
	v_mfma_f32_16x16x32_bf16 v[44:47], v[120:123], v[186:189], v[44:47]
	v_mfma_f32_16x16x32_bf16 v[48:51], v[158:161], v[186:189], v[48:51]
	v_mfma_f32_16x16x32_bf16 v[52:55], v[120:123], v[194:197], v[52:55]
	v_mfma_f32_16x16x32_bf16 v[56:59], v[158:161], v[194:197], v[56:59]
	v_mfma_f32_16x16x32_bf16 v[96:99], v[124:127], v[174:177], v[96:99]
	v_mfma_f32_16x16x32_bf16 v[32:35], v[166:169], v[174:177], v[32:35]
	v_mfma_f32_16x16x32_bf16 v[36:39], v[124:127], v[182:185], v[36:39]
	v_mfma_f32_16x16x32_bf16 v[40:43], v[166:169], v[182:185], v[40:43]
	v_mfma_f32_16x16x32_bf16 v[44:47], v[124:127], v[190:193], v[44:47]
	v_mfma_f32_16x16x32_bf16 v[48:51], v[166:169], v[190:193], v[48:51]
	v_mfma_f32_16x16x32_bf16 v[52:55], v[124:127], v[198:201], v[52:55]
	v_mfma_f32_16x16x32_bf16 v[56:59], v[166:169], v[198:201], v[56:59]
	s_barrier
	s_add_i32 s54, s52, s39
	s_mov_b64 s[60:61], 0x180
	s_add_i32 s52, s54, 0x2000
	v_lshl_add_u64 v[162:163], v[162:163], 0, s[60:61]
	s_mov_b32 m0, s54
	s_add_u32 s56, s26, 0x10180
	ds_read_b128 v[170:173], v165 offset:49152
	ds_read_b128 v[174:177], v165 offset:50176
	ds_read_b128 v[178:181], v165 offset:51200
	ds_read_b128 v[182:185], v165 offset:52224
	ds_read_b128 v[186:189], v165 offset:53248
	ds_read_b128 v[190:193], v165 offset:54272
	ds_read_b128 v[194:197], v165 offset:55296
	ds_read_b128 v[198:201], v165 offset:56320
	global_load_lds_dwordx4 v[162:163], off
	v_lshl_add_u64 v[162:163], v[202:203], 0, s[60:61]
	s_mov_b32 m0, s52
	s_addc_u32 s57, s27, 0
	s_add_i32 s26, s58, s39
	global_load_lds_dwordx4 v[162:163], off
	v_lshl_add_u64 v[162:163], s[56:57], 0, v[232:233]
	s_mov_b32 m0, s26
	s_add_i32 s27, s26, 0x2000
	global_load_lds_dwordx4 v[162:163], off
	v_lshl_add_u64 v[162:163], s[56:57], 0, v[152:153]
	s_mov_b32 m0, s27
	s_nop 0
	global_load_lds_dwordx4 v[162:163], off
	v_lshl_add_u64 v[162:163], v[204:205], 0, s[60:61]
	s_mov_b32 m0, s46
	s_nop 0
	global_load_lds_dwordx4 v[162:163], off
	v_lshl_add_u64 v[162:163], v[206:207], 0, s[60:61]
	s_mov_b32 m0, s47
	s_nop 0
	global_load_lds_dwordx4 v[162:163], off
	s_waitcnt vmcnt(8)
	s_waitcnt lgkmcnt(0)
	s_barrier
	s_waitcnt lgkmcnt(0)
	v_mfma_f32_16x16x32_bf16 v[128:131], v[24:27], v[170:173], v[128:131]
	v_mfma_f32_16x16x32_bf16 v[132:135], v[112:115], v[170:173], v[132:135]
	v_mfma_f32_16x16x32_bf16 v[136:139], v[24:27], v[178:181], v[136:139]
	v_mfma_f32_16x16x32_bf16 v[140:143], v[112:115], v[178:181], v[140:143]
	v_mfma_f32_16x16x32_bf16 v[144:147], v[24:27], v[186:189], v[144:147]
	v_mfma_f32_16x16x32_bf16 v[0:3], v[24:27], v[194:197], v[0:3]
	v_mfma_f32_16x16x32_bf16 v[4:7], v[112:115], v[194:197], v[4:7]
	v_mfma_f32_16x16x32_bf16 v[128:131], v[28:31], v[174:177], v[128:131]
	v_mfma_f32_16x16x32_bf16 v[132:135], v[116:119], v[174:177], v[132:135]
	v_mfma_f32_16x16x32_bf16 v[136:139], v[28:31], v[182:185], v[136:139]
	v_mfma_f32_16x16x32_bf16 v[140:143], v[116:119], v[182:185], v[140:143]
	v_mfma_f32_16x16x32_bf16 v[144:147], v[28:31], v[190:193], v[144:147]
	v_mfma_f32_16x16x32_bf16 v[154:157], v[112:115], v[186:189], v[154:157]
	v_mfma_f32_16x16x32_bf16 v[0:3], v[28:31], v[198:201], v[0:3]
	v_mfma_f32_16x16x32_bf16 v[4:7], v[116:119], v[198:201], v[4:7]
	v_mfma_f32_16x16x32_bf16 v[154:157], v[116:119], v[190:193], v[154:157]
	v_mfma_f32_16x16x32_bf16 v[8:11], v[120:123], v[170:173], v[8:11]
	v_mfma_f32_16x16x32_bf16 v[12:15], v[158:161], v[170:173], v[12:15]
	v_mfma_f32_16x16x32_bf16 v[24:27], v[120:123], v[178:181], v[60:63]
	v_mfma_f32_16x16x32_bf16 v[28:31], v[158:161], v[178:181], v[100:103]
	v_mfma_f32_16x16x32_bf16 v[60:63], v[120:123], v[186:189], v[104:107]
	v_mfma_f32_16x16x32_bf16 v[100:103], v[158:161], v[186:189], v[108:111]
	v_mfma_f32_16x16x32_bf16 v[16:19], v[120:123], v[194:197], v[16:19]
	v_mfma_f32_16x16x32_bf16 v[20:23], v[158:161], v[194:197], v[20:23]
	v_mfma_f32_16x16x32_bf16 v[8:11], v[124:127], v[174:177], v[8:11]
	v_mfma_f32_16x16x32_bf16 v[12:15], v[166:169], v[174:177], v[12:15]
	v_mfma_f32_16x16x32_bf16 v[24:27], v[124:127], v[182:185], v[24:27]
	v_mfma_f32_16x16x32_bf16 v[28:31], v[166:169], v[182:185], v[28:31]
	v_mfma_f32_16x16x32_bf16 v[60:63], v[124:127], v[190:193], v[60:63]
	v_mfma_f32_16x16x32_bf16 v[100:103], v[166:169], v[190:193], v[100:103]
	v_mfma_f32_16x16x32_bf16 v[16:19], v[124:127], v[198:201], v[16:19]
	v_mfma_f32_16x16x32_bf16 v[20:23], v[166:169], v[198:201], v[20:23]
	s_barrier
	ds_read_b128 v[104:107], v210
	ds_read_b128 v[108:111], v210 offset:1024
	ds_read_b128 v[112:115], v210 offset:2048
	ds_read_b128 v[116:119], v210 offset:3072
	ds_read_b128 v[120:123], v211
	ds_read_b128 v[124:127], v211 offset:1024
	ds_read_b128 v[158:161], v211 offset:2048
	ds_read_b128 v[166:169], v211 offset:3072
	s_add_u32 s24, s24, 0x10180
	s_addc_u32 s25, s25, 0
	s_mov_b32 m0, s53
	v_lshl_add_u64 v[162:163], s[24:25], 0, v[148:149]
	ds_read_b128 v[170:173], v165
	ds_read_b128 v[174:177], v165 offset:1024
	ds_read_b128 v[178:181], v165 offset:2048
	ds_read_b128 v[182:185], v165 offset:3072
	ds_read_b128 v[186:189], v165 offset:4096
	ds_read_b128 v[190:193], v165 offset:5120
	ds_read_b128 v[194:197], v165 offset:6144
	ds_read_b128 v[198:201], v165 offset:7168
	global_load_lds_dwordx4 v[162:163], off
	v_lshl_add_u64 v[162:163], s[24:25], 0, v[150:151]
	s_mov_b32 m0, s15
	s_nop 0
	global_load_lds_dwordx4 v[162:163], off
	s_waitcnt vmcnt(8)
	s_waitcnt lgkmcnt(0)
	s_barrier
	s_waitcnt lgkmcnt(0)
	v_mfma_f32_16x16x32_bf16 v[64:67], v[104:107], v[170:173], v[64:67]
	v_mfma_f32_16x16x32_bf16 v[68:71], v[112:115], v[170:173], v[68:71]
	v_mfma_f32_16x16x32_bf16 v[72:75], v[104:107], v[178:181], v[72:75]
	v_mfma_f32_16x16x32_bf16 v[76:79], v[112:115], v[178:181], v[76:79]
	v_mfma_f32_16x16x32_bf16 v[80:83], v[104:107], v[186:189], v[80:83]
	v_mfma_f32_16x16x32_bf16 v[84:87], v[112:115], v[186:189], v[84:87]
	v_mfma_f32_16x16x32_bf16 v[88:91], v[104:107], v[194:197], v[88:91]
	v_mfma_f32_16x16x32_bf16 v[64:67], v[108:111], v[174:177], v[64:67]
	v_mfma_f32_16x16x32_bf16 v[68:71], v[116:119], v[174:177], v[68:71]
	v_mfma_f32_16x16x32_bf16 v[72:75], v[108:111], v[182:185], v[72:75]
	v_mfma_f32_16x16x32_bf16 v[76:79], v[116:119], v[182:185], v[76:79]
	v_mfma_f32_16x16x32_bf16 v[80:83], v[108:111], v[190:193], v[80:83]
	v_mfma_f32_16x16x32_bf16 v[84:87], v[116:119], v[190:193], v[84:87]
	v_mfma_f32_16x16x32_bf16 v[202:205], v[108:111], v[198:201], v[88:91]
	v_mfma_f32_16x16x32_bf16 v[88:91], v[112:115], v[194:197], v[92:95]
	v_mfma_f32_16x16x32_bf16 v[206:209], v[116:119], v[198:201], v[88:91]
	v_mfma_f32_16x16x32_bf16 v[88:91], v[120:123], v[170:173], v[96:99]
	v_mfma_f32_16x16x32_bf16 v[32:35], v[158:161], v[170:173], v[32:35]
	v_mfma_f32_16x16x32_bf16 v[36:39], v[120:123], v[178:181], v[36:39]
	v_mfma_f32_16x16x32_bf16 v[40:43], v[158:161], v[178:181], v[40:43]
	v_mfma_f32_16x16x32_bf16 v[44:47], v[120:123], v[186:189], v[44:47]
	v_mfma_f32_16x16x32_bf16 v[48:51], v[158:161], v[186:189], v[48:51]
	v_mfma_f32_16x16x32_bf16 v[52:55], v[120:123], v[194:197], v[52:55]
	v_mfma_f32_16x16x32_bf16 v[56:59], v[158:161], v[194:197], v[56:59]
	v_mfma_f32_16x16x32_bf16 v[96:99], v[124:127], v[174:177], v[88:91]
	v_mfma_f32_16x16x32_bf16 v[32:35], v[166:169], v[174:177], v[32:35]
	v_mfma_f32_16x16x32_bf16 v[36:39], v[124:127], v[182:185], v[36:39]
	v_mfma_f32_16x16x32_bf16 v[40:43], v[166:169], v[182:185], v[40:43]
	v_mfma_f32_16x16x32_bf16 v[44:47], v[124:127], v[190:193], v[44:47]
	v_mfma_f32_16x16x32_bf16 v[48:51], v[166:169], v[190:193], v[48:51]
	v_mfma_f32_16x16x32_bf16 v[52:55], v[124:127], v[198:201], v[52:55]
	v_mfma_f32_16x16x32_bf16 v[56:59], v[166:169], v[198:201], v[56:59]
	s_barrier
	s_mov_b32 m0, s51
	v_lshl_add_u64 v[162:163], s[28:29], 0, v[232:233]
	s_add_u32 s24, s28, 0x10000
	ds_read_b128 v[88:91], v165 offset:16384
	ds_read_b128 v[92:95], v165 offset:17408
	ds_read_b128 v[170:173], v165 offset:18432
	ds_read_b128 v[174:177], v165 offset:19456
	ds_read_b128 v[178:181], v165 offset:20480
	ds_read_b128 v[182:185], v165 offset:21504
	ds_read_b128 v[186:189], v165 offset:22528
	ds_read_b128 v[190:193], v165 offset:23552
	global_load_lds_dwordx4 v[162:163], off
	v_lshl_add_u64 v[230:231], s[28:29], 0, v[152:153]
	s_mov_b32 m0, s17
	s_addc_u32 s25, s29, 0
	global_load_lds_dwordx4 v[230:231], off
	v_lshl_add_u64 v[194:195], s[24:25], 0, v[232:233]
	s_mov_b32 m0, s49
	v_lshl_add_u64 v[242:243], s[30:31], 0, v[148:149]
	global_load_lds_dwordx4 v[194:195], off
	v_lshl_add_u64 v[194:195], s[24:25], 0, v[152:153]
	s_mov_b32 m0, s50
	v_lshl_add_u64 v[244:245], s[30:31], 0, v[150:151]
	global_load_lds_dwordx4 v[194:195], off
	s_mov_b32 m0, s40
	s_nop 0
	global_load_lds_dwordx4 v[242:243], off
	s_mov_b32 m0, s41
	s_nop 0
	global_load_lds_dwordx4 v[244:245], off
	s_waitcnt vmcnt(8)
	s_waitcnt lgkmcnt(0)
	s_barrier
	s_waitcnt lgkmcnt(0)
	v_mfma_f32_16x16x32_bf16 v[128:131], v[104:107], v[88:91], v[128:131]
	v_mfma_f32_16x16x32_bf16 v[194:197], v[108:111], v[92:95], v[128:131]
	v_mfma_f32_16x16x32_bf16 v[128:131], v[112:115], v[88:91], v[132:135]
	v_mfma_f32_16x16x32_bf16 v[198:201], v[116:119], v[92:95], v[128:131]
	v_mfma_f32_16x16x32_bf16 v[128:131], v[104:107], v[170:173], v[136:139]
	v_mfma_f32_16x16x32_bf16 v[210:213], v[108:111], v[174:177], v[128:131]
	v_mfma_f32_16x16x32_bf16 v[128:131], v[112:115], v[170:173], v[140:143]
	v_mfma_f32_16x16x32_bf16 v[214:217], v[116:119], v[174:177], v[128:131]
	v_mfma_f32_16x16x32_bf16 v[128:131], v[104:107], v[178:181], v[144:147]
	v_mfma_f32_16x16x32_bf16 v[0:3], v[104:107], v[186:189], v[0:3]
	v_mfma_f32_16x16x32_bf16 v[4:7], v[112:115], v[186:189], v[4:7]
	v_mfma_f32_16x16x32_bf16 v[218:221], v[108:111], v[182:185], v[128:131]
	v_mfma_f32_16x16x32_bf16 v[128:131], v[112:115], v[178:181], v[154:157]
	v_mfma_f32_16x16x32_bf16 v[0:3], v[108:111], v[190:193], v[0:3]
	v_mfma_f32_16x16x32_bf16 v[4:7], v[116:119], v[190:193], v[4:7]
	v_mfma_f32_16x16x32_bf16 v[154:157], v[116:119], v[182:185], v[128:131]
	v_mfma_f32_16x16x32_bf16 v[8:11], v[120:123], v[88:91], v[8:11]
	v_mfma_f32_16x16x32_bf16 v[104:107], v[124:127], v[92:95], v[8:11]
	v_mfma_f32_16x16x32_bf16 v[8:11], v[158:161], v[88:91], v[12:15]
	v_mfma_f32_16x16x32_bf16 v[108:111], v[166:169], v[92:95], v[8:11]
	v_mfma_f32_16x16x32_bf16 v[8:11], v[120:123], v[170:173], v[24:27]
	v_mfma_f32_16x16x32_bf16 v[112:115], v[124:127], v[174:177], v[8:11]
	v_mfma_f32_16x16x32_bf16 v[8:11], v[158:161], v[170:173], v[28:31]
	v_mfma_f32_16x16x32_bf16 v[116:119], v[166:169], v[174:177], v[8:11]
	v_mfma_f32_16x16x32_bf16 v[8:11], v[120:123], v[178:181], v[60:63]
	v_mfma_f32_16x16x32_bf16 v[170:173], v[124:127], v[182:185], v[8:11]
	v_mfma_f32_16x16x32_bf16 v[8:11], v[158:161], v[178:181], v[100:103]
	v_mfma_f32_16x16x32_bf16 v[174:177], v[166:169], v[182:185], v[8:11]
	v_mfma_f32_16x16x32_bf16 v[8:11], v[120:123], v[186:189], v[16:19]
	v_mfma_f32_16x16x32_bf16 v[124:127], v[124:127], v[190:193], v[8:11]
	v_mfma_f32_16x16x32_bf16 v[8:11], v[158:161], v[186:189], v[20:23]
	v_mfma_f32_16x16x32_bf16 v[158:161], v[166:169], v[190:193], v[8:11]
	s_barrier
	s_nop 4
	ds_read_b128 v[8:11], v222
	ds_read_b128 v[12:15], v222 offset:1024
	ds_read_b128 v[16:19], v222 offset:2048
	ds_read_b128 v[20:23], v222 offset:3072
	ds_read_b128 v[166:169], v223
	ds_read_b128 v[178:181], v223 offset:1024
	ds_read_b128 v[182:185], v223 offset:2048
	ds_read_b128 v[186:189], v223 offset:3072
	s_add_u32 s24, s30, 0x10000
	s_addc_u32 s25, s31, 0
	s_mov_b32 m0, s42
	v_lshl_add_u64 v[88:89], s[24:25], 0, v[148:149]
	ds_read_b128 v[24:27], v165 offset:32768
	ds_read_b128 v[28:31], v165 offset:33792
	ds_read_b128 v[60:63], v165 offset:34816
	ds_read_b128 v[190:193], v165 offset:35840
	ds_read_b128 v[222:225], v165 offset:36864
	ds_read_b128 v[226:229], v165 offset:37888
	ds_read_b128 v[234:237], v165 offset:38912
	ds_read_b128 v[238:241], v165 offset:39936
	global_load_lds_dwordx4 v[88:89], off
	v_lshl_add_u64 v[88:89], s[24:25], 0, v[150:151]
	s_mov_b32 m0, s43
	s_nop 0
	global_load_lds_dwordx4 v[88:89], off
	s_waitcnt vmcnt(8)
	s_waitcnt lgkmcnt(0)
	s_barrier
	s_waitcnt lgkmcnt(0)
	v_mfma_f32_16x16x32_bf16 v[64:67], v[8:11], v[24:27], v[64:67]
	v_mfma_f32_16x16x32_bf16 v[144:147], v[12:15], v[28:31], v[64:67]
	v_mfma_f32_16x16x32_bf16 v[64:67], v[16:19], v[24:27], v[68:71]
	v_mfma_f32_16x16x32_bf16 v[140:143], v[20:23], v[28:31], v[64:67]
	v_mfma_f32_16x16x32_bf16 v[64:67], v[8:11], v[60:63], v[72:75]
	v_mfma_f32_16x16x32_bf16 v[128:131], v[12:15], v[190:193], v[64:67]
	v_mfma_f32_16x16x32_bf16 v[64:67], v[16:19], v[60:63], v[76:79]
	v_mfma_f32_16x16x32_bf16 v[120:123], v[20:23], v[190:193], v[64:67]
	v_mfma_f32_16x16x32_bf16 v[64:67], v[8:11], v[222:225], v[80:83]
	v_mfma_f32_16x16x32_bf16 v[92:95], v[12:15], v[226:229], v[64:67]
	v_mfma_f32_16x16x32_bf16 v[64:67], v[16:19], v[222:225], v[84:87]
	v_mfma_f32_16x16x32_bf16 v[88:91], v[20:23], v[226:229], v[64:67]
	v_mfma_f32_16x16x32_bf16 v[64:67], v[8:11], v[234:237], v[202:205]
	v_mfma_f32_16x16x32_bf16 v[76:79], v[12:15], v[238:241], v[64:67]
	v_mfma_f32_16x16x32_bf16 v[64:67], v[16:19], v[234:237], v[206:209]
	v_mfma_f32_16x16x32_bf16 v[72:75], v[20:23], v[238:241], v[64:67]
	v_mfma_f32_16x16x32_bf16 v[64:67], v[166:169], v[24:27], v[96:99]
	v_mfma_f32_16x16x32_bf16 v[24:27], v[182:185], v[24:27], v[32:35]
	v_mfma_f32_16x16x32_bf16 v[132:135], v[186:189], v[28:31], v[24:27]
	v_mfma_f32_16x16x32_bf16 v[24:27], v[166:169], v[60:63], v[36:39]
	v_mfma_f32_16x16x32_bf16 v[100:103], v[178:181], v[190:193], v[24:27]
	v_mfma_f32_16x16x32_bf16 v[24:27], v[182:185], v[60:63], v[40:43]
	v_mfma_f32_16x16x32_bf16 v[96:99], v[186:189], v[190:193], v[24:27]
	v_mfma_f32_16x16x32_bf16 v[24:27], v[166:169], v[222:225], v[44:47]
	v_mfma_f32_16x16x32_bf16 v[84:87], v[178:181], v[226:229], v[24:27]
	v_mfma_f32_16x16x32_bf16 v[24:27], v[182:185], v[222:225], v[48:51]
	v_mfma_f32_16x16x32_bf16 v[80:83], v[186:189], v[226:229], v[24:27]
	v_mfma_f32_16x16x32_bf16 v[24:27], v[166:169], v[234:237], v[52:55]
	v_mfma_f32_16x16x32_bf16 v[68:71], v[178:181], v[238:241], v[24:27]
	v_mfma_f32_16x16x32_bf16 v[24:27], v[182:185], v[234:237], v[56:59]
	v_mfma_f32_16x16x32_bf16 v[136:139], v[178:181], v[28:31], v[64:67]
	v_mfma_f32_16x16x32_bf16 v[64:67], v[186:189], v[238:241], v[24:27]
	s_barrier
	s_mov_b32 m0, s54
	s_nop 2
	v_lshl_add_u64 v[24:25], v[162:163], 0, s[94:95]
	s_add_u32 s24, s28, 0x10080
	ds_read_b128 v[32:35], v165 offset:49152
	ds_read_b128 v[36:39], v165 offset:50176
	ds_read_b128 v[190:193], v165 offset:51200
	ds_read_b128 v[202:205], v165 offset:52224
	ds_read_b128 v[206:209], v165 offset:53248
	ds_read_b128 v[222:225], v165 offset:54272
	ds_read_b128 v[226:229], v165 offset:55296
	ds_read_b128 v[234:237], v165 offset:56320
	global_load_lds_dwordx4 v[24:25], off
	v_lshl_add_u64 v[24:25], v[230:231], 0, s[94:95]
	s_mov_b32 m0, s52
	s_addc_u32 s25, s29, 0
	global_load_lds_dwordx4 v[24:25], off
	v_lshl_add_u64 v[24:25], s[24:25], 0, v[232:233]
	s_mov_b32 m0, s26
	s_nop 0
	global_load_lds_dwordx4 v[24:25], off
	v_lshl_add_u64 v[24:25], s[24:25], 0, v[152:153]
	s_mov_b32 m0, s27
	s_nop 0
	global_load_lds_dwordx4 v[24:25], off
	v_lshl_add_u64 v[24:25], v[242:243], 0, s[94:95]
	s_mov_b32 m0, s46
	s_nop 0
	global_load_lds_dwordx4 v[24:25], off
	v_lshl_add_u64 v[24:25], v[244:245], 0, s[94:95]
	s_mov_b32 m0, s47
	s_nop 0
	global_load_lds_dwordx4 v[24:25], off
	s_waitcnt vmcnt(8)
	s_waitcnt lgkmcnt(0)
	s_barrier
	s_waitcnt lgkmcnt(0)
	v_mfma_f32_16x16x32_bf16 v[24:27], v[8:11], v[32:35], v[194:197]
	v_mfma_f32_16x16x32_bf16 v[60:63], v[12:15], v[36:39], v[24:27]
	v_mfma_f32_16x16x32_bf16 v[24:27], v[16:19], v[32:35], v[198:201]
	v_mfma_f32_16x16x32_bf16 v[56:59], v[20:23], v[36:39], v[24:27]
	v_mfma_f32_16x16x32_bf16 v[24:27], v[8:11], v[190:193], v[210:213]
	v_mfma_f32_16x16x32_bf16 v[44:47], v[12:15], v[202:205], v[24:27]
	v_mfma_f32_16x16x32_bf16 v[24:27], v[16:19], v[190:193], v[214:217]
	v_mfma_f32_16x16x32_bf16 v[40:43], v[20:23], v[202:205], v[24:27]
	v_mfma_f32_16x16x32_bf16 v[24:27], v[8:11], v[206:209], v[218:221]
	v_mfma_f32_16x16x32_bf16 v[0:3], v[8:11], v[226:229], v[0:3]
	v_mfma_f32_16x16x32_bf16 v[28:31], v[12:15], v[222:225], v[24:27]
	v_mfma_f32_16x16x32_bf16 v[24:27], v[16:19], v[206:209], v[154:157]
	v_mfma_f32_16x16x32_bf16 v[12:15], v[12:15], v[234:237], v[0:3]
	v_mfma_f32_16x16x32_bf16 v[0:3], v[16:19], v[226:229], v[4:7]
	v_mfma_f32_16x16x32_bf16 v[24:27], v[20:23], v[222:225], v[24:27]
	v_mfma_f32_16x16x32_bf16 v[8:11], v[20:23], v[234:237], v[0:3]
	v_mfma_f32_16x16x32_bf16 v[0:3], v[166:169], v[32:35], v[104:107]
	v_mfma_f32_16x16x32_bf16 v[52:55], v[178:181], v[36:39], v[0:3]
	v_mfma_f32_16x16x32_bf16 v[0:3], v[182:185], v[32:35], v[108:111]
	v_mfma_f32_16x16x32_bf16 v[48:51], v[186:189], v[36:39], v[0:3]
	v_mfma_f32_16x16x32_bf16 v[0:3], v[166:169], v[190:193], v[112:115]
	v_mfma_f32_16x16x32_bf16 v[36:39], v[178:181], v[202:205], v[0:3]
	v_mfma_f32_16x16x32_bf16 v[0:3], v[182:185], v[190:193], v[116:119]
	v_mfma_f32_16x16x32_bf16 v[32:35], v[186:189], v[202:205], v[0:3]
	v_mfma_f32_16x16x32_bf16 v[0:3], v[166:169], v[206:209], v[170:173]
	v_mfma_f32_16x16x32_bf16 v[20:23], v[178:181], v[222:225], v[0:3]
	v_mfma_f32_16x16x32_bf16 v[0:3], v[182:185], v[206:209], v[174:177]
	v_mfma_f32_16x16x32_bf16 v[16:19], v[186:189], v[222:225], v[0:3]
	v_mfma_f32_16x16x32_bf16 v[0:3], v[166:169], v[226:229], v[124:127]
	v_mfma_f32_16x16x32_bf16 v[4:7], v[178:181], v[234:237], v[0:3]
	v_mfma_f32_16x16x32_bf16 v[0:3], v[182:185], v[226:229], v[158:161]
	v_mfma_f32_16x16x32_bf16 v[0:3], v[186:189], v[234:237], v[0:3]
	s_barrier
	s_andn2_b64 vcc, exec, s[10:11]
	s_cbranch_vccnz .LBB0_1422
	s_barrier

.LBB0_1491:
	s_ashr_i32 s23, s22, 31
	s_lshl_b64 s[24:25], s[22:23], 21
	s_add_u32 s24, s70, s24
	s_addc_u32 s25, s71, s25
	s_and_b64 s[26:27], s[4:5], exec
	s_cselect_b32 s23, s25, s35
	s_cselect_b32 s56, s24, s34
	s_ashr_i32 s21, s20, 31
	s_lshl_b64 s[26:27], s[20:21], 21
	s_add_u32 s26, s72, s26
	s_addc_u32 s27, s76, s27
	s_and_b64 s[36:37], s[4:5], exec
	s_cselect_b32 s21, s27, s31
	s_cselect_b32 s57, s26, s30
	s_add_u32 s58, s30, 0x100
	s_addc_u32 s59, s31, 0
	s_add_u32 s30, s34, 0x100080
	s_addc_u32 s31, s35, 0
	s_mov_b32 s60, -2
	s_waitcnt vmcnt(0)
	s_add_u32 s34, s30, 0xfff00080
	s_addc_u32 s35, s31, -1
	s_add_i32 s61, 0, 0x10000
	s_cmp_eq_u32 s60, 60
	s_cselect_b32 s37, s23, s35
	s_cselect_b32 s36, s56, s34
	s_cselect_b32 s35, s21, s59
	s_cselect_b32 s34, s57, s58
	s_add_i32 s64, 0, 0x14000
	v_add_u32_e32 v100, s61, v220
	v_add_u32_e32 v156, s64, v220
	ds_read_b128 v[88:91], v100
	ds_read_b128 v[92:95], v100 offset:1024
	ds_read_b128 v[96:99], v100 offset:2048
	ds_read_b128 v[100:103], v100 offset:3072
	ds_read_b128 v[144:147], v156
	ds_read_b128 v[148:151], v156 offset:1024
	ds_read_b128 v[152:155], v156 offset:2048
	ds_read_b128 v[156:159], v156 offset:3072
	v_lshl_add_u64 v[202:203], s[30:31], 0, v[188:189]
	s_add_i32 m0, s78, 0xc000
	ds_read_b128 v[160:163], v221
	ds_read_b128 v[164:167], v221 offset:1024
	ds_read_b128 v[168:171], v221 offset:2048
	ds_read_b128 v[172:175], v221 offset:3072
	ds_read_b128 v[176:179], v221 offset:4096
	ds_read_b128 v[190:193], v221 offset:5120
	ds_read_b128 v[194:197], v221 offset:6144
	ds_read_b128 v[198:201], v221 offset:7168
	global_load_lds_dwordx4 v[202:203], off
	v_lshl_add_u64 v[202:203], s[30:31], 0, v[186:187]
	s_add_i32 m0, s78, 0xe000
	s_nop 0
	global_load_lds_dwordx4 v[202:203], off
	s_waitcnt vmcnt(8)
	s_waitcnt lgkmcnt(0)
	s_barrier
	s_waitcnt lgkmcnt(0)
	v_mfma_f32_16x16x32_bf16 v[140:143], v[88:91], v[160:163], 0
	v_mfma_f32_16x16x32_bf16 v[136:139], v[96:99], v[160:163], 0
	v_mfma_f32_16x16x32_bf16 v[124:127], v[88:91], v[168:171], 0
	v_mfma_f32_16x16x32_bf16 v[120:123], v[96:99], v[168:171], 0
	v_mfma_f32_16x16x32_bf16 v[108:111], v[88:91], v[176:179], 0
	v_mfma_f32_16x16x32_bf16 v[104:107], v[96:99], v[176:179], 0
	v_mfma_f32_16x16x32_bf16 v[76:79], v[88:91], v[194:197], 0
	v_mfma_f32_16x16x32_bf16 v[72:75], v[96:99], v[194:197], 0
	v_mfma_f32_16x16x32_bf16 v[140:143], v[92:95], v[164:167], v[140:143]
	v_mfma_f32_16x16x32_bf16 v[136:139], v[100:103], v[164:167], v[136:139]
	v_mfma_f32_16x16x32_bf16 v[124:127], v[92:95], v[172:175], v[124:127]
	v_mfma_f32_16x16x32_bf16 v[120:123], v[100:103], v[172:175], v[120:123]
	v_mfma_f32_16x16x32_bf16 v[108:111], v[92:95], v[190:193], v[108:111]
	v_mfma_f32_16x16x32_bf16 v[104:107], v[100:103], v[190:193], v[104:107]
	v_mfma_f32_16x16x32_bf16 v[76:79], v[92:95], v[198:201], v[76:79]
	v_mfma_f32_16x16x32_bf16 v[72:75], v[100:103], v[198:201], v[72:75]
	v_mfma_f32_16x16x32_bf16 v[132:135], v[144:147], v[160:163], 0
	v_mfma_f32_16x16x32_bf16 v[128:131], v[152:155], v[160:163], 0
	v_mfma_f32_16x16x32_bf16 v[116:119], v[144:147], v[168:171], 0
	v_mfma_f32_16x16x32_bf16 v[112:115], v[152:155], v[168:171], 0
	v_mfma_f32_16x16x32_bf16 v[84:87], v[144:147], v[176:179], 0
	v_mfma_f32_16x16x32_bf16 v[80:83], v[152:155], v[176:179], 0
	v_mfma_f32_16x16x32_bf16 v[68:71], v[144:147], v[194:197], 0
	v_mfma_f32_16x16x32_bf16 v[64:67], v[152:155], v[194:197], 0
	v_mfma_f32_16x16x32_bf16 v[132:135], v[148:151], v[164:167], v[132:135]
	v_mfma_f32_16x16x32_bf16 v[128:131], v[156:159], v[164:167], v[128:131]
	v_mfma_f32_16x16x32_bf16 v[116:119], v[148:151], v[172:175], v[116:119]
	v_mfma_f32_16x16x32_bf16 v[112:115], v[156:159], v[172:175], v[112:115]
	v_mfma_f32_16x16x32_bf16 v[84:87], v[148:151], v[190:193], v[84:87]
	v_mfma_f32_16x16x32_bf16 v[80:83], v[156:159], v[190:193], v[80:83]
	v_mfma_f32_16x16x32_bf16 v[68:71], v[148:151], v[198:201], v[68:71]
	v_mfma_f32_16x16x32_bf16 v[64:67], v[156:159], v[198:201], v[64:67]
	s_barrier
	s_add_i32 s61, s61, s77
	v_lshl_add_u64 v[202:203], s[34:35], 0, v[232:233]
	s_mov_b32 m0, s61
	ds_read_b128 v[160:163], v221 offset:16384
	ds_read_b128 v[164:167], v221 offset:17408
	ds_read_b128 v[168:171], v221 offset:18432
	ds_read_b128 v[172:175], v221 offset:19456
	ds_read_b128 v[176:179], v221 offset:20480
	ds_read_b128 v[190:193], v221 offset:21504
	ds_read_b128 v[194:197], v221 offset:22528
	ds_read_b128 v[198:201], v221 offset:23552
	global_load_lds_dwordx4 v[202:203], off
	s_add_i32 m0, s61, 0x2000
	s_add_u32 s62, s34, 0x100000
	v_lshl_add_u64 v[204:205], s[34:35], 0, v[184:185]
	s_addc_u32 s63, s35, 0
	s_add_i32 s61, s64, s77
	global_load_lds_dwordx4 v[204:205], off
	v_lshl_add_u64 v[206:207], s[62:63], 0, v[232:233]
	s_mov_b32 m0, s61
	v_lshl_add_u64 v[208:209], s[36:37], 0, v[182:183]
	global_load_lds_dwordx4 v[206:207], off
	v_lshl_add_u64 v[206:207], s[62:63], 0, v[184:185]
	s_add_i32 m0, s61, 0x2000
	s_nop 0
	global_load_lds_dwordx4 v[206:207], off
	v_lshl_add_u64 v[206:207], s[36:37], 0, v[180:181]
	s_waitcnt vmcnt(6)
	s_waitcnt lgkmcnt(0)
	s_barrier
	s_waitcnt lgkmcnt(0)
	v_mfma_f32_16x16x32_bf16 v[60:63], v[88:91], v[160:163], 0
	v_mfma_f32_16x16x32_bf16 v[56:59], v[96:99], v[160:163], 0
	v_mfma_f32_16x16x32_bf16 v[44:47], v[88:91], v[168:171], 0
	v_mfma_f32_16x16x32_bf16 v[40:43], v[96:99], v[168:171], 0
	v_mfma_f32_16x16x32_bf16 v[28:31], v[88:91], v[176:179], 0
	v_mfma_f32_16x16x32_bf16 v[24:27], v[96:99], v[176:179], 0
	v_mfma_f32_16x16x32_bf16 v[12:15], v[88:91], v[194:197], 0
	v_mfma_f32_16x16x32_bf16 v[8:11], v[96:99], v[194:197], 0
	v_mfma_f32_16x16x32_bf16 v[60:63], v[92:95], v[164:167], v[60:63]
	v_mfma_f32_16x16x32_bf16 v[56:59], v[100:103], v[164:167], v[56:59]
	v_mfma_f32_16x16x32_bf16 v[44:47], v[92:95], v[172:175], v[44:47]
	v_mfma_f32_16x16x32_bf16 v[40:43], v[100:103], v[172:175], v[40:43]
	v_mfma_f32_16x16x32_bf16 v[28:31], v[92:95], v[190:193], v[28:31]
	v_mfma_f32_16x16x32_bf16 v[24:27], v[100:103], v[190:193], v[24:27]
	v_mfma_f32_16x16x32_bf16 v[12:15], v[92:95], v[198:201], v[12:15]
	v_mfma_f32_16x16x32_bf16 v[8:11], v[100:103], v[198:201], v[8:11]
	v_mfma_f32_16x16x32_bf16 v[52:55], v[144:147], v[160:163], 0
	v_mfma_f32_16x16x32_bf16 v[48:51], v[152:155], v[160:163], 0
	v_mfma_f32_16x16x32_bf16 v[36:39], v[144:147], v[168:171], 0
	v_mfma_f32_16x16x32_bf16 v[32:35], v[152:155], v[168:171], 0
	v_mfma_f32_16x16x32_bf16 v[20:23], v[144:147], v[176:179], 0
	v_mfma_f32_16x16x32_bf16 v[16:19], v[152:155], v[176:179], 0
	v_mfma_f32_16x16x32_bf16 v[4:7], v[144:147], v[194:197], 0
	v_mfma_f32_16x16x32_bf16 v[0:3], v[152:155], v[194:197], 0
	v_mfma_f32_16x16x32_bf16 v[52:55], v[148:151], v[164:167], v[52:55]
	v_mfma_f32_16x16x32_bf16 v[48:51], v[156:159], v[164:167], v[48:51]
	v_mfma_f32_16x16x32_bf16 v[36:39], v[148:151], v[172:175], v[36:39]
	v_mfma_f32_16x16x32_bf16 v[32:35], v[156:159], v[172:175], v[32:35]
	v_mfma_f32_16x16x32_bf16 v[20:23], v[148:151], v[190:193], v[20:23]
	v_mfma_f32_16x16x32_bf16 v[16:19], v[156:159], v[190:193], v[16:19]
	v_mfma_f32_16x16x32_bf16 v[4:7], v[148:151], v[198:201], v[4:7]
	v_mfma_f32_16x16x32_bf16 v[0:3], v[156:159], v[198:201], v[0:3]
	s_barrier
	s_branch .Lzmid_6
.LBB0_1492:
	s_add_u32 s34, s30, 0xfff00080
	s_addc_u32 s35, s31, -1
	s_add_i32 s61, 0, 0x10000
	s_cmp_eq_u32 s60, 60
	s_cselect_b32 s37, s23, s35
	s_cselect_b32 s36, s56, s34
	s_cselect_b32 s35, s21, s59
	s_cselect_b32 s34, s57, s58
	s_add_i32 s64, 0, 0x14000
	v_add_u32_e32 v100, s61, v220
	v_add_u32_e32 v156, s64, v220
	ds_read_b128 v[88:91], v100
	ds_read_b128 v[92:95], v100 offset:1024
	ds_read_b128 v[96:99], v100 offset:2048
	ds_read_b128 v[100:103], v100 offset:3072
	ds_read_b128 v[144:147], v156
	ds_read_b128 v[148:151], v156 offset:1024
	ds_read_b128 v[152:155], v156 offset:2048
	ds_read_b128 v[156:159], v156 offset:3072
	v_lshl_add_u64 v[202:203], s[30:31], 0, v[188:189]
	s_add_i32 m0, s78, 0xc000
	ds_read_b128 v[160:163], v221
	ds_read_b128 v[164:167], v221 offset:1024
	ds_read_b128 v[168:171], v221 offset:2048
	ds_read_b128 v[172:175], v221 offset:3072
	ds_read_b128 v[176:179], v221 offset:4096
	ds_read_b128 v[190:193], v221 offset:5120
	ds_read_b128 v[194:197], v221 offset:6144
	ds_read_b128 v[198:201], v221 offset:7168
	global_load_lds_dwordx4 v[202:203], off
	v_lshl_add_u64 v[202:203], s[30:31], 0, v[186:187]
	s_add_i32 m0, s78, 0xe000
	s_nop 0
	global_load_lds_dwordx4 v[202:203], off
	s_waitcnt vmcnt(8)
	s_waitcnt lgkmcnt(0)
	s_barrier
	s_waitcnt lgkmcnt(0)
	v_mfma_f32_16x16x32_bf16 v[140:143], v[88:91], v[160:163], v[140:143]
	v_mfma_f32_16x16x32_bf16 v[136:139], v[96:99], v[160:163], v[136:139]
	v_mfma_f32_16x16x32_bf16 v[124:127], v[88:91], v[168:171], v[124:127]
	v_mfma_f32_16x16x32_bf16 v[120:123], v[96:99], v[168:171], v[120:123]
	v_mfma_f32_16x16x32_bf16 v[108:111], v[88:91], v[176:179], v[108:111]
	v_mfma_f32_16x16x32_bf16 v[104:107], v[96:99], v[176:179], v[104:107]
	v_mfma_f32_16x16x32_bf16 v[76:79], v[88:91], v[194:197], v[76:79]
	v_mfma_f32_16x16x32_bf16 v[72:75], v[96:99], v[194:197], v[72:75]
	v_mfma_f32_16x16x32_bf16 v[140:143], v[92:95], v[164:167], v[140:143]
	v_mfma_f32_16x16x32_bf16 v[136:139], v[100:103], v[164:167], v[136:139]
	v_mfma_f32_16x16x32_bf16 v[124:127], v[92:95], v[172:175], v[124:127]
	v_mfma_f32_16x16x32_bf16 v[120:123], v[100:103], v[172:175], v[120:123]
	v_mfma_f32_16x16x32_bf16 v[108:111], v[92:95], v[190:193], v[108:111]
	v_mfma_f32_16x16x32_bf16 v[104:107], v[100:103], v[190:193], v[104:107]
	v_mfma_f32_16x16x32_bf16 v[76:79], v[92:95], v[198:201], v[76:79]
	v_mfma_f32_16x16x32_bf16 v[72:75], v[100:103], v[198:201], v[72:75]
	v_mfma_f32_16x16x32_bf16 v[132:135], v[144:147], v[160:163], v[132:135]
	v_mfma_f32_16x16x32_bf16 v[128:131], v[152:155], v[160:163], v[128:131]
	v_mfma_f32_16x16x32_bf16 v[116:119], v[144:147], v[168:171], v[116:119]
	v_mfma_f32_16x16x32_bf16 v[112:115], v[152:155], v[168:171], v[112:115]
	v_mfma_f32_16x16x32_bf16 v[84:87], v[144:147], v[176:179], v[84:87]
	v_mfma_f32_16x16x32_bf16 v[80:83], v[152:155], v[176:179], v[80:83]
	v_mfma_f32_16x16x32_bf16 v[68:71], v[144:147], v[194:197], v[68:71]
	v_mfma_f32_16x16x32_bf16 v[64:67], v[152:155], v[194:197], v[64:67]
	v_mfma_f32_16x16x32_bf16 v[132:135], v[148:151], v[164:167], v[132:135]
	v_mfma_f32_16x16x32_bf16 v[128:131], v[156:159], v[164:167], v[128:131]
	v_mfma_f32_16x16x32_bf16 v[116:119], v[148:151], v[172:175], v[116:119]
	v_mfma_f32_16x16x32_bf16 v[112:115], v[156:159], v[172:175], v[112:115]
	v_mfma_f32_16x16x32_bf16 v[84:87], v[148:151], v[190:193], v[84:87]
	v_mfma_f32_16x16x32_bf16 v[80:83], v[156:159], v[190:193], v[80:83]
	v_mfma_f32_16x16x32_bf16 v[68:71], v[148:151], v[198:201], v[68:71]
	v_mfma_f32_16x16x32_bf16 v[64:67], v[156:159], v[198:201], v[64:67]
	s_barrier
	s_add_i32 s61, s61, s77
	v_lshl_add_u64 v[202:203], s[34:35], 0, v[232:233]
	s_mov_b32 m0, s61
	ds_read_b128 v[160:163], v221 offset:16384
	ds_read_b128 v[164:167], v221 offset:17408
	ds_read_b128 v[168:171], v221 offset:18432
	ds_read_b128 v[172:175], v221 offset:19456
	ds_read_b128 v[176:179], v221 offset:20480
	ds_read_b128 v[190:193], v221 offset:21504
	ds_read_b128 v[194:197], v221 offset:22528
	ds_read_b128 v[198:201], v221 offset:23552
	global_load_lds_dwordx4 v[202:203], off
	s_add_i32 m0, s61, 0x2000
	s_add_u32 s62, s34, 0x100000
	v_lshl_add_u64 v[204:205], s[34:35], 0, v[184:185]
	s_addc_u32 s63, s35, 0
	s_add_i32 s61, s64, s77
	global_load_lds_dwordx4 v[204:205], off
	v_lshl_add_u64 v[206:207], s[62:63], 0, v[232:233]
	s_mov_b32 m0, s61
	v_lshl_add_u64 v[208:209], s[36:37], 0, v[182:183]
	global_load_lds_dwordx4 v[206:207], off
	v_lshl_add_u64 v[206:207], s[62:63], 0, v[184:185]
	s_add_i32 m0, s61, 0x2000
	s_nop 0
	global_load_lds_dwordx4 v[206:207], off
	v_lshl_add_u64 v[206:207], s[36:37], 0, v[180:181]
	s_waitcnt vmcnt(6)
	s_waitcnt lgkmcnt(0)
	s_barrier
	s_waitcnt lgkmcnt(0)
	v_mfma_f32_16x16x32_bf16 v[60:63], v[88:91], v[160:163], v[60:63]
	v_mfma_f32_16x16x32_bf16 v[56:59], v[96:99], v[160:163], v[56:59]
	v_mfma_f32_16x16x32_bf16 v[44:47], v[88:91], v[168:171], v[44:47]
	v_mfma_f32_16x16x32_bf16 v[40:43], v[96:99], v[168:171], v[40:43]
	v_mfma_f32_16x16x32_bf16 v[28:31], v[88:91], v[176:179], v[28:31]
	v_mfma_f32_16x16x32_bf16 v[24:27], v[96:99], v[176:179], v[24:27]
	v_mfma_f32_16x16x32_bf16 v[12:15], v[88:91], v[194:197], v[12:15]
	v_mfma_f32_16x16x32_bf16 v[8:11], v[96:99], v[194:197], v[8:11]
	v_mfma_f32_16x16x32_bf16 v[60:63], v[92:95], v[164:167], v[60:63]
	v_mfma_f32_16x16x32_bf16 v[56:59], v[100:103], v[164:167], v[56:59]
	v_mfma_f32_16x16x32_bf16 v[44:47], v[92:95], v[172:175], v[44:47]
	v_mfma_f32_16x16x32_bf16 v[40:43], v[100:103], v[172:175], v[40:43]
	v_mfma_f32_16x16x32_bf16 v[28:31], v[92:95], v[190:193], v[28:31]
	v_mfma_f32_16x16x32_bf16 v[24:27], v[100:103], v[190:193], v[24:27]
	v_mfma_f32_16x16x32_bf16 v[12:15], v[92:95], v[198:201], v[12:15]
	v_mfma_f32_16x16x32_bf16 v[8:11], v[100:103], v[198:201], v[8:11]
	v_mfma_f32_16x16x32_bf16 v[52:55], v[144:147], v[160:163], v[52:55]
	v_mfma_f32_16x16x32_bf16 v[48:51], v[152:155], v[160:163], v[48:51]
	v_mfma_f32_16x16x32_bf16 v[36:39], v[144:147], v[168:171], v[36:39]
	v_mfma_f32_16x16x32_bf16 v[32:35], v[152:155], v[168:171], v[32:35]
	v_mfma_f32_16x16x32_bf16 v[20:23], v[144:147], v[176:179], v[20:23]
	v_mfma_f32_16x16x32_bf16 v[16:19], v[152:155], v[176:179], v[16:19]
	v_mfma_f32_16x16x32_bf16 v[4:7], v[144:147], v[194:197], v[4:7]
	v_mfma_f32_16x16x32_bf16 v[0:3], v[152:155], v[194:197], v[0:3]
	v_mfma_f32_16x16x32_bf16 v[52:55], v[148:151], v[164:167], v[52:55]
	v_mfma_f32_16x16x32_bf16 v[48:51], v[156:159], v[164:167], v[48:51]
	v_mfma_f32_16x16x32_bf16 v[36:39], v[148:151], v[172:175], v[36:39]
	v_mfma_f32_16x16x32_bf16 v[32:35], v[156:159], v[172:175], v[32:35]
	v_mfma_f32_16x16x32_bf16 v[20:23], v[148:151], v[190:193], v[20:23]
	v_mfma_f32_16x16x32_bf16 v[16:19], v[156:159], v[190:193], v[16:19]
	v_mfma_f32_16x16x32_bf16 v[4:7], v[148:151], v[198:201], v[4:7]
	v_mfma_f32_16x16x32_bf16 v[0:3], v[156:159], v[198:201], v[0:3]
	s_barrier
.Lzmid_6:
	s_add_i32 s61, 0, 0x18000
	s_add_i32 s62, 0, 0x1c000
	v_add_u32_e32 v100, s61, v220
	v_add_u32_e32 v156, s62, v220
	ds_read_b128 v[88:91], v100
	ds_read_b128 v[92:95], v100 offset:1024
	ds_read_b128 v[96:99], v100 offset:2048
	ds_read_b128 v[100:103], v100 offset:3072
	ds_read_b128 v[144:147], v156
	ds_read_b128 v[148:151], v156 offset:1024
	ds_read_b128 v[152:155], v156 offset:2048
	ds_read_b128 v[156:159], v156 offset:3072
	s_add_u32 s36, s36, 0x100000
	s_addc_u32 s37, s37, 0
	s_mov_b32 m0, s78
	s_nop 0
	global_load_lds_dwordx4 v[206:207], off
	s_mov_b32 m0, s79
	s_nop 0
	global_load_lds_dwordx4 v[208:209], off
	s_mov_b32 m0, s80
	v_lshl_add_u64 v[210:211], s[36:37], 0, v[180:181]
	ds_read_b128 v[160:163], v221 offset:32768
	ds_read_b128 v[164:167], v221 offset:33792
	ds_read_b128 v[168:171], v221 offset:34816
	ds_read_b128 v[172:175], v221 offset:35840
	ds_read_b128 v[176:179], v221 offset:36864
	ds_read_b128 v[190:193], v221 offset:37888
	ds_read_b128 v[194:197], v221 offset:38912
	ds_read_b128 v[198:201], v221 offset:39936
	global_load_lds_dwordx4 v[210:211], off
	v_lshl_add_u64 v[210:211], s[36:37], 0, v[182:183]
	s_mov_b32 m0, s81
	s_nop 0
	global_load_lds_dwordx4 v[210:211], off
	s_waitcnt vmcnt(8)
	s_waitcnt lgkmcnt(0)
	s_barrier
	s_waitcnt lgkmcnt(0)
	v_mfma_f32_16x16x32_bf16 v[140:143], v[88:91], v[160:163], v[140:143]
	v_mfma_f32_16x16x32_bf16 v[136:139], v[96:99], v[160:163], v[136:139]
	v_mfma_f32_16x16x32_bf16 v[124:127], v[88:91], v[168:171], v[124:127]
	v_mfma_f32_16x16x32_bf16 v[120:123], v[96:99], v[168:171], v[120:123]
	v_mfma_f32_16x16x32_bf16 v[108:111], v[88:91], v[176:179], v[108:111]
	v_mfma_f32_16x16x32_bf16 v[104:107], v[96:99], v[176:179], v[104:107]
	v_mfma_f32_16x16x32_bf16 v[76:79], v[88:91], v[194:197], v[76:79]
	v_mfma_f32_16x16x32_bf16 v[72:75], v[96:99], v[194:197], v[72:75]
	v_mfma_f32_16x16x32_bf16 v[140:143], v[92:95], v[164:167], v[140:143]
	v_mfma_f32_16x16x32_bf16 v[136:139], v[100:103], v[164:167], v[136:139]
	v_mfma_f32_16x16x32_bf16 v[124:127], v[92:95], v[172:175], v[124:127]
	v_mfma_f32_16x16x32_bf16 v[120:123], v[100:103], v[172:175], v[120:123]
	v_mfma_f32_16x16x32_bf16 v[108:111], v[92:95], v[190:193], v[108:111]
	v_mfma_f32_16x16x32_bf16 v[104:107], v[100:103], v[190:193], v[104:107]
	v_mfma_f32_16x16x32_bf16 v[76:79], v[92:95], v[198:201], v[76:79]
	v_mfma_f32_16x16x32_bf16 v[72:75], v[100:103], v[198:201], v[72:75]
	v_mfma_f32_16x16x32_bf16 v[132:135], v[144:147], v[160:163], v[132:135]
	v_mfma_f32_16x16x32_bf16 v[128:131], v[152:155], v[160:163], v[128:131]
	v_mfma_f32_16x16x32_bf16 v[116:119], v[144:147], v[168:171], v[116:119]
	v_mfma_f32_16x16x32_bf16 v[112:115], v[152:155], v[168:171], v[112:115]
	v_mfma_f32_16x16x32_bf16 v[84:87], v[144:147], v[176:179], v[84:87]
	v_mfma_f32_16x16x32_bf16 v[80:83], v[152:155], v[176:179], v[80:83]
	v_mfma_f32_16x16x32_bf16 v[68:71], v[144:147], v[194:197], v[68:71]
	v_mfma_f32_16x16x32_bf16 v[64:67], v[152:155], v[194:197], v[64:67]
	v_mfma_f32_16x16x32_bf16 v[132:135], v[148:151], v[164:167], v[132:135]
	v_mfma_f32_16x16x32_bf16 v[128:131], v[156:159], v[164:167], v[128:131]
	v_mfma_f32_16x16x32_bf16 v[116:119], v[148:151], v[172:175], v[116:119]
	v_mfma_f32_16x16x32_bf16 v[112:115], v[156:159], v[172:175], v[112:115]
	v_mfma_f32_16x16x32_bf16 v[84:87], v[148:151], v[190:193], v[84:87]
	v_mfma_f32_16x16x32_bf16 v[80:83], v[156:159], v[190:193], v[80:83]
	v_mfma_f32_16x16x32_bf16 v[68:71], v[148:151], v[198:201], v[68:71]
	v_mfma_f32_16x16x32_bf16 v[64:67], v[156:159], v[198:201], v[64:67]
	s_barrier
	s_add_i32 s36, s61, s77
	v_lshl_add_u64 v[202:203], v[202:203], 0, s[94:95]
	s_mov_b32 m0, s36
	ds_read_b128 v[160:163], v221 offset:49152
	ds_read_b128 v[164:167], v221 offset:50176
	ds_read_b128 v[168:171], v221 offset:51200
	ds_read_b128 v[172:175], v221 offset:52224
	ds_read_b128 v[176:179], v221 offset:53248
	ds_read_b128 v[190:193], v221 offset:54272
	ds_read_b128 v[194:197], v221 offset:55296
	ds_read_b128 v[198:201], v221 offset:56320
	global_load_lds_dwordx4 v[202:203], off
	s_add_i32 m0, s36, 0x2000
	s_add_u32 s34, s34, 0x100080
	v_lshl_add_u64 v[202:203], v[204:205], 0, s[94:95]
	s_addc_u32 s35, s35, 0
	s_add_i32 s36, s62, s77
	global_load_lds_dwordx4 v[202:203], off
	v_lshl_add_u64 v[202:203], s[34:35], 0, v[232:233]
	s_mov_b32 m0, s36
	s_nop 0
	global_load_lds_dwordx4 v[202:203], off
	v_lshl_add_u64 v[202:203], s[34:35], 0, v[184:185]
	s_add_i32 m0, s36, 0x2000
	s_nop 0
	global_load_lds_dwordx4 v[202:203], off
	v_lshl_add_u64 v[202:203], v[206:207], 0, s[94:95]
	s_mov_b32 m0, s52
	s_nop 0
	global_load_lds_dwordx4 v[202:203], off
	v_lshl_add_u64 v[202:203], v[208:209], 0, s[94:95]
	s_mov_b32 m0, s53
	s_nop 0
	global_load_lds_dwordx4 v[202:203], off
	s_waitcnt vmcnt(8)
	s_waitcnt lgkmcnt(0)
	s_barrier
	s_waitcnt lgkmcnt(0)
	v_mfma_f32_16x16x32_bf16 v[60:63], v[88:91], v[160:163], v[60:63]
	v_mfma_f32_16x16x32_bf16 v[56:59], v[96:99], v[160:163], v[56:59]
	v_mfma_f32_16x16x32_bf16 v[44:47], v[88:91], v[168:171], v[44:47]
	v_mfma_f32_16x16x32_bf16 v[40:43], v[96:99], v[168:171], v[40:43]
	v_mfma_f32_16x16x32_bf16 v[28:31], v[88:91], v[176:179], v[28:31]
	v_mfma_f32_16x16x32_bf16 v[24:27], v[96:99], v[176:179], v[24:27]
	v_mfma_f32_16x16x32_bf16 v[12:15], v[88:91], v[194:197], v[12:15]
	v_mfma_f32_16x16x32_bf16 v[8:11], v[96:99], v[194:197], v[8:11]
	v_mfma_f32_16x16x32_bf16 v[60:63], v[92:95], v[164:167], v[60:63]
	v_mfma_f32_16x16x32_bf16 v[56:59], v[100:103], v[164:167], v[56:59]
	v_mfma_f32_16x16x32_bf16 v[44:47], v[92:95], v[172:175], v[44:47]
	v_mfma_f32_16x16x32_bf16 v[40:43], v[100:103], v[172:175], v[40:43]
	v_mfma_f32_16x16x32_bf16 v[28:31], v[92:95], v[190:193], v[28:31]
	v_mfma_f32_16x16x32_bf16 v[24:27], v[100:103], v[190:193], v[24:27]
	v_mfma_f32_16x16x32_bf16 v[12:15], v[92:95], v[198:201], v[12:15]
	v_mfma_f32_16x16x32_bf16 v[8:11], v[100:103], v[198:201], v[8:11]
	v_mfma_f32_16x16x32_bf16 v[52:55], v[144:147], v[160:163], v[52:55]
	v_mfma_f32_16x16x32_bf16 v[48:51], v[152:155], v[160:163], v[48:51]
	v_mfma_f32_16x16x32_bf16 v[36:39], v[144:147], v[168:171], v[36:39]
	v_mfma_f32_16x16x32_bf16 v[32:35], v[152:155], v[168:171], v[32:35]
	v_mfma_f32_16x16x32_bf16 v[20:23], v[144:147], v[176:179], v[20:23]
	v_mfma_f32_16x16x32_bf16 v[16:19], v[152:155], v[176:179], v[16:19]
	v_mfma_f32_16x16x32_bf16 v[4:7], v[144:147], v[194:197], v[4:7]
	v_mfma_f32_16x16x32_bf16 v[0:3], v[152:155], v[194:197], v[0:3]
	v_mfma_f32_16x16x32_bf16 v[52:55], v[148:151], v[164:167], v[52:55]
	v_mfma_f32_16x16x32_bf16 v[48:51], v[156:159], v[164:167], v[48:51]
	v_mfma_f32_16x16x32_bf16 v[36:39], v[148:151], v[172:175], v[36:39]
	v_mfma_f32_16x16x32_bf16 v[32:35], v[156:159], v[172:175], v[32:35]
	v_mfma_f32_16x16x32_bf16 v[20:23], v[148:151], v[190:193], v[20:23]
	v_mfma_f32_16x16x32_bf16 v[16:19], v[156:159], v[190:193], v[16:19]
	v_mfma_f32_16x16x32_bf16 v[4:7], v[148:151], v[198:201], v[4:7]
	v_mfma_f32_16x16x32_bf16 v[0:3], v[156:159], v[198:201], v[0:3]
	s_barrier
	s_add_i32 s60, s60, 2
	s_add_u32 s58, s58, 0x100
	s_addc_u32 s59, s59, 0
	s_add_u32 s30, s30, 0x100
	s_addc_u32 s31, s31, 0
	s_cmp_gt_u32 s60, 61
	s_cbranch_scc0 .LBB0_1492
	s_and_b64 vcc, exec, s[18:19]
	s_cbranch_vccz .LBB0_1495
	s_barrier
